# attention loops: every v_pk_fma_f32/v_pk_add_f32 split into scalar v_fma/v_add/v_sub (bit-identical), dead halves of horizontal adds dropped
# speedup vs baseline: 1.0038x; 1.0038x over previous
; #define LAS __attribute__((address_space(3)))
; #define INPTR(k) ({ int _i = (k); asm volatile("" : "+s"(_i)); (const float*)(GAS const float*)a.in[_i]; })
; __global__ void __launch_bounds__(512, 2) mega(Args a) {
;     ...
;         bf16_t* XN = (bf16_t*)(ws + WS_ACT);
;         bf16_t* PROJ = XN + (size_t)Tc * 1024;
;         bf16_t* QC = PROJ + (size_t)Tc * INP;
;         bf16_t* KVC = QC + (size_t)Tc * 768;
;         bf16_t* OC = KVC + (size_t)Tc * 1024;
;         bf16_t* MIX = OC + (size_t)Tc * 512;
;         bf16_t* OA = MIX + (size_t)Tc * 1024;
;         bf16_t* OB = OA + (size_t)Tc * 512;
;         float* PART = (float*)(OB + (size_t)Tc * 512);
;     ...
;                 unsigned* ctr = ctl + 64 * (1 + ck * 2 + l + 64 * rep);
;                 LAS int* s_unit = (LAS int*)(lds + LDS_CTRL);
;                 const float lam_init = (l == 0) ? 0.2f : 0.35550906f;
;                 float lam;
;                 { const float* lf = INPTR(3) + (size_t)l * 256; const float sa = wave_sum(lf[lane] * lf[64 + lane]), sb = wave_sum(lf[128 + lane] * lf[192 + lane]); lam = __expf(sa) - __expf(sb) + lam_init; lam = __uint_as_float(__builtin_amdgcn_readfirstlane(__float_as_uint(lam))); }
;                 const float* dgain = INPTR(4) + (size_t)l * 128;
.LBB0_16:
	s_mul_i32 s6, s5, 0x67
	s_sext_i32_i16 s7, s6
	s_ashr_i32 s7, s7, 10
	s_bfe_u32 s6, s6, 0x1000f
	s_add_i32 s14, s7, s6
	s_bfe_i64 s[6:7], s[14:15], 0x100000
	s_add_i32 s5, s5, 9
	s_cmp_lt_u32 s5, 19
	v_writelane_b32 v253, s6, 50
	s_cselect_b64 s[22:23], -1, 0
	s_add_u32 s8, s74, 0x5000000
	v_writelane_b32 v253, s7, 51
	s_addc_u32 s9, s75, 0
	s_lshl_b64 s[6:7], s[16:17], 10
	s_lshl_b64 s[18:19], s[16:17], 11
	s_add_u32 s10, s8, s18
	s_addc_u32 s11, s9, s19
	s_mul_i32 s12, s16, 0x3600
	s_mul_hi_i32 s5, s16, 0x3600
	s_add_u32 s13, s10, s12
	s_addc_u32 s20, s11, s5
	s_mul_hi_i32 s5, s16, 0x600
	v_writelane_b32 v253, s16, 52
	s_mul_i32 s12, s16, 0x600
	s_add_u32 s12, s13, s12
	v_writelane_b32 v253, s17, 53
	v_writelane_b32 v253, s13, 54
	v_writelane_b32 v253, s20, 55
	s_addc_u32 s5, s20, s5
	v_writelane_b32 v253, s12, 56
	s_add_u32 s12, s12, s18
	v_writelane_b32 v253, s5, 57
	s_addc_u32 s5, s5, s19
	v_writelane_b32 v253, s12, 58
	s_add_u32 s12, s12, s6
	v_writelane_b32 v253, s5, 59
	s_addc_u32 s13, s5, s7
	s_add_u32 s5, s12, s18
	v_writelane_b32 v253, s18, 60
	s_addc_u32 s16, s13, s19
	v_writelane_b32 v251, s16, 0
	v_writelane_b32 v253, s19, 61
	v_writelane_b32 v253, s5, 62
	s_add_u32 s5, s5, s6
	v_writelane_b32 v253, s5, 63
	s_addc_u32 s5, s16, s7
	v_writelane_b32 v251, s5, 1
	s_mov_b64 s[18:19], -1
	s_cmp_lt_i32 s15, 4
	s_mov_b64 s[16:17], 0
	v_writelane_b32 v251, s92, 2
	v_writelane_b32 v251, s15, 3
	s_cbranch_scc1 .LBB0_1233
	s_cmp_eq_u32 s15, 4
	s_mov_b64 s[16:17], -1
	s_cbranch_scc0 .LBB0_1232
	s_sext_i32_i16 s5, s14
	s_lshl_b32 s4, s4, 1
	s_add_i32 s5, s5, s4
	s_lshl_b32 s4, s5, 6
	s_add_i32 s4, s4, 64
	s_ashr_i32 s5, s4, 31
	s_lshl_b64 s[4:5], s[4:5], 2
	v_writelane_b32 v251, s28, 4
	s_add_u32 s4, s74, s4
	s_addc_u32 s5, s75, s5
	v_writelane_b32 v251, s29, 5
	v_writelane_b32 v251, s4, 6
	v_readlane_b32 s16, v253, 50
	v_readlane_b32 s17, v253, 51
	v_writelane_b32 v251, s5, 7
	s_mov_b32 s4, 3
	s_ashr_i32 s5, s4, 31
	s_lshl_b64 s[4:5], s[4:5], 3
	s_add_u32 s4, s0, s4
	s_addc_u32 s5, s1, s5
	s_load_dwordx2 s[4:5], s[4:5], 0x0
	s_lshl_b64 s[6:7], s[16:17], 10
	v_lshlrev_b32_e32 v0, 2, v203
	v_cmp_lt_i32_e32 vcc, v185, v184
	v_writelane_b32 v251, s22, 8
	s_waitcnt lgkmcnt(0)
	s_add_u32 s4, s4, s6
	s_addc_u32 s5, s5, s7
	global_load_dword v1, v0, s[4:5]
	global_load_dword v2, v0, s[4:5] offset:256
	global_load_dword v3, v0, s[4:5] offset:512
	s_nop 0
	global_load_dword v0, v0, s[4:5] offset:768
	v_cndmask_b32_e32 v6, v183, v185, vcc
	v_lshlrev_b32_e32 v6, 2, v6
	v_cmp_lt_i32_e32 vcc, v186, v184
	s_mov_b32 s4, 4
	s_ashr_i32 s5, s4, 31
	v_cndmask_b32_e32 v7, v183, v186, vcc
	v_lshlrev_b32_e32 v7, 2, v7
	v_cmp_lt_i32_e32 vcc, v187, v184
	s_lshl_b64 s[4:5], s[4:5], 3
	s_add_u32 s4, s0, s4
	v_cndmask_b32_e32 v8, v183, v187, vcc
	v_cmp_lt_i32_e32 vcc, v188, v184
	s_addc_u32 s5, s1, s5
	s_load_dwordx2 s[4:5], s[4:5], 0x0
	v_cndmask_b32_e32 v9, v183, v188, vcc
	v_cmp_lt_i32_e32 vcc, v189, v184
	s_lshl_b64 s[6:7], s[16:17], 9
	v_cndmask_b32_e64 v4, v193, v194, s[22:23]
	s_mul_i32 s14, s92, 0x2200
	s_waitcnt lgkmcnt(0)
	s_add_u32 s42, s4, s6
	s_addc_u32 s43, s5, s7
	s_add_i32 s4, s14, 0
	v_writelane_b32 v251, s23, 9
	s_add_i32 s71, s4, 0x12800
	v_cmp_eq_u32_e64 s[62:63], 0, v202
	s_lshl_b32 s73, s92, 5
	v_sub_f32_e32 v152, 1.0, v4
	s_waitcnt vmcnt(0)
	v_mul_f32_e32 v10, v1, v2
	ds_bpermute_b32 v10, v6, v10
	s_waitcnt vmcnt(0)
	v_mul_f32_e32 v11, v3, v0
	ds_bpermute_b32 v6, v6, v11
	v_cndmask_b32_e32 v11, v183, v189, vcc
	v_cmp_lt_i32_e32 vcc, v190, v184
	s_waitcnt lgkmcnt(1)
	v_fmac_f32_e32 v10, v1, v2
	s_waitcnt lgkmcnt(0)
	v_fmac_f32_e32 v6, v3, v0
	ds_bpermute_b32 v0, v7, v10
	ds_bpermute_b32 v1, v7, v6
	v_lshlrev_b32_e32 v3, 2, v8
	v_cndmask_b32_e32 v2, v183, v190, vcc
	v_lshlrev_b32_e32 v7, 2, v9
	s_waitcnt lgkmcnt(1)
	v_add_f32_e32 v0, v10, v0
	s_waitcnt lgkmcnt(0)
	v_add_f32_e32 v1, v6, v1
	ds_bpermute_b32 v6, v3, v0
	ds_bpermute_b32 v3, v3, v1
	v_lshlrev_b32_e32 v174, 2, v2
	v_lshlrev_b32_e32 v8, 2, v11
	s_waitcnt lgkmcnt(1)
	v_add_f32_e32 v0, v0, v6
	s_waitcnt lgkmcnt(0)
	v_add_f32_e32 v1, v1, v3
	ds_bpermute_b32 v2, v7, v0
	ds_bpermute_b32 v3, v7, v1
	s_waitcnt lgkmcnt(1)
	v_add_f32_e32 v0, v0, v2
	s_waitcnt lgkmcnt(0)
	v_add_f32_e32 v1, v1, v3
	ds_bpermute_b32 v2, v8, v0
	ds_bpermute_b32 v3, v8, v1
	s_waitcnt lgkmcnt(1)
	v_add_f32_e32 v0, v0, v2
	s_waitcnt lgkmcnt(0)
	v_add_f32_e32 v1, v1, v3
	ds_bpermute_b32 v2, v174, v0
	ds_bpermute_b32 v3, v174, v1
	s_waitcnt lgkmcnt(1)
	v_add_f32_e32 v0, v0, v2
	s_waitcnt lgkmcnt(0)
	v_add_f32_e32 v1, v1, v3
	v_mul_f32_e32 v0, 0x3fb8aa3b, v0
	v_mul_f32_e32 v1, 0x3fb8aa3b, v1
	v_exp_f32_e32 v0, v0
	v_exp_f32_e32 v1, v1
	s_nop 0
	v_sub_f32_e32 v0, v0, v1
	v_add_f32_e32 v0, v4, v0
	s_nop 0
	v_readfirstlane_b32 s4, v0
	s_nop 1
	v_writelane_b32 v251, s4, 10
	v_writelane_b32 v251, s62, 11
	s_nop 1
	v_writelane_b32 v251, s63, 12
	v_writelane_b32 v251, s73, 13
	s_branch .LBB0_140

; __global__ void __launch_bounds__(512, 2) mega(Args a) {
;     ...
;                     if (tid == 0) *s_unit = (int)atomicAdd(ctr, 1u);
.LBB0_140:
	s_and_saveexec_b64 s[14:15], s[62:63]
	s_cbranch_execz .LBB0_142
	v_readlane_b32 s4, v251, 6
	v_readlane_b32 s5, v251, 7
	s_nop 1
	v_mov_b64_e32 v[0:1], s[4:5]
	flat_atomic_add v0, v[0:1], v191 sc0
	v_readlane_b32 s4, v253, 26
	s_nop 1
	v_mov_b32_e32 v1, s4
	s_waitcnt vmcnt(0) lgkmcnt(0)
	ds_write_b32 v1, v0

.LBB0_159:
	ds_read_b128 v[38:41], v134 offset:6656
	ds_read_b128 v[42:45], v134
	ds_read_b128 v[138:141], v134 offset:32
	ds_read_b128 v[142:145], v134 offset:6688
	s_cmp_eq_u32 s25, -1
	s_cselect_b64 s[18:19], -1, 0
	s_waitcnt lgkmcnt(2)
	v_mfma_f32_32x32x16_bf16 v[54:69], v[42:45], v[70:73], 0
	v_cndmask_b32_e64 v146, -v137, v195, s[18:19]
	v_cmp_lt_i32_e32 vcc, 0, v128
	s_mov_b64 s[20:21], s[18:19]
	v_mfma_f32_32x32x16_bf16 v[38:53], v[38:41], v[70:73], 0
	s_waitcnt lgkmcnt(1)
	v_mfma_f32_32x32x16_bf16 v[54:69], v[138:141], v[74:77], v[54:69]
	s_waitcnt lgkmcnt(0)
	v_mfma_f32_32x32x16_bf16 v[38:53], v[142:145], v[74:77], v[38:53]
	ds_read_b128 v[138:141], v134 offset:64
	ds_read_b128 v[142:145], v134 offset:6720
	s_waitcnt lgkmcnt(1)
	v_mfma_f32_32x32x16_bf16 v[54:69], v[138:141], v[78:81], v[54:69]
	s_waitcnt lgkmcnt(0)
	v_mfma_f32_32x32x16_bf16 v[38:53], v[142:145], v[78:81], v[38:53]
	ds_read_b128 v[138:141], v134 offset:96
	ds_read_b128 v[142:145], v134 offset:6752
	s_waitcnt lgkmcnt(1)
	v_mfma_f32_32x32x16_bf16 v[54:69], v[138:141], v[82:85], v[54:69]
	s_waitcnt lgkmcnt(0)
	v_mfma_f32_32x32x16_bf16 v[38:53], v[142:145], v[82:85], v[38:53]
	ds_read_b128 v[138:141], v134 offset:128
	ds_read_b128 v[142:145], v134 offset:6784
	s_waitcnt lgkmcnt(1)
	v_mfma_f32_32x32x16_bf16 v[54:69], v[138:141], v[86:89], v[54:69]
	s_waitcnt lgkmcnt(0)
	v_mfma_f32_32x32x16_bf16 v[38:53], v[142:145], v[86:89], v[38:53]
	ds_read_b128 v[138:141], v134 offset:160
	ds_read_b128 v[142:145], v134 offset:6816
	s_waitcnt lgkmcnt(1)
	v_mfma_f32_32x32x16_bf16 v[54:69], v[138:141], v[90:93], v[54:69]
	s_waitcnt lgkmcnt(0)
	v_mfma_f32_32x32x16_bf16 v[38:53], v[142:145], v[90:93], v[38:53]
	s_nop 9
	v_fma_f32 v0, v54, s88, v146
	v_fma_f32 v1, v55, s88, v146
	v_cndmask_b32_e32 v4, v196, v1, vcc
	v_cmp_lt_i32_e32 vcc, -1, v128
	s_nop 1
	v_cndmask_b32_e32 v143, v196, v0, vcc
	v_fma_f32 v0, v38, s88, v146
	v_fma_f32 v1, v39, s88, v146
	v_cmp_lt_i32_e32 vcc, 32, v128
	s_nop 1
	v_cndmask_b32_e32 v142, v196, v1, vcc
	v_cmp_lt_i32_e32 vcc, 31, v128
	s_nop 1
	v_cndmask_b32_e32 v145, v196, v0, vcc
	v_fma_f32 v0, v56, s88, v146
	v_fma_f32 v1, v57, s88, v146
	v_cmp_lt_i32_e32 vcc, 2, v128
	s_nop 1
	v_cndmask_b32_e32 v130, v196, v1, vcc
	v_cmp_lt_i32_e32 vcc, 1, v128
	s_nop 1
	v_cndmask_b32_e32 v140, v196, v0, vcc
	v_fma_f32 v0, v40, s88, v146
	v_fma_f32 v1, v41, s88, v146
	v_cmp_lt_i32_e32 vcc, 34, v128
	s_nop 1
	v_cndmask_b32_e32 v139, v196, v1, vcc
	v_cmp_lt_i32_e32 vcc, 33, v128
	s_nop 1
	v_cndmask_b32_e32 v144, v196, v0, vcc
	v_fma_f32 v0, v58, s88, v146
	v_fma_f32 v1, v59, s88, v146
	v_cmp_lt_i32_e32 vcc, 8, v128
	s_nop 1
	v_cndmask_b32_e32 v56, v196, v1, vcc
	v_cmp_lt_i32_e32 vcc, 7, v128
	s_nop 1
	v_cndmask_b32_e32 v138, v196, v0, vcc
	v_fma_f32 v0, v42, s88, v146
	v_fma_f32 v1, v43, s88, v146
	v_cmp_lt_i32_e32 vcc, 40, v128
	s_nop 1
	v_cndmask_b32_e32 v131, v196, v1, vcc
	v_cmp_lt_i32_e32 vcc, 39, v128
	s_nop 1
	v_cndmask_b32_e32 v141, v196, v0, vcc
	v_fma_f32 v0, v60, s88, v146
	v_fma_f32 v1, v61, s88, v146
	v_cmp_lt_i32_e32 vcc, 10, v128
	s_nop 1
	v_cndmask_b32_e32 v54, v196, v1, vcc
	v_cmp_lt_i32_e32 vcc, 9, v128
	s_nop 1
	v_cndmask_b32_e32 v58, v196, v0, vcc
	v_fma_f32 v0, v44, s88, v146
	v_fma_f32 v1, v45, s88, v146
	v_cmp_lt_i32_e32 vcc, 42, v128
	s_nop 1
	v_cndmask_b32_e32 v57, v196, v1, vcc
	v_cmp_lt_i32_e32 vcc, 41, v128
	s_nop 1
	v_cndmask_b32_e32 v60, v196, v0, vcc
	v_fma_f32 v0, v62, s88, v146
	v_fma_f32 v1, v63, s88, v146
	v_cmp_lt_i32_e32 vcc, 16, v128
	s_nop 1
	v_cndmask_b32_e32 v43, v196, v1, vcc
	v_cmp_lt_i32_e32 vcc, 15, v128
	s_nop 1
	v_cndmask_b32_e32 v55, v196, v0, vcc
	v_fma_f32 v0, v46, s88, v146
	v_fma_f32 v1, v47, s88, v146
	v_cmp_lt_i32_e32 vcc, 48, v128
	s_nop 1
	v_cndmask_b32_e32 v47, v196, v1, vcc
	v_cmp_lt_i32_e32 vcc, 47, v128
	s_nop 1
	v_cndmask_b32_e32 v59, v196, v0, vcc
	v_fma_f32 v0, v64, s88, v146
	v_fma_f32 v1, v65, s88, v146
	v_cmp_lt_i32_e32 vcc, 18, v128
	s_nop 1
	v_cndmask_b32_e32 v39, v196, v1, vcc
	v_cmp_lt_i32_e32 vcc, 17, v128
	s_nop 1
	v_cndmask_b32_e32 v45, v196, v0, vcc
	v_fma_f32 v0, v48, s88, v146
	v_fma_f32 v1, v49, s88, v146
	v_cmp_lt_i32_e32 vcc, 50, v128
	v_max_f32_e32 v49, v4, v142
	v_max3_f32 v49, v143, v145, v49
	v_cndmask_b32_e32 v44, v196, v1, vcc
	v_cmp_lt_i32_e32 vcc, 49, v128
	s_nop 1
	v_cndmask_b32_e32 v48, v196, v0, vcc
	v_fma_f32 v0, v66, s88, v146
	v_fma_f32 v1, v67, s88, v146
	v_cmp_lt_i32_e32 vcc, 24, v128
	s_nop 1
	v_cndmask_b32_e32 v3, v196, v1, vcc
	v_cmp_lt_i32_e32 vcc, 23, v128
	s_nop 1
	v_cndmask_b32_e32 v41, v196, v0, vcc
	v_fma_f32 v0, v50, s88, v146
	v_fma_f32 v1, v51, s88, v146
	v_cmp_lt_i32_e32 vcc, 56, v128
	v_fma_f32 v50, v68, s88, v146
	v_fma_f32 v51, v69, s88, v146
	s_nop 0
	v_cndmask_b32_e32 v40, v196, v1, vcc
	v_cmp_lt_i32_e32 vcc, 55, v128
	s_nop 1
	v_cndmask_b32_e32 v46, v196, v0, vcc
	v_cmp_lt_i32_e32 vcc, 26, v128
	s_nop 1
	v_cndmask_b32_e32 v0, v196, v51, vcc
	v_cmp_lt_i32_e32 vcc, 25, v128
	s_nop 1
	v_cndmask_b32_e32 v38, v196, v50, vcc
	v_fma_f32 v50, v52, s88, v146
	v_fma_f32 v51, v53, s88, v146
	v_cmp_lt_i32_e32 vcc, 58, v128
	s_nop 1
	v_cndmask_b32_e32 v1, v196, v51, vcc
	v_cmp_lt_i32_e32 vcc, 57, v128
	v_max_f32_e32 v51, v130, v139
	s_nop 0
	v_cndmask_b32_e32 v42, v196, v50, vcc
	v_max_f32_e32 v50, v140, v144
	v_max3_f32 v49, v49, v50, v51
	v_max_f32_e32 v50, v138, v141
	v_max_f32_e32 v51, v56, v131
	v_max3_f32 v49, v49, v50, v51
	v_max_f32_e32 v50, v58, v60
	v_max_f32_e32 v51, v54, v57
	v_max3_f32 v49, v49, v50, v51
	v_max_f32_e32 v50, v55, v59
	v_max_f32_e32 v51, v43, v47
	v_max3_f32 v49, v49, v50, v51
	v_max_f32_e32 v50, v45, v48
	v_max_f32_e32 v51, v39, v44
	v_max3_f32 v49, v49, v50, v51
	v_max_f32_e32 v50, v41, v46
	v_max_f32_e32 v51, v3, v40
	v_max3_f32 v49, v49, v50, v51
	v_max_f32_e32 v50, v38, v42
	v_max_f32_e32 v51, v0, v1
	v_max3_f32 v49, v49, v50, v51
	ds_bpermute_b32 v50, v174, v49
	s_and_b64 vcc, exec, s[18:19]
	s_waitcnt lgkmcnt(0)
	v_max_f32_e32 v50, v50, v50
	v_max_f32_e32 v49, v49, v50
	v_cmp_lt_f32_e64 s[46:47], s38, v49
	s_cbranch_vccnz .LBB0_161
	s_cmp_lg_u64 s[46:47], 0
	s_cselect_b64 s[20:21], -1, 0

.LBB0_163:
	v_exp_f32_e32 v49, v143
	v_exp_f32_e32 v143, v145
	v_exp_f32_e32 v4, v4
	v_exp_f32_e32 v50, v142
	v_exp_f32_e32 v142, v144
	v_add_f32_e32 v51, v143, v49
	v_exp_f32_e32 v62, v139
	v_add_f32_e32 v52, v50, v4
	v_add_f32_e32 v53, v51, v5
	v_exp_f32_e32 v51, v140
	v_add_f32_e32 v53, v52, v53
	v_exp_f32_e32 v52, v130
	v_exp_f32_e32 v66, v131
	v_add_f32_e32 v63, v142, v51
	v_exp_f32_e32 v130, v44
	v_add_f32_e32 v64, v62, v52
	v_add_f32_e32 v65, v63, v53
	v_exp_f32_e32 v53, v138
	v_add_f32_e32 v65, v64, v65
	v_exp_f32_e32 v63, v141
	v_exp_f32_e32 v64, v56
	v_exp_f32_e32 v138, v40
	v_exp_f32_e32 v140, v1
	v_add_f32_e32 v67, v63, v53
	v_add_f32_e32 v68, v66, v64
	v_add_f32_e32 v69, v67, v65
	v_exp_f32_e32 v65, v58
	v_add_f32_e32 v69, v68, v69
	v_exp_f32_e32 v67, v60
	v_exp_f32_e32 v68, v54
	v_exp_f32_e32 v60, v57
	v_exp_f32_e32 v54, v47
	v_add_f32_e32 v61, v67, v65
	v_add_f32_e32 v56, v60, v68
	v_add_f32_e32 v57, v61, v69
	s_nop 0
	v_add_f32_e32 v57, v56, v57
	v_exp_f32_e32 v61, v55
	v_exp_f32_e32 v69, v59
	v_exp_f32_e32 v56, v43
	v_exp_f32_e32 v43, v45
	v_add_f32_e32 v55, v69, v61
	v_add_f32_e32 v58, v54, v56
	v_add_f32_e32 v59, v55, v57
	v_exp_f32_e32 v55, v48
	v_add_f32_e32 v59, v58, v59
	v_exp_f32_e32 v58, v39
	v_exp_f32_e32 v48, v41
	v_add_f32_e32 v131, v55, v43
	v_exp_f32_e32 v57, v46
	v_add_f32_e32 v44, v130, v58
	v_add_f32_e32 v45, v131, v59
	v_exp_f32_e32 v59, v42
	v_add_f32_e32 v45, v44, v45
	v_exp_f32_e32 v44, v3
	v_add_f32_e32 v139, v57, v48
	v_exp_f32_e32 v3, v38
	v_cvt_pk_bf16_f32 v38, v49, v4
	v_add_f32_e32 v40, v138, v44
	v_add_f32_e32 v41, v139, v45
	v_cvt_pk_bf16_f32 v39, v51, v52
	v_add_f32_e32 v141, v59, v3
	v_add_f32_e32 v47, v40, v41
	v_exp_f32_e32 v46, v0
	v_cvt_pk_bf16_f32 v40, v53, v64
	v_cvt_pk_bf16_f32 v41, v65, v68
	v_cvt_pk_bf16_f32 v42, v61, v56
	v_cvt_pk_bf16_f32 v43, v43, v58
	v_cvt_pk_bf16_f32 v44, v48, v44
	s_nop 0
	v_add_f32_e32 v0, v140, v46
	v_add_f32_e32 v1, v141, v47
	v_cvt_pk_bf16_f32 v45, v3, v46
	v_cvt_pk_bf16_f32 v46, v143, v50
	v_cvt_pk_bf16_f32 v47, v142, v62
	v_cvt_pk_bf16_f32 v48, v63, v66
	v_cvt_pk_bf16_f32 v49, v67, v60
	v_cvt_pk_bf16_f32 v50, v69, v54
	v_cvt_pk_bf16_f32 v51, v55, v130
	v_cvt_pk_bf16_f32 v52, v57, v138
	v_cvt_pk_bf16_f32 v53, v59, v140
	ds_read_b64_tr_b16 v[54:55], v135 offset:26624
	ds_read_b64_tr_b16 v[56:57], v135 offset:28160
	ds_read_b64_tr_b16 v[58:59], v135 offset:26688
	ds_read_b64_tr_b16 v[60:61], v135 offset:28224
	ds_read_b64_tr_b16 v[62:63], v135 offset:29696
	ds_read_b64_tr_b16 v[64:65], v135 offset:31232
	ds_read_b64_tr_b16 v[66:67], v135 offset:29760
	ds_read_b64_tr_b16 v[68:69], v135 offset:31296
	v_add_f32_e32 v0, v0, v1
	s_setprio 1
	s_waitcnt lgkmcnt(6)
	v_mfma_f32_32x32x16_bf16 v[6:21], v[54:57], v[38:41], v[6:21]
	s_waitcnt lgkmcnt(4)
	v_mfma_f32_32x32x16_bf16 v[22:37], v[58:61], v[38:41], v[22:37]
	s_setprio 0
	ds_read_b64_tr_b16 v[38:39], v135 offset:32768
	ds_read_b64_tr_b16 v[40:41], v135 offset:34304
	ds_read_b64_tr_b16 v[56:57], v135 offset:34368
	ds_read_b64_tr_b16 v[54:55], v135 offset:32832
	s_setprio 1
	s_waitcnt lgkmcnt(6)
	v_mfma_f32_32x32x16_bf16 v[6:21], v[62:65], v[42:45], v[6:21]
	s_waitcnt lgkmcnt(4)
	v_mfma_f32_32x32x16_bf16 v[22:37], v[66:69], v[42:45], v[22:37]
	s_setprio 0
	ds_read_b64_tr_b16 v[42:43], v135 offset:35840
	ds_read_b64_tr_b16 v[44:45], v135 offset:37376
	ds_read_b64_tr_b16 v[60:61], v135 offset:37440
	ds_read_b64_tr_b16 v[58:59], v135 offset:35904
	s_setprio 1
	s_waitcnt lgkmcnt(6)
	v_mfma_f32_32x32x16_bf16 v[6:21], v[38:41], v[46:49], v[6:21]
	s_waitcnt lgkmcnt(4)
	v_mfma_f32_32x32x16_bf16 v[22:37], v[54:57], v[46:49], v[22:37]
	s_setprio 0
	s_setprio 1
	s_waitcnt lgkmcnt(2)
	v_mfma_f32_32x32x16_bf16 v[6:21], v[42:45], v[50:53], v[6:21]
	s_waitcnt lgkmcnt(0)
	v_mfma_f32_32x32x16_bf16 v[22:37], v[58:61], v[50:53], v[22:37]
	s_setprio 0
	v_add_f32_e32 v136, v136, v0
	s_cmp_lt_i32 s24, 1
	s_cbranch_scc1 .LBB0_167

.LBB0_173:
	ds_read_b128 v[0:3], v134 offset:19968
	ds_read_b128 v[38:41], v134 offset:13312
	ds_read_b128 v[138:141], v134 offset:13344
	s_cmp_eq_u32 s25, 0
	s_cselect_b64 s[18:19], -1, 0
	v_add_u32_e32 v147, 64, v128
	s_waitcnt lgkmcnt(1)
	v_mfma_f32_32x32x16_bf16 v[54:69], v[38:41], v[70:73], 0
	v_cndmask_b32_e64 v146, -v137, v195, s[18:19]
	v_cmp_lt_i32_e32 vcc, 0, v147
	s_mov_b64 s[20:21], s[18:19]
	v_mfma_f32_32x32x16_bf16 v[38:53], v[0:3], v[70:73], 0
	ds_read_b128 v[0:3], v134 offset:20000
	s_waitcnt lgkmcnt(1)
	v_mfma_f32_32x32x16_bf16 v[54:69], v[138:141], v[74:77], v[54:69]
	s_waitcnt lgkmcnt(0)
	v_mfma_f32_32x32x16_bf16 v[38:53], v[0:3], v[74:77], v[38:53]
	ds_read_b128 v[0:3], v134 offset:13376
	ds_read_b128 v[138:141], v134 offset:20032
	s_waitcnt lgkmcnt(1)
	v_mfma_f32_32x32x16_bf16 v[54:69], v[0:3], v[78:81], v[54:69]
	s_waitcnt lgkmcnt(0)
	v_mfma_f32_32x32x16_bf16 v[38:53], v[138:141], v[78:81], v[38:53]
	ds_read_b128 v[0:3], v134 offset:13408
	ds_read_b128 v[138:141], v134 offset:20064
	s_waitcnt lgkmcnt(1)
	v_mfma_f32_32x32x16_bf16 v[54:69], v[0:3], v[82:85], v[54:69]
	s_waitcnt lgkmcnt(0)
	v_mfma_f32_32x32x16_bf16 v[38:53], v[138:141], v[82:85], v[38:53]
	ds_read_b128 v[0:3], v134 offset:13440
	ds_read_b128 v[138:141], v134 offset:20096
	s_waitcnt lgkmcnt(1)
	v_mfma_f32_32x32x16_bf16 v[54:69], v[0:3], v[86:89], v[54:69]
	s_waitcnt lgkmcnt(0)
	v_mfma_f32_32x32x16_bf16 v[38:53], v[138:141], v[86:89], v[38:53]
	ds_read_b128 v[0:3], v134 offset:13472
	ds_read_b128 v[138:141], v134 offset:20128
	s_waitcnt lgkmcnt(1)
	v_mfma_f32_32x32x16_bf16 v[54:69], v[0:3], v[90:93], v[54:69]
	s_waitcnt lgkmcnt(0)
	v_mfma_f32_32x32x16_bf16 v[38:53], v[138:141], v[90:93], v[38:53]
	s_nop 9
	v_fma_f32 v0, v54, s88, v146
	v_fma_f32 v1, v55, s88, v146
	v_cndmask_b32_e32 v4, v196, v1, vcc
	v_cmp_lt_i32_e32 vcc, -1, v147
	s_nop 1
	v_cndmask_b32_e32 v143, v196, v0, vcc
	v_fma_f32 v0, v38, s88, v146
	v_fma_f32 v1, v39, s88, v146
	v_cmp_lt_i32_e32 vcc, 32, v147
	s_nop 1
	v_cndmask_b32_e32 v142, v196, v1, vcc
	v_cmp_lt_i32_e32 vcc, 31, v147
	s_nop 1
	v_cndmask_b32_e32 v145, v196, v0, vcc
	v_fma_f32 v0, v56, s88, v146
	v_fma_f32 v1, v57, s88, v146
	v_cmp_lt_i32_e32 vcc, 2, v147
	s_nop 1
	v_cndmask_b32_e32 v130, v196, v1, vcc
	v_cmp_lt_i32_e32 vcc, 1, v147
	s_nop 1
	v_cndmask_b32_e32 v140, v196, v0, vcc
	v_fma_f32 v0, v40, s88, v146
	v_fma_f32 v1, v41, s88, v146
	v_cmp_lt_i32_e32 vcc, 34, v147
	s_nop 1
	v_cndmask_b32_e32 v139, v196, v1, vcc
	v_cmp_lt_i32_e32 vcc, 33, v147
	s_nop 1
	v_cndmask_b32_e32 v144, v196, v0, vcc
	v_fma_f32 v0, v58, s88, v146
	v_fma_f32 v1, v59, s88, v146
	v_cmp_lt_i32_e32 vcc, 8, v147
	s_nop 1
	v_cndmask_b32_e32 v56, v196, v1, vcc
	v_cmp_lt_i32_e32 vcc, 7, v147
	s_nop 1
	v_cndmask_b32_e32 v138, v196, v0, vcc
	v_fma_f32 v0, v42, s88, v146
	v_fma_f32 v1, v43, s88, v146
	v_cmp_lt_i32_e32 vcc, 40, v147
	s_nop 1
	v_cndmask_b32_e32 v131, v196, v1, vcc
	v_cmp_lt_i32_e32 vcc, 39, v147
	s_nop 1
	v_cndmask_b32_e32 v141, v196, v0, vcc
	v_fma_f32 v0, v60, s88, v146
	v_fma_f32 v1, v61, s88, v146
	v_cmp_lt_i32_e32 vcc, 10, v147
	s_nop 1
	v_cndmask_b32_e32 v54, v196, v1, vcc
	v_cmp_lt_i32_e32 vcc, 9, v147
	s_nop 1
	v_cndmask_b32_e32 v58, v196, v0, vcc
	v_fma_f32 v0, v44, s88, v146
	v_fma_f32 v1, v45, s88, v146
	v_cmp_lt_i32_e32 vcc, 42, v147
	s_nop 1
	v_cndmask_b32_e32 v57, v196, v1, vcc
	v_cmp_lt_i32_e32 vcc, 41, v147
	s_nop 1
	v_cndmask_b32_e32 v60, v196, v0, vcc
	v_fma_f32 v0, v62, s88, v146
	v_fma_f32 v1, v63, s88, v146
	v_cmp_lt_i32_e32 vcc, 16, v147
	s_nop 1
	v_cndmask_b32_e32 v42, v196, v1, vcc
	v_cmp_lt_i32_e32 vcc, 15, v147
	s_nop 1
	v_cndmask_b32_e32 v55, v196, v0, vcc
	v_fma_f32 v0, v46, s88, v146
	v_fma_f32 v1, v47, s88, v146
	v_cmp_lt_i32_e32 vcc, 48, v147
	s_nop 1
	v_cndmask_b32_e32 v46, v196, v1, vcc
	v_cmp_lt_i32_e32 vcc, 47, v147
	s_nop 1
	v_cndmask_b32_e32 v59, v196, v0, vcc
	v_fma_f32 v0, v64, s88, v146
	v_fma_f32 v1, v65, s88, v146
	v_cmp_lt_i32_e32 vcc, 18, v147
	s_nop 1
	v_cndmask_b32_e32 v38, v196, v1, vcc
	v_cmp_lt_i32_e32 vcc, 17, v147
	s_nop 1
	v_cndmask_b32_e32 v44, v196, v0, vcc
	v_fma_f32 v0, v48, s88, v146
	v_fma_f32 v1, v49, s88, v146
	v_cmp_lt_i32_e32 vcc, 50, v147
	v_fma_f32 v48, v68, s88, v146
	v_fma_f32 v49, v69, s88, v146
	s_nop 0
	v_cndmask_b32_e32 v43, v196, v1, vcc
	v_cmp_lt_i32_e32 vcc, 49, v147
	s_nop 1
	v_cndmask_b32_e32 v47, v196, v0, vcc
	v_fma_f32 v0, v66, s88, v146
	v_fma_f32 v1, v67, s88, v146
	v_cmp_lt_i32_e32 vcc, 24, v147
	s_nop 1
	v_cndmask_b32_e32 v2, v196, v1, vcc
	v_cmp_lt_i32_e32 vcc, 23, v147
	s_nop 1
	v_cndmask_b32_e32 v40, v196, v0, vcc
	v_fma_f32 v0, v50, s88, v146
	v_fma_f32 v1, v51, s88, v146
	v_cmp_lt_i32_e32 vcc, 56, v147
	v_max_f32_e32 v50, v130, v139
	s_nop 0
	v_cndmask_b32_e32 v39, v196, v1, vcc
	v_cmp_lt_i32_e32 vcc, 55, v147
	s_nop 1
	v_cndmask_b32_e32 v45, v196, v0, vcc
	v_cmp_lt_i32_e32 vcc, 26, v147
	s_nop 1
	v_cndmask_b32_e32 v0, v196, v49, vcc
	v_cmp_lt_i32_e32 vcc, 25, v147
	s_nop 1
	v_cndmask_b32_e32 v3, v196, v48, vcc
	v_fma_f32 v48, v52, s88, v146
	v_fma_f32 v49, v53, s88, v146
	v_cmp_lt_i32_e32 vcc, 58, v147
	s_nop 1
	v_cndmask_b32_e32 v1, v196, v49, vcc
	v_cmp_lt_i32_e32 vcc, 57, v147
	v_max_f32_e32 v49, v140, v144
	s_nop 0
	v_cndmask_b32_e32 v41, v196, v48, vcc
	v_max_f32_e32 v48, v4, v142
	v_max3_f32 v48, v143, v145, v48
	v_max3_f32 v48, v48, v49, v50
	v_max_f32_e32 v49, v138, v141
	v_max_f32_e32 v50, v56, v131
	v_max3_f32 v48, v48, v49, v50
	v_max_f32_e32 v49, v58, v60
	v_max_f32_e32 v50, v54, v57
	v_max3_f32 v48, v48, v49, v50
	v_max_f32_e32 v49, v55, v59
	v_max_f32_e32 v50, v42, v46
	v_max3_f32 v48, v48, v49, v50
	v_max_f32_e32 v49, v44, v47
	v_max_f32_e32 v50, v38, v43
	v_max3_f32 v48, v48, v49, v50
	v_max_f32_e32 v49, v40, v45
	v_max_f32_e32 v50, v2, v39
	v_max3_f32 v48, v48, v49, v50
	v_max_f32_e32 v49, v3, v41
	v_max_f32_e32 v50, v0, v1
	v_max3_f32 v48, v48, v49, v50
	ds_bpermute_b32 v49, v174, v48
	s_and_b64 vcc, exec, s[18:19]
	s_waitcnt lgkmcnt(0)
	v_max_f32_e32 v49, v49, v49
	v_max_f32_e32 v48, v48, v49
	v_cmp_lt_f32_e64 s[46:47], s38, v48
	s_cbranch_vccnz .LBB0_175
	s_cmp_lg_u64 s[46:47], 0
	s_cselect_b64 s[20:21], -1, 0

.LBB0_177:
	v_exp_f32_e32 v143, v143
	v_exp_f32_e32 v145, v145
	v_exp_f32_e32 v4, v4
	v_exp_f32_e32 v48, v142
	v_exp_f32_e32 v52, v139
	v_add_f32_e32 v49, v145, v143
	v_exp_f32_e32 v64, v131
	v_add_f32_e32 v50, v48, v4
	v_add_f32_e32 v51, v49, v5
	v_exp_f32_e32 v49, v140
	v_add_f32_e32 v51, v50, v51
	v_exp_f32_e32 v140, v144
	v_exp_f32_e32 v50, v130
	v_exp_f32_e32 v47, v47
	v_exp_f32_e32 v68, v43
	v_add_f32_e32 v53, v140, v49
	v_add_f32_e32 v62, v52, v50
	v_add_f32_e32 v63, v53, v51
	v_exp_f32_e32 v51, v138
	v_add_f32_e32 v63, v62, v63
	v_exp_f32_e32 v53, v141
	v_exp_f32_e32 v62, v56
	v_exp_f32_e32 v40, v40
	v_exp_f32_e32 v130, v39
	v_add_f32_e32 v65, v53, v51
	v_add_f32_e32 v66, v64, v62
	v_add_f32_e32 v67, v65, v63
	v_exp_f32_e32 v63, v58
	v_add_f32_e32 v67, v66, v67
	v_exp_f32_e32 v65, v60
	v_exp_f32_e32 v66, v54
	v_exp_f32_e32 v60, v57
	v_exp_f32_e32 v54, v46
	v_add_f32_e32 v61, v65, v63
	v_exp_f32_e32 v46, v44
	v_add_f32_e32 v56, v60, v66
	v_add_f32_e32 v57, v61, v67
	v_exp_f32_e32 v61, v55
	v_add_f32_e32 v57, v56, v57
	v_exp_f32_e32 v67, v59
	v_exp_f32_e32 v56, v42
	v_add_f32_e32 v69, v47, v46
	v_exp_f32_e32 v138, v1
	v_add_f32_e32 v55, v67, v61
	v_add_f32_e32 v58, v54, v56
	v_add_f32_e32 v59, v55, v57
	v_exp_f32_e32 v55, v45
	v_add_f32_e32 v59, v58, v59
	v_exp_f32_e32 v58, v38
	v_exp_f32_e32 v57, v41
	v_add_f32_e32 v131, v55, v40
	v_add_f32_e32 v42, v68, v58
	v_add_f32_e32 v43, v69, v59
	s_nop 0
	v_add_f32_e32 v43, v42, v43
	v_exp_f32_e32 v42, v2
	s_nop 0
	v_add_f32_e32 v38, v130, v42
	v_add_f32_e32 v39, v131, v43
	s_nop 0
	v_add_f32_e32 v45, v38, v39
	v_exp_f32_e32 v43, v3
	v_exp_f32_e32 v44, v0
	v_add_f32_e32 v139, v57, v43
	v_add_f32_e32 v0, v138, v44
	v_add_f32_e32 v1, v139, v45
	s_nop 0
	v_add_f32_e32 v69, v0, v1
	v_cvt_pk_bf16_f32 v0, v143, v4
	v_cvt_pk_bf16_f32 v1, v49, v50
	v_cvt_pk_bf16_f32 v2, v51, v62
	v_cvt_pk_bf16_f32 v3, v63, v66
	v_cvt_pk_bf16_f32 v38, v61, v56
	v_cvt_pk_bf16_f32 v39, v46, v58
	v_cvt_pk_bf16_f32 v40, v40, v42
	v_cvt_pk_bf16_f32 v41, v43, v44
	v_cvt_pk_bf16_f32 v42, v145, v48
	v_cvt_pk_bf16_f32 v43, v140, v52
	v_cvt_pk_bf16_f32 v44, v53, v64
	v_cvt_pk_bf16_f32 v45, v65, v60
	v_cvt_pk_bf16_f32 v46, v67, v54
	v_cvt_pk_bf16_f32 v47, v47, v68
	v_cvt_pk_bf16_f32 v48, v55, v130
	v_cvt_pk_bf16_f32 v49, v57, v138
	ds_read_b64_tr_b16 v[50:51], v135 offset:38912
	ds_read_b64_tr_b16 v[52:53], v135 offset:40448
	ds_read_b64_tr_b16 v[54:55], v135 offset:38976
	ds_read_b64_tr_b16 v[56:57], v135 offset:40512
	ds_read_b64_tr_b16 v[58:59], v135 offset:41984
	ds_read_b64_tr_b16 v[60:61], v135 offset:43520
	ds_read_b64_tr_b16 v[62:63], v135 offset:42048
	ds_read_b64_tr_b16 v[64:65], v135 offset:43584
	s_setprio 1
	s_waitcnt lgkmcnt(6)
	v_mfma_f32_32x32x16_bf16 v[6:21], v[50:53], v[0:3], v[6:21]
	s_waitcnt lgkmcnt(4)
	v_mfma_f32_32x32x16_bf16 v[22:37], v[54:57], v[0:3], v[22:37]
	s_setprio 0
	ds_read_b64_tr_b16 v[0:1], v135 offset:45056
	ds_read_b64_tr_b16 v[2:3], v135 offset:46592
	ds_read_b64_tr_b16 v[52:53], v135 offset:46656
	ds_read_b64_tr_b16 v[50:51], v135 offset:45120
	s_setprio 1
	s_waitcnt lgkmcnt(6)
	v_mfma_f32_32x32x16_bf16 v[6:21], v[58:61], v[38:41], v[6:21]
	s_waitcnt lgkmcnt(4)
	v_mfma_f32_32x32x16_bf16 v[22:37], v[62:65], v[38:41], v[22:37]
	s_setprio 0
	ds_read_b64_tr_b16 v[38:39], v135 offset:48128
	ds_read_b64_tr_b16 v[40:41], v135 offset:49664
	ds_read_b64_tr_b16 v[56:57], v135 offset:49728
	ds_read_b64_tr_b16 v[54:55], v135 offset:48192
	s_setprio 1
	s_waitcnt lgkmcnt(6)
	v_mfma_f32_32x32x16_bf16 v[6:21], v[0:3], v[42:45], v[6:21]
	s_waitcnt lgkmcnt(4)
	v_mfma_f32_32x32x16_bf16 v[22:37], v[50:53], v[42:45], v[22:37]
	s_setprio 0
	s_setprio 1
	s_waitcnt lgkmcnt(2)
	v_mfma_f32_32x32x16_bf16 v[6:21], v[38:41], v[46:49], v[6:21]
	s_waitcnt lgkmcnt(0)
	v_mfma_f32_32x32x16_bf16 v[22:37], v[54:57], v[46:49], v[22:37]
	s_setprio 0
	v_add_f32_e32 v136, v136, v69
	s_andn2_b64 vcc, exec, s[16:17]
	s_cbranch_vccnz .LBB0_181

.LBB0_194:
	v_add_u32_e32 v3, s4, v134
	ds_read_b128 v[38:41], v3 offset:6656
	ds_read_b128 v[42:45], v3
	ds_read_b128 v[120:123], v3 offset:32
	ds_read_b128 v[124:127], v3 offset:6688
	s_cmp_eq_u32 s7, s23
	s_cselect_b64 s[18:19], -1, 0
	s_waitcnt lgkmcnt(2)
	v_mfma_f32_32x32x16_bf16 v[54:69], v[42:45], v[70:73], 0
	v_cndmask_b32_e64 v4, -v137, v195, s[18:19]
	s_and_b64 vcc, exec, s[18:19]
	s_mov_b64 s[20:21], s[18:19]
	v_mfma_f32_32x32x16_bf16 v[38:53], v[38:41], v[70:73], 0
	s_waitcnt lgkmcnt(1)
	v_mfma_f32_32x32x16_bf16 v[54:69], v[120:123], v[74:77], v[54:69]
	s_waitcnt lgkmcnt(0)
	v_mfma_f32_32x32x16_bf16 v[38:53], v[124:127], v[74:77], v[38:53]
	ds_read_b128 v[120:123], v3 offset:64
	ds_read_b128 v[124:127], v3 offset:6720
	s_waitcnt lgkmcnt(1)
	v_mfma_f32_32x32x16_bf16 v[54:69], v[120:123], v[78:81], v[54:69]
	s_waitcnt lgkmcnt(0)
	v_mfma_f32_32x32x16_bf16 v[38:53], v[124:127], v[78:81], v[38:53]
	ds_read_b128 v[120:123], v3 offset:96
	ds_read_b128 v[124:127], v3 offset:6752
	s_waitcnt lgkmcnt(1)
	v_mfma_f32_32x32x16_bf16 v[54:69], v[120:123], v[82:85], v[54:69]
	s_waitcnt lgkmcnt(0)
	v_mfma_f32_32x32x16_bf16 v[38:53], v[124:127], v[82:85], v[38:53]
	ds_read_b128 v[120:123], v3 offset:128
	ds_read_b128 v[124:127], v3 offset:6784
	s_waitcnt lgkmcnt(1)
	v_mfma_f32_32x32x16_bf16 v[54:69], v[120:123], v[86:89], v[54:69]
	s_waitcnt lgkmcnt(0)
	v_mfma_f32_32x32x16_bf16 v[38:53], v[124:127], v[86:89], v[38:53]
	ds_read_b128 v[120:123], v3 offset:160
	ds_read_b128 v[124:127], v3 offset:6816
	s_waitcnt lgkmcnt(1)
	v_mfma_f32_32x32x16_bf16 v[54:69], v[120:123], v[90:93], v[54:69]
	s_waitcnt lgkmcnt(0)
	v_mfma_f32_32x32x16_bf16 v[38:53], v[124:127], v[90:93], v[38:53]
	s_nop 9
	v_fma_f32 v128, v54, s88, v4
	v_fma_f32 v129, v55, s88, v4
	v_fma_f32 v124, v56, s88, v4
	v_fma_f32 v125, v57, s88, v4
	v_fma_f32 v120, v58, s88, v4
	v_fma_f32 v121, v59, s88, v4
	v_fma_f32 v58, v60, s88, v4
	v_fma_f32 v59, v61, s88, v4
	v_fma_f32 v54, v62, s88, v4
	v_fma_f32 v55, v63, s88, v4
	v_fma_f32 v130, v38, s88, v4
	v_fma_f32 v131, v39, s88, v4
	v_fma_f32 v126, v40, s88, v4
	v_fma_f32 v127, v41, s88, v4
	v_max_f32_e32 v3, v129, v131
	v_fma_f32 v122, v42, s88, v4
	v_fma_f32 v123, v43, s88, v4
	v_fma_f32 v60, v44, s88, v4
	v_fma_f32 v61, v45, s88, v4
	v_fma_f32 v56, v46, s88, v4
	v_fma_f32 v57, v47, s88, v4
	v_fma_f32 v46, v64, s88, v4
	v_fma_f32 v47, v65, s88, v4
	v_fma_f32 v48, v48, s88, v4
	v_fma_f32 v49, v49, s88, v4
	v_fma_f32 v42, v66, s88, v4
	v_fma_f32 v43, v67, s88, v4
	v_fma_f32 v44, v50, s88, v4
	v_fma_f32 v45, v51, s88, v4
	v_fma_f32 v38, v68, s88, v4
	v_fma_f32 v39, v69, s88, v4
	v_fma_f32 v40, v52, s88, v4
	v_fma_f32 v41, v53, s88, v4
	v_max3_f32 v3, v128, v130, v3
	v_max_f32_e32 v4, v124, v126
	v_max_f32_e32 v50, v125, v127
	v_max3_f32 v3, v3, v4, v50
	v_max_f32_e32 v4, v120, v122
	v_max_f32_e32 v50, v121, v123
	v_max3_f32 v3, v3, v4, v50
	v_max_f32_e32 v4, v58, v60
	v_max_f32_e32 v50, v59, v61
	v_max3_f32 v3, v3, v4, v50
	v_max_f32_e32 v4, v54, v56
	v_max_f32_e32 v50, v55, v57
	v_max3_f32 v3, v3, v4, v50
	v_max_f32_e32 v4, v46, v48
	v_max_f32_e32 v50, v47, v49
	v_max3_f32 v3, v3, v4, v50
	v_max_f32_e32 v4, v42, v44
	v_max_f32_e32 v50, v43, v45
	v_max3_f32 v3, v3, v4, v50
	v_max_f32_e32 v4, v38, v40
	v_max_f32_e32 v50, v39, v41
	v_max3_f32 v3, v3, v4, v50
	ds_bpermute_b32 v4, v174, v3
	s_waitcnt lgkmcnt(0)
	v_max_f32_e32 v4, v4, v4
	v_max_f32_e32 v3, v3, v4
	v_cmp_lt_f32_e64 s[46:47], s38, v3
	s_cbranch_vccnz .LBB0_196
	s_cmp_lg_u64 s[46:47], 0
	s_cselect_b64 s[20:21], -1, 0

.LBB0_198:
	v_exp_f32_e32 v3, v128
	v_exp_f32_e32 v128, v130
	v_exp_f32_e32 v50, v129
	v_exp_f32_e32 v4, v131
	v_exp_f32_e32 v126, v126
	v_add_f32_e32 v51, v3, v128
	v_exp_f32_e32 v62, v125
	v_add_f32_e32 v52, v50, v4
	v_add_f32_e32 v53, v51, v5
	v_exp_f32_e32 v51, v124
	v_add_f32_e32 v53, v52, v53
	v_exp_f32_e32 v52, v127
	v_exp_f32_e32 v66, v121
	v_add_f32_e32 v63, v51, v126
	v_add_f32_e32 v64, v62, v52
	v_add_f32_e32 v65, v63, v53
	s_nop 0
	v_add_f32_e32 v65, v64, v65
	v_exp_f32_e32 v53, v120
	v_exp_f32_e32 v63, v122
	v_exp_f32_e32 v64, v123
	v_exp_f32_e32 v120, v59
	v_add_f32_e32 v67, v53, v63
	v_add_f32_e32 v68, v66, v64
	v_add_f32_e32 v69, v67, v65
	v_exp_f32_e32 v65, v58
	v_add_f32_e32 v69, v68, v69
	v_exp_f32_e32 v67, v60
	v_exp_f32_e32 v68, v61
	v_exp_f32_e32 v60, v55
	v_add_f32_e32 v121, v65, v67
	v_add_f32_e32 v58, v120, v68
	v_add_f32_e32 v59, v121, v69
	v_exp_f32_e32 v69, v54
	v_add_f32_e32 v59, v58, v59
	v_exp_f32_e32 v121, v56
	v_exp_f32_e32 v58, v57
	v_exp_f32_e32 v56, v47
	v_add_f32_e32 v61, v69, v121
	v_add_f32_e32 v54, v60, v58
	v_add_f32_e32 v55, v61, v59
	v_exp_f32_e32 v59, v46
	v_add_f32_e32 v55, v54, v55
	v_exp_f32_e32 v61, v48
	v_exp_f32_e32 v54, v49
	v_exp_f32_e32 v48, v39
	v_add_f32_e32 v57, v59, v61
	v_add_f32_e32 v46, v56, v54
	v_add_f32_e32 v47, v57, v55
	v_exp_f32_e32 v55, v42
	v_add_f32_e32 v123, v46, v47
	v_exp_f32_e32 v57, v44
	v_exp_f32_e32 v46, v43
	v_exp_f32_e32 v122, v45
	v_exp_f32_e32 v45, v38
	v_add_f32_e32 v47, v55, v57
	v_add_f32_e32 v42, v46, v122
	v_add_f32_e32 v43, v47, v123
	s_nop 0
	v_add_f32_e32 v125, v42, v43
	v_exp_f32_e32 v123, v40
	v_exp_f32_e32 v124, v41
	v_add_f32_e32 v49, v45, v123
	v_add_f32_e32 v38, v48, v124
	v_add_f32_e32 v39, v49, v125
	s_nop 0
	v_add_f32_e32 v125, v38, v39
	v_cvt_pk_bf16_f32 v38, v3, v50
	v_add_u32_e32 v3, s5, v135
	v_cvt_pk_bf16_f32 v39, v51, v62
	v_cvt_pk_bf16_f32 v40, v53, v66
	v_cvt_pk_bf16_f32 v41, v65, v120
	v_cvt_pk_bf16_f32 v42, v69, v60
	v_cvt_pk_bf16_f32 v43, v59, v56
	v_cvt_pk_bf16_f32 v44, v55, v46
	v_cvt_pk_bf16_f32 v45, v45, v48
	v_cvt_pk_bf16_f32 v46, v128, v4
	v_cvt_pk_bf16_f32 v47, v126, v52
	v_cvt_pk_bf16_f32 v48, v63, v64
	v_cvt_pk_bf16_f32 v49, v67, v68
	v_cvt_pk_bf16_f32 v50, v121, v58
	v_cvt_pk_bf16_f32 v51, v61, v54
	v_cvt_pk_bf16_f32 v52, v57, v122
	v_cvt_pk_bf16_f32 v53, v123, v124
	ds_read_b64_tr_b16 v[54:55], v3 offset:26624
	ds_read_b64_tr_b16 v[56:57], v3 offset:28160
	ds_read_b64_tr_b16 v[58:59], v3 offset:26688
	ds_read_b64_tr_b16 v[60:61], v3 offset:28224
	ds_read_b64_tr_b16 v[62:63], v3 offset:29696
	ds_read_b64_tr_b16 v[64:65], v3 offset:31232
	ds_read_b64_tr_b16 v[66:67], v3 offset:29760
	ds_read_b64_tr_b16 v[68:69], v3 offset:31296
	s_setprio 1
	s_waitcnt lgkmcnt(6)
	v_mfma_f32_32x32x16_bf16 v[6:21], v[54:57], v[38:41], v[6:21]
	s_waitcnt lgkmcnt(4)
	v_mfma_f32_32x32x16_bf16 v[22:37], v[58:61], v[38:41], v[22:37]
	s_setprio 0
	ds_read_b64_tr_b16 v[38:39], v3 offset:32768
	ds_read_b64_tr_b16 v[40:41], v3 offset:34304
	ds_read_b64_tr_b16 v[56:57], v3 offset:34368
	ds_read_b64_tr_b16 v[54:55], v3 offset:32832
	s_setprio 1
	s_waitcnt lgkmcnt(6)
	v_mfma_f32_32x32x16_bf16 v[6:21], v[62:65], v[42:45], v[6:21]
	s_waitcnt lgkmcnt(4)
	v_mfma_f32_32x32x16_bf16 v[22:37], v[66:69], v[42:45], v[22:37]
	s_setprio 0
	ds_read_b64_tr_b16 v[42:43], v3 offset:35840
	ds_read_b64_tr_b16 v[44:45], v3 offset:37376
	ds_read_b64_tr_b16 v[60:61], v3 offset:37440
	ds_read_b64_tr_b16 v[58:59], v3 offset:35904
	s_setprio 1
	s_waitcnt lgkmcnt(6)
	v_mfma_f32_32x32x16_bf16 v[6:21], v[38:41], v[46:49], v[6:21]
	s_waitcnt lgkmcnt(4)
	v_mfma_f32_32x32x16_bf16 v[22:37], v[54:57], v[46:49], v[22:37]
	s_setprio 0
	s_setprio 1
	s_waitcnt lgkmcnt(2)
	v_mfma_f32_32x32x16_bf16 v[6:21], v[42:45], v[50:53], v[6:21]
	s_waitcnt lgkmcnt(0)
	v_mfma_f32_32x32x16_bf16 v[22:37], v[58:61], v[50:53], v[22:37]
	s_setprio 0
	v_add_f32_e32 v136, v136, v125
	s_cmp_eq_u32 s23, 0
	s_cbranch_scc1 .LBB0_202

.LBB0_208:
	v_add_u32_e32 v3, s22, v134
	ds_read_b128 v[38:41], v3 offset:6656
	ds_read_b128 v[42:45], v3
	ds_read_b128 v[120:123], v3 offset:32
	ds_read_b128 v[124:127], v3 offset:6688
	s_cmp_eq_u32 s25, s23
	s_cselect_b64 s[18:19], -1, 0
	s_waitcnt lgkmcnt(2)
	v_mfma_f32_32x32x16_bf16 v[54:69], v[42:45], v[70:73], 0
	v_cndmask_b32_e64 v4, -v137, v195, s[18:19]
	s_and_b64 vcc, exec, s[18:19]
	s_mov_b64 s[20:21], s[18:19]
	v_mfma_f32_32x32x16_bf16 v[38:53], v[38:41], v[70:73], 0
	s_waitcnt lgkmcnt(1)
	v_mfma_f32_32x32x16_bf16 v[54:69], v[120:123], v[74:77], v[54:69]
	s_waitcnt lgkmcnt(0)
	v_mfma_f32_32x32x16_bf16 v[38:53], v[124:127], v[74:77], v[38:53]
	ds_read_b128 v[120:123], v3 offset:64
	ds_read_b128 v[124:127], v3 offset:6720
	s_waitcnt lgkmcnt(1)
	v_mfma_f32_32x32x16_bf16 v[54:69], v[120:123], v[78:81], v[54:69]
	s_waitcnt lgkmcnt(0)
	v_mfma_f32_32x32x16_bf16 v[38:53], v[124:127], v[78:81], v[38:53]
	ds_read_b128 v[120:123], v3 offset:96
	ds_read_b128 v[124:127], v3 offset:6752
	s_waitcnt lgkmcnt(1)
	v_mfma_f32_32x32x16_bf16 v[54:69], v[120:123], v[82:85], v[54:69]
	s_waitcnt lgkmcnt(0)
	v_mfma_f32_32x32x16_bf16 v[38:53], v[124:127], v[82:85], v[38:53]
	ds_read_b128 v[120:123], v3 offset:128
	ds_read_b128 v[124:127], v3 offset:6784
	s_waitcnt lgkmcnt(1)
	v_mfma_f32_32x32x16_bf16 v[54:69], v[120:123], v[86:89], v[54:69]
	s_waitcnt lgkmcnt(0)
	v_mfma_f32_32x32x16_bf16 v[38:53], v[124:127], v[86:89], v[38:53]
	ds_read_b128 v[120:123], v3 offset:160
	ds_read_b128 v[124:127], v3 offset:6816
	s_waitcnt lgkmcnt(1)
	v_mfma_f32_32x32x16_bf16 v[54:69], v[120:123], v[90:93], v[54:69]
	s_waitcnt lgkmcnt(0)
	v_mfma_f32_32x32x16_bf16 v[38:53], v[124:127], v[90:93], v[38:53]
	s_nop 9
	v_fma_f32 v128, v54, s88, v4
	v_fma_f32 v129, v55, s88, v4
	v_fma_f32 v124, v56, s88, v4
	v_fma_f32 v125, v57, s88, v4
	v_fma_f32 v120, v58, s88, v4
	v_fma_f32 v121, v59, s88, v4
	v_fma_f32 v58, v60, s88, v4
	v_fma_f32 v59, v61, s88, v4
	v_fma_f32 v54, v62, s88, v4
	v_fma_f32 v55, v63, s88, v4
	v_fma_f32 v130, v38, s88, v4
	v_fma_f32 v131, v39, s88, v4
	v_fma_f32 v126, v40, s88, v4
	v_fma_f32 v127, v41, s88, v4
	v_max_f32_e32 v3, v129, v131
	v_fma_f32 v122, v42, s88, v4
	v_fma_f32 v123, v43, s88, v4
	v_fma_f32 v60, v44, s88, v4
	v_fma_f32 v61, v45, s88, v4
	v_fma_f32 v56, v46, s88, v4
	v_fma_f32 v57, v47, s88, v4
	v_fma_f32 v46, v64, s88, v4
	v_fma_f32 v47, v65, s88, v4
	v_fma_f32 v48, v48, s88, v4
	v_fma_f32 v49, v49, s88, v4
	v_fma_f32 v42, v66, s88, v4
	v_fma_f32 v43, v67, s88, v4
	v_fma_f32 v44, v50, s88, v4
	v_fma_f32 v45, v51, s88, v4
	v_fma_f32 v38, v68, s88, v4
	v_fma_f32 v39, v69, s88, v4
	v_fma_f32 v40, v52, s88, v4
	v_fma_f32 v41, v53, s88, v4
	v_max3_f32 v3, v128, v130, v3
	v_max_f32_e32 v4, v124, v126
	v_max_f32_e32 v50, v125, v127
	v_max3_f32 v3, v3, v4, v50
	v_max_f32_e32 v4, v120, v122
	v_max_f32_e32 v50, v121, v123
	v_max3_f32 v3, v3, v4, v50
	v_max_f32_e32 v4, v58, v60
	v_max_f32_e32 v50, v59, v61
	v_max3_f32 v3, v3, v4, v50
	v_max_f32_e32 v4, v54, v56
	v_max_f32_e32 v50, v55, v57
	v_max3_f32 v3, v3, v4, v50
	v_max_f32_e32 v4, v46, v48
	v_max_f32_e32 v50, v47, v49
	v_max3_f32 v3, v3, v4, v50
	v_max_f32_e32 v4, v42, v44
	v_max_f32_e32 v50, v43, v45
	v_max3_f32 v3, v3, v4, v50
	v_max_f32_e32 v4, v38, v40
	v_max_f32_e32 v50, v39, v41
	v_max3_f32 v3, v3, v4, v50
	ds_bpermute_b32 v4, v174, v3
	s_waitcnt lgkmcnt(0)
	v_max_f32_e32 v4, v4, v4
	v_max_f32_e32 v3, v3, v4
	v_cmp_lt_f32_e64 s[46:47], s38, v3
	s_cbranch_vccnz .LBB0_210
	s_cmp_lg_u64 s[46:47], 0
	s_cselect_b64 s[20:21], -1, 0

.LBB0_212:
	v_exp_f32_e32 v3, v128
	v_exp_f32_e32 v128, v130
	v_exp_f32_e32 v50, v129
	v_exp_f32_e32 v4, v131
	v_exp_f32_e32 v126, v126
	v_add_f32_e32 v51, v3, v128
	v_exp_f32_e32 v62, v125
	v_add_f32_e32 v52, v50, v4
	v_add_f32_e32 v53, v51, v5
	v_exp_f32_e32 v51, v124
	v_add_f32_e32 v53, v52, v53
	v_exp_f32_e32 v52, v127
	v_exp_f32_e32 v66, v121
	v_add_f32_e32 v63, v51, v126
	v_add_f32_e32 v64, v62, v52
	v_add_f32_e32 v65, v63, v53
	s_nop 0
	v_add_f32_e32 v65, v64, v65
	v_exp_f32_e32 v53, v120
	v_exp_f32_e32 v63, v122
	v_exp_f32_e32 v64, v123
	v_exp_f32_e32 v120, v59
	v_add_f32_e32 v67, v53, v63
	v_add_f32_e32 v68, v66, v64
	v_add_f32_e32 v69, v67, v65
	v_exp_f32_e32 v65, v58
	v_add_f32_e32 v69, v68, v69
	v_exp_f32_e32 v67, v60
	v_exp_f32_e32 v68, v61
	v_exp_f32_e32 v60, v55
	v_add_f32_e32 v121, v65, v67
	v_add_f32_e32 v58, v120, v68
	v_add_f32_e32 v59, v121, v69
	v_exp_f32_e32 v69, v54
	v_add_f32_e32 v59, v58, v59
	v_exp_f32_e32 v121, v56
	v_exp_f32_e32 v58, v57
	v_exp_f32_e32 v56, v47
	v_add_f32_e32 v61, v69, v121
	v_add_f32_e32 v54, v60, v58
	v_add_f32_e32 v55, v61, v59
	v_exp_f32_e32 v59, v46
	v_add_f32_e32 v55, v54, v55
	v_exp_f32_e32 v61, v48
	v_exp_f32_e32 v54, v49
	v_exp_f32_e32 v48, v39
	v_add_f32_e32 v57, v59, v61
	v_add_f32_e32 v46, v56, v54
	v_add_f32_e32 v47, v57, v55
	v_exp_f32_e32 v55, v42
	v_add_f32_e32 v123, v46, v47
	v_exp_f32_e32 v57, v44
	v_exp_f32_e32 v46, v43
	v_exp_f32_e32 v122, v45
	v_exp_f32_e32 v45, v38
	v_add_f32_e32 v47, v55, v57
	v_add_f32_e32 v42, v46, v122
	v_add_f32_e32 v43, v47, v123
	s_nop 0
	v_add_f32_e32 v125, v42, v43
	v_exp_f32_e32 v123, v40
	v_exp_f32_e32 v124, v41
	v_add_f32_e32 v49, v45, v123
	v_add_f32_e32 v38, v48, v124
	v_add_f32_e32 v39, v49, v125
	s_nop 0
	v_add_f32_e32 v125, v38, v39
	v_cvt_pk_bf16_f32 v38, v3, v50
	v_add_u32_e32 v3, s24, v135
	v_cvt_pk_bf16_f32 v39, v51, v62
	v_cvt_pk_bf16_f32 v40, v53, v66
	v_cvt_pk_bf16_f32 v41, v65, v120
	v_cvt_pk_bf16_f32 v42, v69, v60
	v_cvt_pk_bf16_f32 v43, v59, v56
	v_cvt_pk_bf16_f32 v44, v55, v46
	v_cvt_pk_bf16_f32 v45, v45, v48
	v_cvt_pk_bf16_f32 v46, v128, v4
	v_cvt_pk_bf16_f32 v47, v126, v52
	v_cvt_pk_bf16_f32 v48, v63, v64
	v_cvt_pk_bf16_f32 v49, v67, v68
	v_cvt_pk_bf16_f32 v50, v121, v58
	v_cvt_pk_bf16_f32 v51, v61, v54
	v_cvt_pk_bf16_f32 v52, v57, v122
	v_cvt_pk_bf16_f32 v53, v123, v124
	ds_read_b64_tr_b16 v[54:55], v3 offset:26624
	ds_read_b64_tr_b16 v[56:57], v3 offset:28160
	ds_read_b64_tr_b16 v[58:59], v3 offset:26688
	ds_read_b64_tr_b16 v[60:61], v3 offset:28224
	ds_read_b64_tr_b16 v[62:63], v3 offset:29696
	ds_read_b64_tr_b16 v[64:65], v3 offset:31232
	ds_read_b64_tr_b16 v[66:67], v3 offset:29760
	ds_read_b64_tr_b16 v[68:69], v3 offset:31296
	s_setprio 1
	s_waitcnt lgkmcnt(6)
	v_mfma_f32_32x32x16_bf16 v[6:21], v[54:57], v[38:41], v[6:21]
	s_waitcnt lgkmcnt(4)
	v_mfma_f32_32x32x16_bf16 v[22:37], v[58:61], v[38:41], v[22:37]
	s_setprio 0
	ds_read_b64_tr_b16 v[38:39], v3 offset:32768
	ds_read_b64_tr_b16 v[40:41], v3 offset:34304
	ds_read_b64_tr_b16 v[56:57], v3 offset:34368
	ds_read_b64_tr_b16 v[54:55], v3 offset:32832
	s_setprio 1
	s_waitcnt lgkmcnt(6)
	v_mfma_f32_32x32x16_bf16 v[6:21], v[62:65], v[42:45], v[6:21]
	s_waitcnt lgkmcnt(4)
	v_mfma_f32_32x32x16_bf16 v[22:37], v[66:69], v[42:45], v[22:37]
	s_setprio 0
	ds_read_b64_tr_b16 v[42:43], v3 offset:35840
	ds_read_b64_tr_b16 v[44:45], v3 offset:37376
	ds_read_b64_tr_b16 v[60:61], v3 offset:37440
	ds_read_b64_tr_b16 v[58:59], v3 offset:35904
	s_setprio 1
	s_waitcnt lgkmcnt(6)
	v_mfma_f32_32x32x16_bf16 v[6:21], v[38:41], v[46:49], v[6:21]
	s_waitcnt lgkmcnt(4)
	v_mfma_f32_32x32x16_bf16 v[22:37], v[54:57], v[46:49], v[22:37]
	s_setprio 0
	s_setprio 1
	s_waitcnt lgkmcnt(2)
	v_mfma_f32_32x32x16_bf16 v[6:21], v[42:45], v[50:53], v[6:21]
	s_waitcnt lgkmcnt(0)
	v_mfma_f32_32x32x16_bf16 v[22:37], v[58:61], v[50:53], v[22:37]
	s_setprio 0
	v_add_f32_e32 v136, v136, v125
	s_andn2_b64 vcc, exec, s[16:17]
	s_cbranch_vccnz .LBB0_187

.LBB0_228:
	s_cmp_eq_u32 s92, s84
	s_cselect_b64 s[16:17], -1, 0
	s_cmp_lg_u32 s92, s84
	s_cselect_b64 s[18:19], -1, 0
	s_lshl_b32 s5, s92, 6
	v_or_b32_e32 v0, s5, v179
	v_sub_u32_e32 v4, v153, v0
	v_cvt_f32_i32_e32 v0, v4
	v_cndmask_b32_e64 v1, v206, 0, s[16:17]
	s_mov_b32 s20, 2.0
	s_mov_b32 s22, 0x41200000
	v_fma_f32 v10, -v144, v0, -v1
	ds_read_b128 v[0:3], v180
	ds_read_b128 v[6:9], v176
	s_mov_b32 s24, 0x41800000
	s_mov_b32 s28, 0x41900000
	s_mov_b32 s21, 0x40400000
	s_mov_b32 s23, 0x41300000
	s_mov_b32 s25, 0x41880000
	s_mov_b32 s29, 0x41980000
	v_add_f32_e32 v14, v204, v10
	v_fma_f32 v96, 0, v144, v10
	v_add_f32_e32 v97, v144, v10
	v_fma_f32 v98, v144, s20, v10
	v_fma_f32 v99, v145, s21, v10
	v_fma_f32 v100, v144, s38, v10
	v_fma_f32 v101, v145, s39, v10
	v_fma_f32 v102, v144, s22, v10
	v_fma_f32 v103, v145, s23, v10
	v_fma_f32 v104, v144, s24, v10
	v_fma_f32 v105, v145, s25, v10
	v_fma_f32 v106, v144, s28, v10
	v_fma_f32 v107, v145, s29, v10
	v_fma_f32 v108, v144, s26, v10
	v_fma_f32 v109, v145, s27, v10
	v_fma_f32 v110, v144, s36, v10
	v_fma_f32 v111, v145, s37, v10
	ds_read_b128 v[10:13], v180 offset:8704
	v_fma_f32 v80, 0, v144, v14
	s_waitcnt lgkmcnt(1)
	v_mfma_f32_32x32x16_bf16 v[96:111], v[0:3], v[6:9], v[96:111]
	v_add_f32_e32 v81, v144, v14
	v_fma_f32 v82, v144, s20, v14
	v_fma_f32 v83, v145, s21, v14
	v_fma_f32 v84, v144, s38, v14
	v_fma_f32 v85, v145, s39, v14
	v_fma_f32 v86, v144, s22, v14
	v_fma_f32 v87, v145, s23, v14
	v_fma_f32 v88, v144, s24, v14
	v_fma_f32 v89, v145, s25, v14
	v_fma_f32 v90, v144, s28, v14
	v_fma_f32 v91, v145, s29, v14
	v_fma_f32 v92, v144, s26, v14
	v_fma_f32 v93, v145, s27, v14
	v_fma_f32 v94, v144, s36, v14
	v_fma_f32 v95, v145, s37, v14
	s_or_b32 s4, s5, 63
	s_sub_i32 s20, s49, s4
	s_waitcnt lgkmcnt(0)
	v_mfma_f32_32x32x16_bf16 v[80:95], v[10:13], v[6:9], v[80:95]
	ds_read_b128 v[0:3], v180 offset:32
	ds_read_b128 v[6:9], v176 offset:32
	s_mov_b32 s4, 0
	s_cmpk_gt_i32 s20, 0x200
	s_waitcnt lgkmcnt(0)
	v_mfma_f32_32x32x16_bf16 v[96:111], v[0:3], v[6:9], v[96:111]
	ds_read_b128 v[0:3], v180 offset:8736
	s_waitcnt lgkmcnt(0)
	v_mfma_f32_32x32x16_bf16 v[80:95], v[0:3], v[6:9], v[80:95]
	ds_read_b128 v[0:3], v180 offset:64
	ds_read_b128 v[6:9], v176 offset:64
	s_waitcnt lgkmcnt(0)
	v_mfma_f32_32x32x16_bf16 v[96:111], v[0:3], v[6:9], v[96:111]
	ds_read_b128 v[0:3], v180 offset:8768
	s_waitcnt lgkmcnt(0)
	v_mfma_f32_32x32x16_bf16 v[80:95], v[0:3], v[6:9], v[80:95]
	ds_read_b128 v[0:3], v180 offset:96
	ds_read_b128 v[6:9], v176 offset:96
	s_waitcnt lgkmcnt(0)
	v_mfma_f32_32x32x16_bf16 v[96:111], v[0:3], v[6:9], v[96:111]
	ds_read_b128 v[0:3], v180 offset:8800
	s_waitcnt lgkmcnt(0)
	v_mfma_f32_32x32x16_bf16 v[80:95], v[0:3], v[6:9], v[80:95]
	ds_read_b128 v[0:3], v180 offset:128
	ds_read_b128 v[6:9], v176 offset:128
	s_waitcnt lgkmcnt(0)
	v_mfma_f32_32x32x16_bf16 v[96:111], v[0:3], v[6:9], v[96:111]
	ds_read_b128 v[0:3], v180 offset:8832
	s_waitcnt lgkmcnt(0)
	v_mfma_f32_32x32x16_bf16 v[80:95], v[0:3], v[6:9], v[80:95]
	ds_read_b128 v[0:3], v180 offset:160
	ds_read_b128 v[6:9], v176 offset:160
	s_waitcnt lgkmcnt(0)
	v_mfma_f32_32x32x16_bf16 v[96:111], v[0:3], v[6:9], v[96:111]
	ds_read_b128 v[0:3], v180 offset:8864
	s_waitcnt lgkmcnt(0)
	v_mfma_f32_32x32x16_bf16 v[80:95], v[0:3], v[6:9], v[80:95]
	ds_read_b128 v[0:3], v180 offset:192
	ds_read_b128 v[6:9], v176 offset:192
	s_waitcnt lgkmcnt(0)
	v_mfma_f32_32x32x16_bf16 v[96:111], v[0:3], v[6:9], v[96:111]
	ds_read_b128 v[0:3], v180 offset:8896
	s_waitcnt lgkmcnt(0)
	v_mfma_f32_32x32x16_bf16 v[80:95], v[0:3], v[6:9], v[80:95]
	ds_read_b128 v[0:3], v180 offset:224
	ds_read_b128 v[6:9], v176 offset:224
	s_waitcnt lgkmcnt(0)
	v_mfma_f32_32x32x16_bf16 v[96:111], v[0:3], v[6:9], v[96:111]
	ds_read_b128 v[0:3], v180 offset:8928
	s_waitcnt lgkmcnt(0)
	v_mfma_f32_32x32x16_bf16 v[80:95], v[0:3], v[6:9], v[80:95]
	s_cbranch_scc1 .LBB0_230
	s_sub_i32 s24, s46, s5
	s_cmpk_gt_i32 s20, 0x80
	s_cselect_b64 s[4:5], -1, 0
	s_cmpk_lt_i32 s24, 0x201
	s_cselect_b64 s[22:23], -1, 0
	s_and_b64 s[4:5], s[4:5], s[22:23]
	s_cmp_gt_i32 s20, -1
	s_cselect_b64 s[20:21], -1, 0
	s_cmpk_lt_i32 s24, 0x81
	s_cselect_b64 s[22:23], -1, 0
	s_and_b64 s[20:21], s[20:21], s[22:23]
	s_and_b64 s[20:21], s[20:21], exec
	s_cselect_b32 s20, 2, 3
	s_and_b64 s[4:5], s[4:5], exec
	s_cselect_b32 s4, 1, s20

.LBB0_429:
	s_cmp_eq_u32 s4, s84
	s_cselect_b64 s[16:17], -1, 0
	s_cmp_lg_u32 s4, s84
	s_cselect_b64 s[18:19], -1, 0
	s_lshl_b32 s5, s4, 6
	v_or_b32_e32 v0, s5, v179
	v_sub_u32_e32 v4, v153, v0
	v_cvt_f32_i32_e32 v0, v4
	v_cndmask_b32_e64 v1, v206, 0, s[16:17]
	s_mov_b32 s20, 2.0
	s_mov_b32 s22, 0x41200000
	v_fma_f32 v10, -v144, v0, -v1
	ds_read_b128 v[0:3], v180 offset:17408
	ds_read_b128 v[6:9], v176
	s_mov_b32 s24, 0x41800000
	s_mov_b32 s28, 0x41900000
	s_mov_b32 s21, 0x40400000
	s_mov_b32 s23, 0x41300000
	s_mov_b32 s25, 0x41880000
	s_mov_b32 s29, 0x41980000
	v_add_f32_e32 v14, v204, v10
	v_fma_f32 v96, 0, v144, v10
	v_add_f32_e32 v97, v144, v10
	v_fma_f32 v98, v144, s20, v10
	v_fma_f32 v99, v145, s21, v10
	v_fma_f32 v100, v144, s38, v10
	v_fma_f32 v101, v145, s39, v10
	v_fma_f32 v102, v144, s22, v10
	v_fma_f32 v103, v145, s23, v10
	v_fma_f32 v104, v144, s24, v10
	v_fma_f32 v105, v145, s25, v10
	v_fma_f32 v106, v144, s28, v10
	v_fma_f32 v107, v145, s29, v10
	v_fma_f32 v108, v144, s26, v10
	v_fma_f32 v109, v145, s27, v10
	v_fma_f32 v110, v144, s36, v10
	v_fma_f32 v111, v145, s37, v10
	ds_read_b128 v[10:13], v180 offset:26112
	v_fma_f32 v80, 0, v144, v14
	s_waitcnt lgkmcnt(1)
	v_mfma_f32_32x32x16_bf16 v[96:111], v[0:3], v[6:9], v[96:111]
	v_add_f32_e32 v81, v144, v14
	v_fma_f32 v82, v144, s20, v14
	v_fma_f32 v83, v145, s21, v14
	v_fma_f32 v84, v144, s38, v14
	v_fma_f32 v85, v145, s39, v14
	v_fma_f32 v86, v144, s22, v14
	v_fma_f32 v87, v145, s23, v14
	v_fma_f32 v88, v144, s24, v14
	v_fma_f32 v89, v145, s25, v14
	v_fma_f32 v90, v144, s28, v14
	v_fma_f32 v91, v145, s29, v14
	v_fma_f32 v92, v144, s26, v14
	v_fma_f32 v93, v145, s27, v14
	v_fma_f32 v94, v144, s36, v14
	v_fma_f32 v95, v145, s37, v14
	s_or_b32 s4, s5, 63
	s_sub_i32 s20, s49, s4
	s_waitcnt lgkmcnt(0)
	v_mfma_f32_32x32x16_bf16 v[80:95], v[10:13], v[6:9], v[80:95]
	ds_read_b128 v[0:3], v180 offset:17440
	ds_read_b128 v[6:9], v176 offset:32
	s_mov_b32 s4, 0
	s_cmpk_gt_i32 s20, 0x200
	s_waitcnt lgkmcnt(0)
	v_mfma_f32_32x32x16_bf16 v[96:111], v[0:3], v[6:9], v[96:111]
	ds_read_b128 v[0:3], v180 offset:26144
	s_waitcnt lgkmcnt(0)
	v_mfma_f32_32x32x16_bf16 v[80:95], v[0:3], v[6:9], v[80:95]
	ds_read_b128 v[0:3], v180 offset:17472
	ds_read_b128 v[6:9], v176 offset:64
	s_waitcnt lgkmcnt(0)
	v_mfma_f32_32x32x16_bf16 v[96:111], v[0:3], v[6:9], v[96:111]
	ds_read_b128 v[0:3], v180 offset:26176
	s_waitcnt lgkmcnt(0)
	v_mfma_f32_32x32x16_bf16 v[80:95], v[0:3], v[6:9], v[80:95]
	ds_read_b128 v[0:3], v180 offset:17504
	ds_read_b128 v[6:9], v176 offset:96
	s_waitcnt lgkmcnt(0)
	v_mfma_f32_32x32x16_bf16 v[96:111], v[0:3], v[6:9], v[96:111]
	ds_read_b128 v[0:3], v180 offset:26208
	s_waitcnt lgkmcnt(0)
	v_mfma_f32_32x32x16_bf16 v[80:95], v[0:3], v[6:9], v[80:95]
	ds_read_b128 v[0:3], v180 offset:17536
	ds_read_b128 v[6:9], v176 offset:128
	s_waitcnt lgkmcnt(0)
	v_mfma_f32_32x32x16_bf16 v[96:111], v[0:3], v[6:9], v[96:111]
	ds_read_b128 v[0:3], v180 offset:26240
	s_waitcnt lgkmcnt(0)
	v_mfma_f32_32x32x16_bf16 v[80:95], v[0:3], v[6:9], v[80:95]
	ds_read_b128 v[0:3], v180 offset:17568
	ds_read_b128 v[6:9], v176 offset:160
	s_waitcnt lgkmcnt(0)
	v_mfma_f32_32x32x16_bf16 v[96:111], v[0:3], v[6:9], v[96:111]
	ds_read_b128 v[0:3], v180 offset:26272
	s_waitcnt lgkmcnt(0)
	v_mfma_f32_32x32x16_bf16 v[80:95], v[0:3], v[6:9], v[80:95]
	ds_read_b128 v[0:3], v180 offset:17600
	ds_read_b128 v[6:9], v176 offset:192
	s_waitcnt lgkmcnt(0)
	v_mfma_f32_32x32x16_bf16 v[96:111], v[0:3], v[6:9], v[96:111]
	ds_read_b128 v[0:3], v180 offset:26304
	s_waitcnt lgkmcnt(0)
	v_mfma_f32_32x32x16_bf16 v[80:95], v[0:3], v[6:9], v[80:95]
	ds_read_b128 v[0:3], v180 offset:17632
	ds_read_b128 v[6:9], v176 offset:224
	s_waitcnt lgkmcnt(0)
	v_mfma_f32_32x32x16_bf16 v[96:111], v[0:3], v[6:9], v[96:111]
	ds_read_b128 v[0:3], v180 offset:26336
	s_waitcnt lgkmcnt(0)
	v_mfma_f32_32x32x16_bf16 v[80:95], v[0:3], v[6:9], v[80:95]
	s_cbranch_scc1 .LBB0_431
	s_sub_i32 s24, s46, s5
	s_cmpk_gt_i32 s20, 0x80
	s_cselect_b64 s[4:5], -1, 0
	s_cmpk_lt_i32 s24, 0x201
	s_cselect_b64 s[22:23], -1, 0
	s_and_b64 s[4:5], s[4:5], s[22:23]
	s_cmp_gt_i32 s20, -1
	s_cselect_b64 s[20:21], -1, 0
	s_cmpk_lt_i32 s24, 0x81
	s_cselect_b64 s[22:23], -1, 0
	s_and_b64 s[20:21], s[20:21], s[22:23]
	s_and_b64 s[20:21], s[20:21], exec
	s_cselect_b32 s20, 2, 3
	s_and_b64 s[4:5], s[4:5], exec
	s_cselect_b32 s4, 1, s20

.LBB0_630:
	s_mov_b64 s[22:23], -1
	s_cmp_lg_u32 s4, 1
	v_and_b32_e32 v4, 15, v4
	s_cbranch_scc0 .LBB0_632
	v_cmp_eq_u32_e32 vcc, 1, v4
	s_mov_b64 s[22:23], 0
	s_nop 0
	v_cndmask_b32_e64 v9, v196, 0, vcc
	v_cmp_eq_u32_e32 vcc, 0, v4
	s_nop 1
	v_cndmask_b32_e64 v8, v196, 0, vcc
	v_cmp_eq_u32_e32 vcc, 3, v4
	v_add_f32_e32 v2, v8, v80
	v_add_f32_e32 v3, v9, v81
	v_add_f32_e32 v160, v8, v96
	v_add_f32_e32 v161, v9, v97
	v_cndmask_b32_e64 v13, v196, 0, vcc
	v_cmp_eq_u32_e32 vcc, 2, v4
	v_add_f32_e32 v170, v8, v104
	v_add_f32_e32 v171, v9, v105
	v_add_f32_e32 v14, v8, v88
	v_add_f32_e32 v15, v9, v89
	v_cndmask_b32_e64 v12, v196, 0, vcc
	v_cmp_eq_u32_e32 vcc, 9, v4
	v_add_f32_e32 v6, v12, v82
	v_add_f32_e32 v7, v13, v83
	v_add_f32_e32 v164, v12, v98
	v_add_f32_e32 v165, v13, v99
	v_cndmask_b32_e64 v159, v196, 0, vcc
	v_cmp_eq_u32_e32 vcc, 8, v4
	v_add_f32_e32 v166, v12, v106
	v_add_f32_e32 v167, v13, v107
	v_add_f32_e32 v12, v12, v90
	v_add_f32_e32 v13, v13, v91
	v_cndmask_b32_e64 v158, v196, 0, vcc
	v_cmp_eq_u32_e32 vcc, 11, v4
	v_add_f32_e32 v10, v158, v84
	v_add_f32_e32 v11, v159, v85
	v_add_f32_e32 v168, v158, v100
	v_add_f32_e32 v169, v159, v101
	v_cndmask_b32_e64 v1, v196, 0, vcc
	v_cmp_eq_u32_e32 vcc, 10, v4
	v_add_f32_e32 v162, v158, v108
	v_add_f32_e32 v163, v159, v109
	v_add_f32_e32 v8, v158, v92
	v_add_f32_e32 v9, v159, v93
	v_cndmask_b32_e64 v0, v196, 0, vcc
	v_add_f32_e32 v156, v0, v86
	v_add_f32_e32 v157, v1, v87
	v_add_f32_e32 v172, v0, v102
	v_add_f32_e32 v173, v1, v103
	v_add_f32_e32 v158, v0, v110
	v_add_f32_e32 v0, v0, v94

.LBB0_637:
	s_andn2_b64 vcc, exec, s[20:21]
	s_cbranch_vccnz .LBB0_639
	v_cmp_lt_f32_e32 vcc, s38, v4
	s_or_b64 vcc, s[16:17], vcc
	s_nop 0
	v_cndmask_b32_e32 v80, 0, v4, vcc
	v_add_f32_e32 v81, v206, v80
	v_cndmask_b32_e64 v206, v81, v4, s[16:17]
	v_exp_f32_e64 v4, -v80
	v_sub_f32_e32 v160, v160, v80
	v_sub_f32_e32 v161, v161, v80
	v_sub_f32_e32 v2, v2, v80
	v_sub_f32_e32 v3, v3, v80
	v_sub_f32_e32 v164, v164, v80
	v_sub_f32_e32 v165, v165, v80
	v_sub_f32_e32 v6, v6, v80
	v_sub_f32_e32 v7, v7, v80
	v_sub_f32_e32 v168, v168, v80
	v_sub_f32_e32 v169, v169, v80
	v_sub_f32_e32 v10, v10, v80
	v_sub_f32_e32 v11, v11, v80
	v_sub_f32_e32 v172, v172, v80
	v_sub_f32_e32 v173, v173, v80
	v_sub_f32_e32 v156, v156, v80
	v_sub_f32_e32 v157, v157, v80
	v_sub_f32_e32 v170, v170, v80
	v_sub_f32_e32 v171, v171, v80
	v_sub_f32_e32 v14, v14, v80
	v_sub_f32_e32 v15, v15, v80
	v_sub_f32_e32 v166, v166, v80
	v_sub_f32_e32 v167, v167, v80
	v_sub_f32_e32 v12, v12, v80
	v_sub_f32_e32 v13, v13, v80
	v_sub_f32_e32 v162, v162, v80
	v_sub_f32_e32 v163, v163, v80
	v_sub_f32_e32 v8, v8, v80
	v_sub_f32_e32 v9, v9, v80
	v_sub_f32_e32 v158, v158, v80
	v_sub_f32_e32 v159, v159, v80
	v_sub_f32_e32 v0, v0, v80
	v_sub_f32_e32 v1, v1, v80
	v_pk_mul_f32 v[78:79], v[78:79], v[4:5] op_sel_hi:[1,0]
	v_pk_mul_f32 v[76:77], v[76:77], v[4:5] op_sel_hi:[1,0]
	v_pk_mul_f32 v[74:75], v[74:75], v[4:5] op_sel_hi:[1,0]
	v_pk_mul_f32 v[72:73], v[72:73], v[4:5] op_sel_hi:[1,0]
	v_pk_mul_f32 v[70:71], v[70:71], v[4:5] op_sel_hi:[1,0]
	v_pk_mul_f32 v[68:69], v[68:69], v[4:5] op_sel_hi:[1,0]
	v_pk_mul_f32 v[66:67], v[66:67], v[4:5] op_sel_hi:[1,0]
	v_pk_mul_f32 v[64:65], v[64:65], v[4:5] op_sel_hi:[1,0]
	v_pk_mul_f32 v[62:63], v[62:63], v[4:5] op_sel_hi:[1,0]
	v_pk_mul_f32 v[60:61], v[60:61], v[4:5] op_sel_hi:[1,0]
	v_pk_mul_f32 v[58:59], v[58:59], v[4:5] op_sel_hi:[1,0]
	v_pk_mul_f32 v[56:57], v[56:57], v[4:5] op_sel_hi:[1,0]
	v_pk_mul_f32 v[54:55], v[54:55], v[4:5] op_sel_hi:[1,0]
	v_pk_mul_f32 v[52:53], v[52:53], v[4:5] op_sel_hi:[1,0]
	v_pk_mul_f32 v[50:51], v[50:51], v[4:5] op_sel_hi:[1,0]
	v_pk_mul_f32 v[48:49], v[48:49], v[4:5] op_sel_hi:[1,0]
	v_pk_mul_f32 v[46:47], v[46:47], v[4:5] op_sel_hi:[1,0]
	v_pk_mul_f32 v[44:45], v[44:45], v[4:5] op_sel_hi:[1,0]
	v_pk_mul_f32 v[42:43], v[42:43], v[4:5] op_sel_hi:[1,0]
	v_pk_mul_f32 v[40:41], v[40:41], v[4:5] op_sel_hi:[1,0]
	v_pk_mul_f32 v[38:39], v[38:39], v[4:5] op_sel_hi:[1,0]
	v_pk_mul_f32 v[36:37], v[36:37], v[4:5] op_sel_hi:[1,0]
	v_pk_mul_f32 v[34:35], v[34:35], v[4:5] op_sel_hi:[1,0]
	v_pk_mul_f32 v[32:33], v[32:33], v[4:5] op_sel_hi:[1,0]
	v_pk_mul_f32 v[30:31], v[30:31], v[4:5] op_sel_hi:[1,0]
	v_pk_mul_f32 v[28:29], v[28:29], v[4:5] op_sel_hi:[1,0]
	v_pk_mul_f32 v[26:27], v[26:27], v[4:5] op_sel_hi:[1,0]
	v_pk_mul_f32 v[24:25], v[24:25], v[4:5] op_sel_hi:[1,0]
	v_pk_mul_f32 v[22:23], v[22:23], v[4:5] op_sel_hi:[1,0]
	v_pk_mul_f32 v[20:21], v[20:21], v[4:5] op_sel_hi:[1,0]
	v_pk_mul_f32 v[18:19], v[18:19], v[4:5] op_sel_hi:[1,0]
	v_pk_mul_f32 v[16:17], v[16:17], v[4:5] op_sel_hi:[1,0]
	v_mul_f32_e32 v205, v205, v4
.LBB0_639:
	v_exp_f32_e32 v100, v160
	v_exp_f32_e32 v101, v2
	v_exp_f32_e32 v4, v161
	v_exp_f32_e32 v80, v3
	v_exp_f32_e32 v102, v6
	v_add_f32_e32 v81, v101, v100
	v_exp_f32_e32 v82, v7
	v_add_f32_e32 v2, v80, v4
	v_add_f32_e32 v3, v81, v5
	v_exp_f32_e32 v81, v164
	v_add_f32_e32 v3, v2, v3
	v_exp_f32_e32 v2, v165
	v_exp_f32_e32 v84, v11
	v_add_f32_e32 v83, v102, v81
	v_exp_f32_e32 v86, v157
	v_add_f32_e32 v6, v82, v2
	v_add_f32_e32 v7, v83, v3
	v_exp_f32_e32 v3, v168
	v_add_f32_e32 v7, v6, v7
	v_exp_f32_e32 v83, v10
	v_exp_f32_e32 v6, v169
	v_exp_f32_e32 v90, v15
	v_exp_f32_e32 v92, v13
	v_add_f32_e32 v85, v83, v3
	v_add_f32_e32 v10, v84, v6
	v_add_f32_e32 v11, v85, v7
	v_exp_f32_e32 v7, v172
	v_add_f32_e32 v11, v10, v11
	v_exp_f32_e32 v85, v156
	v_exp_f32_e32 v10, v173
	v_exp_f32_e32 v94, v9
	v_exp_f32_e32 v98, v1
	v_add_f32_e32 v87, v85, v7
	v_add_f32_e32 v88, v86, v10
	v_add_f32_e32 v89, v87, v11
	v_exp_f32_e32 v11, v170
	v_add_f32_e32 v89, v88, v89
	v_exp_f32_e32 v87, v14
	v_exp_f32_e32 v88, v171
	v_add_f32_e32 v91, v87, v11
	v_add_f32_e32 v14, v90, v88
	v_add_f32_e32 v15, v91, v89
	v_exp_f32_e32 v89, v166
	v_add_f32_e32 v15, v14, v15
	v_exp_f32_e32 v91, v12
	v_exp_f32_e32 v14, v167
	v_add_f32_e32 v93, v91, v89
	v_add_f32_e32 v12, v92, v14
	v_add_f32_e32 v13, v93, v15
	v_exp_f32_e32 v15, v162
	v_add_f32_e32 v13, v12, v13
	v_exp_f32_e32 v93, v8
	v_exp_f32_e32 v12, v163
	v_add_f32_e32 v95, v93, v15
	v_add_f32_e32 v8, v94, v12
	v_add_f32_e32 v9, v95, v13
	v_exp_f32_e32 v95, v0
	v_add_f32_e32 v97, v8, v9
	v_exp_f32_e32 v9, v158
	v_exp_f32_e32 v96, v159
	v_add_f32_e32 v99, v95, v9
	v_add_f32_e32 v0, v98, v96
	v_add_f32_e32 v1, v99, v97
	s_nop 0
	v_add_f32_e32 v160, v0, v1
	v_cvt_pk_bf16_f32 v0, v100, v4
	v_cvt_pk_bf16_f32 v1, v81, v2
	v_cvt_pk_bf16_f32 v2, v3, v6
	v_cvt_pk_bf16_f32 v3, v7, v10
	v_cvt_pk_bf16_f32 v6, v11, v88
	v_cvt_pk_bf16_f32 v7, v89, v14
	v_cvt_pk_bf16_f32 v8, v15, v12
	v_cvt_pk_bf16_f32 v9, v9, v96
	v_cvt_pk_bf16_f32 v10, v101, v80
	v_cvt_pk_bf16_f32 v11, v102, v82
	v_cvt_pk_bf16_f32 v12, v83, v84
	v_cvt_pk_bf16_f32 v13, v85, v86
	v_cvt_pk_bf16_f32 v80, v87, v90
	v_cvt_pk_bf16_f32 v81, v91, v92
	v_cvt_pk_bf16_f32 v82, v93, v94
	v_cvt_pk_bf16_f32 v83, v95, v98
	ds_read_b64_tr_b16 v[84:85], v181 offset:34816
	ds_read_b64_tr_b16 v[86:87], v181 offset:37376
	ds_read_b64_tr_b16 v[88:89], v181 offset:34880
	ds_read_b64_tr_b16 v[90:91], v181 offset:37440
	ds_read_b64_tr_b16 v[92:93], v181 offset:34944
	ds_read_b64_tr_b16 v[94:95], v181 offset:37504
	ds_read_b64_tr_b16 v[96:97], v181 offset:35008
	ds_read_b64_tr_b16 v[98:99], v181 offset:37568
	ds_read_b64_tr_b16 v[100:101], v181 offset:39936
	ds_read_b64_tr_b16 v[102:103], v181 offset:42496
	ds_read_b64_tr_b16 v[104:105], v181 offset:40000
	ds_read_b64_tr_b16 v[106:107], v181 offset:42560
	ds_read_b64_tr_b16 v[108:109], v181 offset:40064
	ds_read_b64_tr_b16 v[110:111], v181 offset:42624
	ds_read_b64_tr_b16 v[156:157], v181 offset:40128
	ds_read_b64_tr_b16 v[158:159], v181 offset:42688
	s_setprio 1
	s_waitcnt lgkmcnt(14)
	v_mfma_f32_32x32x16_bf16 v[64:79], v[84:87], v[0:3], v[64:79]
	s_waitcnt lgkmcnt(12)
	v_mfma_f32_32x32x16_bf16 v[48:63], v[88:91], v[0:3], v[48:63]
	s_waitcnt lgkmcnt(10)
	v_mfma_f32_32x32x16_bf16 v[32:47], v[92:95], v[0:3], v[32:47]
	s_waitcnt lgkmcnt(8)
	v_mfma_f32_32x32x16_bf16 v[16:31], v[96:99], v[0:3], v[16:31]
	s_setprio 0
	ds_read_b64_tr_b16 v[0:1], v181 offset:45056
	ds_read_b64_tr_b16 v[84:85], v181 offset:45120
	ds_read_b64_tr_b16 v[88:89], v181 offset:45184
	ds_read_b64_tr_b16 v[92:93], v181 offset:45248
	ds_read_b64_tr_b16 v[2:3], v181 offset:47616
	ds_read_b64_tr_b16 v[86:87], v181 offset:47680
	ds_read_b64_tr_b16 v[90:91], v181 offset:47744
	ds_read_b64_tr_b16 v[94:95], v181 offset:47808
	s_setprio 1
	s_waitcnt lgkmcnt(14)
	v_mfma_f32_32x32x16_bf16 v[64:79], v[100:103], v[6:9], v[64:79]
	s_waitcnt lgkmcnt(12)
	v_mfma_f32_32x32x16_bf16 v[48:63], v[104:107], v[6:9], v[48:63]
	s_waitcnt lgkmcnt(10)
	v_mfma_f32_32x32x16_bf16 v[32:47], v[108:111], v[6:9], v[32:47]
	s_waitcnt lgkmcnt(8)
	v_mfma_f32_32x32x16_bf16 v[16:31], v[156:159], v[6:9], v[16:31]
	s_setprio 0
	ds_read_b64_tr_b16 v[6:7], v181 offset:50176
	ds_read_b64_tr_b16 v[96:97], v181 offset:50240
	ds_read_b64_tr_b16 v[100:101], v181 offset:50304
	ds_read_b64_tr_b16 v[104:105], v181 offset:50368
	ds_read_b64_tr_b16 v[8:9], v181 offset:52736
	ds_read_b64_tr_b16 v[98:99], v181 offset:52800
	ds_read_b64_tr_b16 v[102:103], v181 offset:52864
	ds_read_b64_tr_b16 v[106:107], v181 offset:52928
	s_setprio 1
	s_waitcnt lgkmcnt(11)
	v_mfma_f32_32x32x16_bf16 v[64:79], v[0:3], v[10:13], v[64:79]
	s_waitcnt lgkmcnt(10)
	v_mfma_f32_32x32x16_bf16 v[48:63], v[84:87], v[10:13], v[48:63]
	s_waitcnt lgkmcnt(9)
	v_mfma_f32_32x32x16_bf16 v[32:47], v[88:91], v[10:13], v[32:47]
	s_waitcnt lgkmcnt(8)
	v_mfma_f32_32x32x16_bf16 v[16:31], v[92:95], v[10:13], v[16:31]
	s_setprio 0
	s_setprio 1
	s_waitcnt lgkmcnt(3)
	v_mfma_f32_32x32x16_bf16 v[64:79], v[6:9], v[80:83], v[64:79]
	s_waitcnt lgkmcnt(2)
	v_mfma_f32_32x32x16_bf16 v[48:63], v[96:99], v[80:83], v[48:63]
	s_waitcnt lgkmcnt(1)
	v_mfma_f32_32x32x16_bf16 v[32:47], v[100:103], v[80:83], v[32:47]
	s_waitcnt lgkmcnt(0)
	v_mfma_f32_32x32x16_bf16 v[16:31], v[104:107], v[80:83], v[16:31]
	s_setprio 0
	v_add_f32_e32 v205, v205, v160
	s_cmp_lt_i32 s92, 1
	s_cbranch_scc0 .LBB0_223
	s_branch .LBB0_224

.LBB0_650:
	v_exp_f32_e32 v100, v160
	v_exp_f32_e32 v101, v2
	v_exp_f32_e32 v4, v161
	v_exp_f32_e32 v80, v3
	v_exp_f32_e32 v102, v6
	v_add_f32_e32 v81, v101, v100
	v_exp_f32_e32 v82, v7
	v_add_f32_e32 v2, v80, v4
	v_add_f32_e32 v3, v81, v5
	v_exp_f32_e32 v81, v164
	v_add_f32_e32 v3, v2, v3
	v_exp_f32_e32 v2, v165
	v_exp_f32_e32 v84, v11
	v_add_f32_e32 v83, v102, v81
	v_exp_f32_e32 v86, v157
	v_add_f32_e32 v6, v82, v2
	v_add_f32_e32 v7, v83, v3
	v_exp_f32_e32 v3, v168
	v_add_f32_e32 v7, v6, v7
	v_exp_f32_e32 v83, v10
	v_exp_f32_e32 v6, v169
	v_exp_f32_e32 v90, v15
	v_exp_f32_e32 v92, v13
	v_add_f32_e32 v85, v83, v3
	v_add_f32_e32 v10, v84, v6
	v_add_f32_e32 v11, v85, v7
	v_exp_f32_e32 v7, v172
	v_add_f32_e32 v11, v10, v11
	v_exp_f32_e32 v85, v156
	v_exp_f32_e32 v10, v173
	v_exp_f32_e32 v94, v9
	v_exp_f32_e32 v98, v1
	v_add_f32_e32 v87, v85, v7
	v_add_f32_e32 v88, v86, v10
	v_add_f32_e32 v89, v87, v11
	v_exp_f32_e32 v11, v170
	v_add_f32_e32 v89, v88, v89
	v_exp_f32_e32 v87, v14
	v_exp_f32_e32 v88, v171
	v_add_f32_e32 v91, v87, v11
	v_add_f32_e32 v14, v90, v88
	v_add_f32_e32 v15, v91, v89
	v_exp_f32_e32 v89, v166
	v_add_f32_e32 v15, v14, v15
	v_exp_f32_e32 v91, v12
	v_exp_f32_e32 v14, v167
	v_add_f32_e32 v93, v91, v89
	v_add_f32_e32 v12, v92, v14
	v_add_f32_e32 v13, v93, v15
	v_exp_f32_e32 v15, v162
	v_add_f32_e32 v13, v12, v13
	v_exp_f32_e32 v93, v8
	v_exp_f32_e32 v12, v163
	v_add_f32_e32 v95, v93, v15
	v_add_f32_e32 v8, v94, v12
	v_add_f32_e32 v9, v95, v13
	v_exp_f32_e32 v95, v0
	v_add_f32_e32 v97, v8, v9
	v_exp_f32_e32 v9, v158
	v_exp_f32_e32 v96, v159
	v_add_f32_e32 v99, v95, v9
	v_add_f32_e32 v0, v98, v96
	v_add_f32_e32 v1, v99, v97
	s_nop 0
	v_add_f32_e32 v160, v0, v1
	v_cvt_pk_bf16_f32 v0, v100, v4
	v_cvt_pk_bf16_f32 v1, v81, v2
	v_cvt_pk_bf16_f32 v2, v3, v6
	v_cvt_pk_bf16_f32 v3, v7, v10
	v_cvt_pk_bf16_f32 v6, v11, v88
	v_cvt_pk_bf16_f32 v7, v89, v14
	v_cvt_pk_bf16_f32 v8, v15, v12
	v_cvt_pk_bf16_f32 v9, v9, v96
	v_cvt_pk_bf16_f32 v10, v101, v80
	v_cvt_pk_bf16_f32 v11, v102, v82
	v_cvt_pk_bf16_f32 v12, v83, v84
	v_cvt_pk_bf16_f32 v13, v85, v86
	v_cvt_pk_bf16_f32 v80, v87, v90
	v_cvt_pk_bf16_f32 v81, v91, v92
	v_cvt_pk_bf16_f32 v82, v93, v94
	v_cvt_pk_bf16_f32 v83, v95, v98
	ds_read_b64_tr_b16 v[84:85], v181 offset:55296
	ds_read_b64_tr_b16 v[86:87], v181 offset:57856
	ds_read_b64_tr_b16 v[88:89], v181 offset:55360
	ds_read_b64_tr_b16 v[90:91], v181 offset:57920
	ds_read_b64_tr_b16 v[92:93], v181 offset:55424
	ds_read_b64_tr_b16 v[94:95], v181 offset:57984
	ds_read_b64_tr_b16 v[96:97], v181 offset:55488
	ds_read_b64_tr_b16 v[98:99], v181 offset:58048
	ds_read_b64_tr_b16 v[100:101], v181 offset:60416
	ds_read_b64_tr_b16 v[102:103], v181 offset:62976
	ds_read_b64_tr_b16 v[104:105], v181 offset:60480
	ds_read_b64_tr_b16 v[106:107], v181 offset:63040
	ds_read_b64_tr_b16 v[108:109], v181 offset:60544
	ds_read_b64_tr_b16 v[110:111], v181 offset:63104
	ds_read_b64_tr_b16 v[156:157], v181 offset:60608
	ds_read_b64_tr_b16 v[158:159], v181 offset:63168
	s_setprio 1
	s_waitcnt lgkmcnt(14)
	v_mfma_f32_32x32x16_bf16 v[64:79], v[84:87], v[0:3], v[64:79]
	s_waitcnt lgkmcnt(12)
	v_mfma_f32_32x32x16_bf16 v[48:63], v[88:91], v[0:3], v[48:63]
	s_waitcnt lgkmcnt(10)
	v_mfma_f32_32x32x16_bf16 v[32:47], v[92:95], v[0:3], v[32:47]
	s_waitcnt lgkmcnt(8)
	v_mfma_f32_32x32x16_bf16 v[16:31], v[96:99], v[0:3], v[16:31]
	s_setprio 0
	ds_read_b64_tr_b16 v[0:1], v224 offset:30720
	ds_read_b64_tr_b16 v[84:85], v224 offset:30784
	ds_read_b64_tr_b16 v[88:89], v224 offset:30848
	ds_read_b64_tr_b16 v[92:93], v224 offset:30912
	ds_read_b64_tr_b16 v[2:3], v224 offset:33280
	ds_read_b64_tr_b16 v[86:87], v224 offset:33344
	ds_read_b64_tr_b16 v[90:91], v224 offset:33408
	ds_read_b64_tr_b16 v[94:95], v224 offset:33472
	s_setprio 1
	s_waitcnt lgkmcnt(14)
	v_mfma_f32_32x32x16_bf16 v[64:79], v[100:103], v[6:9], v[64:79]
	s_waitcnt lgkmcnt(12)
	v_mfma_f32_32x32x16_bf16 v[48:63], v[104:107], v[6:9], v[48:63]
	s_waitcnt lgkmcnt(10)
	v_mfma_f32_32x32x16_bf16 v[32:47], v[108:111], v[6:9], v[32:47]
	s_waitcnt lgkmcnt(8)
	v_mfma_f32_32x32x16_bf16 v[16:31], v[156:159], v[6:9], v[16:31]
	s_setprio 0
	ds_read_b64_tr_b16 v[6:7], v224 offset:35840
	ds_read_b64_tr_b16 v[96:97], v224 offset:35904
	ds_read_b64_tr_b16 v[100:101], v224 offset:35968
	ds_read_b64_tr_b16 v[104:105], v224 offset:36032
	ds_read_b64_tr_b16 v[8:9], v224 offset:38400
	ds_read_b64_tr_b16 v[98:99], v224 offset:38464
	ds_read_b64_tr_b16 v[102:103], v224 offset:38528
	ds_read_b64_tr_b16 v[106:107], v224 offset:38592
	s_setprio 1
	s_waitcnt lgkmcnt(11)
	v_mfma_f32_32x32x16_bf16 v[64:79], v[0:3], v[10:13], v[64:79]
	s_waitcnt lgkmcnt(10)
	v_mfma_f32_32x32x16_bf16 v[48:63], v[84:87], v[10:13], v[48:63]
	s_waitcnt lgkmcnt(9)
	v_mfma_f32_32x32x16_bf16 v[32:47], v[88:91], v[10:13], v[32:47]
	s_waitcnt lgkmcnt(8)
	v_mfma_f32_32x32x16_bf16 v[16:31], v[92:95], v[10:13], v[16:31]
	s_setprio 0
	s_setprio 1
	s_waitcnt lgkmcnt(3)
	v_mfma_f32_32x32x16_bf16 v[64:79], v[6:9], v[80:83], v[64:79]
	s_waitcnt lgkmcnt(2)
	v_mfma_f32_32x32x16_bf16 v[48:63], v[96:99], v[80:83], v[48:63]
	s_waitcnt lgkmcnt(1)
	v_mfma_f32_32x32x16_bf16 v[32:47], v[100:103], v[80:83], v[32:47]
	s_waitcnt lgkmcnt(0)
	v_mfma_f32_32x32x16_bf16 v[16:31], v[104:107], v[80:83], v[16:31]
	s_setprio 0
	v_add_f32_e32 v205, v205, v160
	s_andn2_b64 vcc, exec, s[14:15]
	s_cbranch_vccnz .LBB0_219

.LBB0_667:
	v_cvt_f32_i32_e32 v4, v180
	s_cmp_eq_u32 s23, -1
	s_cselect_b64 s[18:19], -1, 0
	v_cndmask_b32_e64 v3, v169, 0, s[18:19]
	v_fma_f32 v4, -v154, v4, -v3
	s_mov_b32 s20, 2.0
	v_add_f32_e32 v6, v153, v4
	s_mov_b32 s21, 0x40400000
	v_fma_f32 v98, v154, s20, v4
	v_fma_f32 v99, v155, s21, v4
	v_fma_f32 v82, v154, s20, v6
	v_fma_f32 v83, v155, s21, v6
	s_mov_b32 s20, 0x41200000
	s_mov_b32 s21, 0x41300000
	v_fma_f32 v102, v154, s20, v4
	v_fma_f32 v103, v155, s21, v4
	v_fma_f32 v86, v154, s20, v6
	v_fma_f32 v87, v155, s21, v6
	s_mov_b32 s20, 0x41800000
	s_mov_b32 s21, 0x41880000
	v_fma_f32 v104, v154, s20, v4
	v_fma_f32 v105, v155, s21, v4
	v_fma_f32 v88, v154, s20, v6
	v_fma_f32 v89, v155, s21, v6
	s_mov_b32 s20, 0x41900000
	s_mov_b32 s21, 0x41980000
	v_fma_f32 v80, 0, v154, v6
	v_add_f32_e32 v81, v154, v6
	v_fma_f32 v84, v154, s38, v6
	v_fma_f32 v85, v155, s39, v6
	v_fma_f32 v90, v154, s20, v6
	v_fma_f32 v91, v155, s21, v6
	v_fma_f32 v92, v154, s26, v6
	v_fma_f32 v93, v155, s27, v6
	v_fma_f32 v94, v154, s36, v6
	v_fma_f32 v95, v155, s37, v6
	ds_read_b128 v[6:9], v166 offset:4608
	ds_read_b128 v[10:13], v166
	ds_read_b128 v[206:209], v166 offset:32
	v_fma_f32 v96, 0, v154, v4
	v_add_f32_e32 v97, v154, v4
	v_fma_f32 v100, v154, s38, v4
	v_fma_f32 v101, v155, s39, v4
	v_fma_f32 v106, v154, s20, v4
	v_fma_f32 v107, v155, s21, v4
	v_fma_f32 v108, v154, s26, v4
	v_fma_f32 v109, v155, s27, v4
	v_fma_f32 v110, v154, s36, v4
	v_fma_f32 v111, v155, s37, v4
	s_waitcnt vmcnt(6) lgkmcnt(2)
	v_mfma_f32_32x32x16_bf16 v[80:95], v[6:9], v[112:115], v[80:95]
	ds_read_b128 v[6:9], v166 offset:4640
	v_cmp_lt_i32_e32 vcc, 0, v180
	s_mov_b64 s[20:21], s[18:19]
	s_waitcnt lgkmcnt(2)
	v_mfma_f32_32x32x16_bf16 v[96:111], v[10:13], v[112:115], v[96:111]
	s_waitcnt vmcnt(5) lgkmcnt(1)
	v_mfma_f32_32x32x16_bf16 v[96:111], v[206:209], v[116:119], v[96:111]
	s_waitcnt lgkmcnt(0)
	v_mfma_f32_32x32x16_bf16 v[80:95], v[6:9], v[116:119], v[80:95]
	ds_read_b128 v[6:9], v166 offset:64
	ds_read_b128 v[10:13], v166 offset:4672
	s_waitcnt vmcnt(4) lgkmcnt(1)
	v_mfma_f32_32x32x16_bf16 v[96:111], v[6:9], v[120:123], v[96:111]
	s_waitcnt lgkmcnt(0)
	v_mfma_f32_32x32x16_bf16 v[80:95], v[10:13], v[120:123], v[80:95]
	ds_read_b128 v[6:9], v166 offset:96
	ds_read_b128 v[10:13], v166 offset:4704
	s_waitcnt vmcnt(3) lgkmcnt(1)
	v_mfma_f32_32x32x16_bf16 v[96:111], v[6:9], v[124:127], v[96:111]
	s_waitcnt lgkmcnt(0)
	v_mfma_f32_32x32x16_bf16 v[80:95], v[10:13], v[124:127], v[80:95]
	s_nop 9
	v_cndmask_b32_e32 v4, v196, v97, vcc
	v_cmp_lt_i32_e32 vcc, -1, v180
	s_nop 1
	v_cndmask_b32_e32 v211, v196, v96, vcc
	v_cmp_lt_i32_e32 vcc, 32, v180
	s_nop 1
	v_cndmask_b32_e32 v210, v196, v81, vcc
	v_cmp_lt_i32_e32 vcc, 31, v180
	s_nop 1
	v_cndmask_b32_e32 v212, v196, v80, vcc
	v_cmp_lt_i32_e32 vcc, 2, v180
	s_nop 1
	v_cndmask_b32_e32 v206, v196, v99, vcc
	v_cmp_lt_i32_e32 vcc, 1, v180
	s_nop 1
	v_cndmask_b32_e32 v208, v196, v98, vcc
	v_cmp_lt_i32_e32 vcc, 34, v180
	s_nop 1
	v_cndmask_b32_e32 v207, v196, v83, vcc
	v_cmp_lt_i32_e32 vcc, 33, v180
	s_nop 1
	v_cndmask_b32_e32 v209, v196, v82, vcc
	v_cmp_lt_i32_e32 vcc, 8, v180
	s_nop 1
	v_cndmask_b32_e32 v97, v196, v101, vcc
	v_cmp_lt_i32_e32 vcc, 7, v180
	s_nop 1
	v_cndmask_b32_e32 v99, v196, v100, vcc
	v_cmp_lt_i32_e32 vcc, 40, v180
	s_nop 1
	v_cndmask_b32_e32 v98, v196, v85, vcc
	v_cmp_lt_i32_e32 vcc, 39, v180
	s_nop 1
	v_cndmask_b32_e32 v100, v196, v84, vcc
	v_cmp_lt_i32_e32 vcc, 10, v180
	s_nop 1
	v_cndmask_b32_e32 v84, v196, v103, vcc
	v_cmp_lt_i32_e32 vcc, 9, v180
	s_nop 1
	v_cndmask_b32_e32 v96, v196, v102, vcc
	v_cmp_lt_i32_e32 vcc, 42, v180
	s_nop 1
	v_cndmask_b32_e32 v87, v196, v87, vcc
	v_cmp_lt_i32_e32 vcc, 41, v180
	s_nop 1
	v_cndmask_b32_e32 v86, v196, v86, vcc
	v_cmp_lt_i32_e32 vcc, 16, v180
	s_nop 1
	v_cndmask_b32_e32 v80, v196, v105, vcc
	v_cmp_lt_i32_e32 vcc, 15, v180
	s_nop 1
	v_cndmask_b32_e32 v83, v196, v104, vcc
	v_cmp_lt_i32_e32 vcc, 48, v180
	s_nop 1
	v_cndmask_b32_e32 v82, v196, v89, vcc
	v_cmp_lt_i32_e32 vcc, 47, v180
	v_max_f32_e32 v89, v210, v210
	s_nop 0
	v_cndmask_b32_e32 v85, v196, v88, vcc
	v_cmp_lt_i32_e32 vcc, 18, v180
	v_max_f32_e32 v88, v4, v4
	v_max_f32_e32 v88, v88, v89
	v_cndmask_b32_e32 v12, v196, v107, vcc
	v_cmp_lt_i32_e32 vcc, 17, v180
	v_max_f32_e32 v89, v208, v208
	v_max3_f32 v88, v211, v212, v88
	v_cndmask_b32_e32 v15, v196, v106, vcc
	v_cmp_lt_i32_e32 vcc, 50, v180
	s_nop 1
	v_cndmask_b32_e32 v14, v196, v91, vcc
	v_cmp_lt_i32_e32 vcc, 49, v180
	v_max_f32_e32 v91, v207, v207
	s_nop 0
	v_cndmask_b32_e32 v81, v196, v90, vcc
	v_max_f32_e32 v90, v209, v209
	v_max_f32_e32 v89, v89, v90
	v_max_f32_e32 v90, v206, v206
	v_max_f32_e32 v90, v90, v91
	v_max3_f32 v88, v88, v89, v90
	v_max_f32_e32 v89, v99, v99
	v_max_f32_e32 v90, v100, v100
	v_max_f32_e32 v89, v89, v90
	v_max_f32_e32 v90, v97, v97
	v_max_f32_e32 v91, v98, v98
	v_max_f32_e32 v90, v90, v91
	v_max3_f32 v88, v88, v89, v90
	v_max_f32_e32 v89, v96, v96
	v_max_f32_e32 v90, v86, v86
	v_max_f32_e32 v89, v89, v90
	v_max_f32_e32 v90, v84, v84
	v_max_f32_e32 v91, v87, v87
	v_max_f32_e32 v90, v90, v91
	v_cmp_lt_i32_e32 vcc, 24, v180
	v_max3_f32 v88, v88, v89, v90
	v_max_f32_e32 v89, v83, v83
	v_max_f32_e32 v90, v85, v85
	v_cndmask_b32_e32 v8, v196, v109, vcc
	v_cmp_lt_i32_e32 vcc, 23, v180
	v_max_f32_e32 v89, v89, v90
	v_max_f32_e32 v90, v80, v80
	v_max_f32_e32 v91, v82, v82
	v_cndmask_b32_e32 v11, v196, v108, vcc
	v_cmp_lt_i32_e32 vcc, 56, v180
	v_max_f32_e32 v90, v90, v91
	v_max3_f32 v88, v88, v89, v90
	v_cndmask_b32_e32 v10, v196, v93, vcc
	v_cmp_lt_i32_e32 vcc, 55, v180
	v_max_f32_e32 v89, v15, v15
	v_max_f32_e32 v90, v81, v81
	v_cndmask_b32_e32 v13, v196, v92, vcc
	v_cmp_lt_i32_e32 vcc, 26, v180
	v_max_f32_e32 v89, v89, v90
	v_max_f32_e32 v90, v12, v12
	v_max_f32_e32 v91, v14, v14
	v_cndmask_b32_e32 v3, v196, v111, vcc
	v_cmp_lt_i32_e32 vcc, 25, v180
	v_max_f32_e32 v90, v90, v91
	v_max3_f32 v88, v88, v89, v90
	v_cndmask_b32_e32 v7, v196, v110, vcc
	v_cmp_lt_i32_e32 vcc, 58, v180
	v_max_f32_e32 v89, v11, v11
	v_max_f32_e32 v90, v13, v13
	v_cndmask_b32_e32 v6, v196, v95, vcc
	v_cmp_lt_i32_e32 vcc, 57, v180
	v_max_f32_e32 v89, v89, v90
	v_max_f32_e32 v90, v8, v8
	v_max_f32_e32 v91, v10, v10
	v_cndmask_b32_e32 v9, v196, v94, vcc
	v_max_f32_e32 v90, v90, v91
	v_max3_f32 v88, v88, v89, v90
	v_max_f32_e32 v89, v7, v7
	v_max_f32_e32 v90, v9, v9
	v_max_f32_e32 v89, v89, v90
	v_max_f32_e32 v90, v3, v3
	v_max_f32_e32 v91, v6, v6
	v_max_f32_e32 v90, v90, v91
	v_max3_f32 v88, v88, v89, v90
	ds_bpermute_b32 v89, v174, v88
	s_and_b64 vcc, exec, s[18:19]
	s_waitcnt lgkmcnt(0)
	v_max_f32_e32 v89, v89, v89
	v_max_f32_e32 v88, v88, v89
	v_cmp_lt_f32_e64 s[44:45], s38, v88
	s_cbranch_vccnz .LBB0_669
	s_cmp_lg_u64 s[44:45], 0
	s_cselect_b64 s[20:21], -1, 0

.LBB0_671:
	v_exp_f32_e32 v108, v211
	v_exp_f32_e32 v109, v212
	v_exp_f32_e32 v4, v4
	v_exp_f32_e32 v88, v210
	v_exp_f32_e32 v110, v209
	v_add_f32_e32 v89, v109, v108
	v_exp_f32_e32 v92, v207
	v_add_f32_e32 v90, v88, v4
	v_add_f32_e32 v91, v89, v5
	v_exp_f32_e32 v89, v208
	v_add_f32_e32 v91, v90, v91
	v_exp_f32_e32 v90, v206
	v_exp_f32_e32 v98, v98
	v_add_f32_e32 v93, v110, v89
	v_exp_f32_e32 v14, v14
	v_add_f32_e32 v94, v92, v90
	v_add_f32_e32 v95, v93, v91
	v_exp_f32_e32 v91, v99
	v_add_f32_e32 v95, v94, v95
	v_exp_f32_e32 v93, v100
	v_exp_f32_e32 v94, v97
	v_exp_f32_e32 v102, v10
	v_exp_f32_e32 v106, v6
	v_add_f32_e32 v99, v93, v91
	v_add_f32_e32 v100, v98, v94
	v_add_f32_e32 v101, v99, v95
	v_exp_f32_e32 v95, v96
	v_add_f32_e32 v101, v100, v101
	v_exp_f32_e32 v99, v86
	v_exp_f32_e32 v100, v84
	v_exp_f32_e32 v96, v87
	v_exp_f32_e32 v84, v82
	v_add_f32_e32 v97, v99, v95
	v_add_f32_e32 v86, v96, v100
	v_add_f32_e32 v87, v97, v101
	s_nop 0
	v_add_f32_e32 v87, v86, v87
	v_exp_f32_e32 v97, v83
	v_exp_f32_e32 v101, v85
	v_exp_f32_e32 v86, v80
	v_add_f32_e32 v85, v101, v97
	v_add_f32_e32 v82, v84, v86
	v_add_f32_e32 v83, v85, v87
	v_exp_f32_e32 v85, v15
	v_add_f32_e32 v83, v82, v83
	v_exp_f32_e32 v87, v81
	v_exp_f32_e32 v82, v12
	v_exp_f32_e32 v12, v11
	v_add_f32_e32 v15, v87, v85
	v_add_f32_e32 v80, v14, v82
	v_add_f32_e32 v81, v15, v83
	v_exp_f32_e32 v15, v13
	v_add_f32_e32 v81, v80, v81
	v_exp_f32_e32 v80, v8
	v_exp_f32_e32 v13, v7
	v_add_f32_e32 v103, v15, v12
	v_add_f32_e32 v10, v102, v80
	v_add_f32_e32 v11, v103, v81
	s_nop 0
	v_add_f32_e32 v105, v10, v11
	v_exp_f32_e32 v103, v9
	v_exp_f32_e32 v104, v3
	v_add_f32_e32 v107, v103, v13
	v_add_f32_e32 v6, v106, v104
	v_add_f32_e32 v7, v107, v105
	s_nop 0
	v_add_f32_e32 v3, v6, v7
	v_cvt_pk_bf16_f32 v6, v108, v4
	v_cvt_pk_bf16_f32 v7, v89, v90
	v_cvt_pk_bf16_f32 v8, v91, v94
	v_cvt_pk_bf16_f32 v9, v95, v100
	v_cvt_pk_bf16_f32 v10, v97, v86
	v_cvt_pk_bf16_f32 v11, v85, v82
	v_cvt_pk_bf16_f32 v12, v12, v80
	v_cvt_pk_bf16_f32 v13, v13, v104
	v_cvt_pk_bf16_f32 v80, v109, v88
	v_cvt_pk_bf16_f32 v81, v110, v92
	v_cvt_pk_bf16_f32 v82, v93, v98
	v_cvt_pk_bf16_f32 v83, v99, v96
	v_cvt_pk_bf16_f32 v84, v101, v84
	v_cvt_pk_bf16_f32 v85, v87, v14
	v_cvt_pk_bf16_f32 v86, v15, v102
	v_cvt_pk_bf16_f32 v87, v103, v106
	ds_read_b64_tr_b16 v[88:89], v167 offset:18432
	ds_read_b64_tr_b16 v[90:91], v167 offset:20992
	ds_read_b64_tr_b16 v[92:93], v167 offset:18496
	ds_read_b64_tr_b16 v[94:95], v167 offset:21056
	ds_read_b64_tr_b16 v[96:97], v167 offset:18560
	ds_read_b64_tr_b16 v[98:99], v167 offset:21120
	ds_read_b64_tr_b16 v[100:101], v167 offset:18624
	ds_read_b64_tr_b16 v[102:103], v167 offset:21184
	ds_read_b64_tr_b16 v[104:105], v167 offset:23552
	ds_read_b64_tr_b16 v[106:107], v167 offset:26112
	ds_read_b64_tr_b16 v[108:109], v167 offset:23616
	ds_read_b64_tr_b16 v[110:111], v167 offset:26176
	ds_read_b64_tr_b16 v[206:207], v167 offset:23680
	ds_read_b64_tr_b16 v[208:209], v167 offset:26240
	ds_read_b64_tr_b16 v[210:211], v167 offset:23744
	ds_read_b64_tr_b16 v[212:213], v167 offset:26304
	s_setprio 1
	s_waitcnt lgkmcnt(14)
	v_mfma_f32_32x32x16_bf16 v[64:79], v[88:91], v[6:9], v[64:79]
	s_waitcnt lgkmcnt(12)
	v_mfma_f32_32x32x16_bf16 v[48:63], v[92:95], v[6:9], v[48:63]
	s_waitcnt lgkmcnt(10)
	v_mfma_f32_32x32x16_bf16 v[32:47], v[96:99], v[6:9], v[32:47]
	s_waitcnt lgkmcnt(8)
	v_mfma_f32_32x32x16_bf16 v[16:31], v[100:103], v[6:9], v[16:31]
	s_setprio 0
	ds_read_b64_tr_b16 v[6:7], v167 offset:28672
	ds_read_b64_tr_b16 v[88:89], v167 offset:28736
	ds_read_b64_tr_b16 v[92:93], v167 offset:28800
	ds_read_b64_tr_b16 v[96:97], v167 offset:28864
	ds_read_b64_tr_b16 v[8:9], v167 offset:31232
	ds_read_b64_tr_b16 v[90:91], v167 offset:31296
	ds_read_b64_tr_b16 v[94:95], v167 offset:31360
	ds_read_b64_tr_b16 v[98:99], v167 offset:31424
	s_setprio 1
	s_waitcnt lgkmcnt(14)
	v_mfma_f32_32x32x16_bf16 v[64:79], v[104:107], v[10:13], v[64:79]
	s_waitcnt lgkmcnt(12)
	v_mfma_f32_32x32x16_bf16 v[48:63], v[108:111], v[10:13], v[48:63]
	s_waitcnt lgkmcnt(10)
	v_mfma_f32_32x32x16_bf16 v[32:47], v[206:209], v[10:13], v[32:47]
	s_waitcnt lgkmcnt(8)
	v_mfma_f32_32x32x16_bf16 v[16:31], v[210:213], v[10:13], v[16:31]
	s_setprio 0
	ds_read_b64_tr_b16 v[10:11], v167 offset:33792
	ds_read_b64_tr_b16 v[100:101], v167 offset:33856
	ds_read_b64_tr_b16 v[104:105], v167 offset:33920
	ds_read_b64_tr_b16 v[108:109], v167 offset:33984
	ds_read_b64_tr_b16 v[12:13], v167 offset:36352
	ds_read_b64_tr_b16 v[102:103], v167 offset:36416
	ds_read_b64_tr_b16 v[106:107], v167 offset:36480
	ds_read_b64_tr_b16 v[110:111], v167 offset:36544
	s_setprio 1
	s_waitcnt lgkmcnt(11)
	v_mfma_f32_32x32x16_bf16 v[64:79], v[6:9], v[80:83], v[64:79]
	s_waitcnt lgkmcnt(10)
	v_mfma_f32_32x32x16_bf16 v[48:63], v[88:91], v[80:83], v[48:63]
	s_waitcnt lgkmcnt(9)
	v_mfma_f32_32x32x16_bf16 v[32:47], v[92:95], v[80:83], v[32:47]
	s_waitcnt lgkmcnt(8)
	v_mfma_f32_32x32x16_bf16 v[16:31], v[96:99], v[80:83], v[16:31]
	s_setprio 0
	s_setprio 1
	s_waitcnt lgkmcnt(3)
	v_mfma_f32_32x32x16_bf16 v[64:79], v[10:13], v[84:87], v[64:79]
	s_waitcnt lgkmcnt(2)
	v_mfma_f32_32x32x16_bf16 v[48:63], v[100:103], v[84:87], v[48:63]
	s_waitcnt lgkmcnt(1)
	v_mfma_f32_32x32x16_bf16 v[32:47], v[104:107], v[84:87], v[32:47]
	s_waitcnt lgkmcnt(0)
	v_mfma_f32_32x32x16_bf16 v[16:31], v[108:111], v[84:87], v[16:31]
	s_setprio 0
	v_add_f32_e32 v168, v168, v3
	s_cmp_lt_i32 s24, 1
	s_cbranch_scc0 .LBB0_659
	s_branch .LBB0_660

.LBB0_673:
	v_add_u32_e32 v212, 64, v180
	v_cvt_f32_i32_e32 v1, v212
	s_cmp_eq_u32 s23, 0
	s_cselect_b64 s[18:19], -1, 0
	v_cndmask_b32_e64 v0, v169, 0, s[18:19]
	v_fma_f32 v0, -v154, v1, -v0
	s_mov_b32 s20, 2.0
	v_add_f32_e32 v2, v153, v0
	s_mov_b32 s21, 0x40400000
	v_fma_f32 v98, v154, s20, v0
	v_fma_f32 v99, v155, s21, v0
	v_fma_f32 v82, v154, s20, v2
	v_fma_f32 v83, v155, s21, v2
	s_mov_b32 s20, 0x41200000
	s_mov_b32 s21, 0x41300000
	v_fma_f32 v102, v154, s20, v0
	v_fma_f32 v103, v155, s21, v0
	v_fma_f32 v86, v154, s20, v2
	v_fma_f32 v87, v155, s21, v2
	s_mov_b32 s20, 0x41800000
	s_mov_b32 s21, 0x41880000
	v_fma_f32 v104, v154, s20, v0
	v_fma_f32 v105, v155, s21, v0
	v_fma_f32 v88, v154, s20, v2
	v_fma_f32 v89, v155, s21, v2
	s_mov_b32 s20, 0x41900000
	s_mov_b32 s21, 0x41980000
	v_fma_f32 v96, 0, v154, v0
	v_fma_f32 v80, 0, v154, v2
	v_add_f32_e32 v97, v154, v0
	v_add_f32_e32 v81, v154, v2
	v_fma_f32 v100, v154, s38, v0
	v_fma_f32 v101, v155, s39, v0
	v_fma_f32 v84, v154, s38, v2
	v_fma_f32 v85, v155, s39, v2
	v_fma_f32 v106, v154, s20, v0
	v_fma_f32 v107, v155, s21, v0
	v_fma_f32 v90, v154, s20, v2
	v_fma_f32 v91, v155, s21, v2
	v_fma_f32 v108, v154, s26, v0
	v_fma_f32 v109, v155, s27, v0
	v_fma_f32 v92, v154, s26, v2
	v_fma_f32 v93, v155, s27, v2
	v_fma_f32 v110, v154, s36, v0
	v_fma_f32 v111, v155, s37, v0
	v_fma_f32 v94, v154, s36, v2
	v_fma_f32 v95, v155, s37, v2
	ds_read_b128 v[0:3], v166 offset:13824
	ds_read_b128 v[6:9], v166 offset:9216
	ds_read_b128 v[10:13], v166 offset:9248
	s_waitcnt vmcnt(6) lgkmcnt(1)
	v_mfma_f32_32x32x16_bf16 v[96:111], v[6:9], v[112:115], v[96:111]
	v_cmp_lt_i32_e32 vcc, 0, v212
	s_mov_b64 s[20:21], s[18:19]
	v_mfma_f32_32x32x16_bf16 v[80:95], v[0:3], v[112:115], v[80:95]
	ds_read_b128 v[0:3], v166 offset:13856
	s_waitcnt vmcnt(5) lgkmcnt(1)
	v_mfma_f32_32x32x16_bf16 v[96:111], v[10:13], v[116:119], v[96:111]
	s_waitcnt lgkmcnt(0)
	v_mfma_f32_32x32x16_bf16 v[80:95], v[0:3], v[116:119], v[80:95]
	ds_read_b128 v[0:3], v166 offset:9280
	ds_read_b128 v[6:9], v166 offset:13888
	s_waitcnt vmcnt(4) lgkmcnt(1)
	v_mfma_f32_32x32x16_bf16 v[96:111], v[0:3], v[120:123], v[96:111]
	s_waitcnt lgkmcnt(0)
	v_mfma_f32_32x32x16_bf16 v[80:95], v[6:9], v[120:123], v[80:95]
	ds_read_b128 v[0:3], v166 offset:9312
	ds_read_b128 v[6:9], v166 offset:13920
	s_waitcnt vmcnt(3) lgkmcnt(1)
	v_mfma_f32_32x32x16_bf16 v[96:111], v[0:3], v[124:127], v[96:111]
	s_waitcnt lgkmcnt(0)
	v_mfma_f32_32x32x16_bf16 v[80:95], v[6:9], v[124:127], v[80:95]
	s_nop 9
	v_cndmask_b32_e32 v4, v196, v97, vcc
	v_cmp_lt_i32_e32 vcc, -1, v212
	s_nop 1
	v_cndmask_b32_e32 v210, v196, v96, vcc
	v_cmp_lt_i32_e32 vcc, 32, v212
	s_nop 1
	v_cndmask_b32_e32 v209, v196, v81, vcc
	v_cmp_lt_i32_e32 vcc, 31, v212
	s_nop 1
	v_cndmask_b32_e32 v211, v196, v80, vcc
	v_cmp_lt_i32_e32 vcc, 2, v212
	s_nop 1
	v_cndmask_b32_e32 v99, v196, v99, vcc
	v_cmp_lt_i32_e32 vcc, 1, v212
	s_nop 1
	v_cndmask_b32_e32 v207, v196, v98, vcc
	v_cmp_lt_i32_e32 vcc, 34, v212
	s_nop 1
	v_cndmask_b32_e32 v206, v196, v83, vcc
	v_cmp_lt_i32_e32 vcc, 33, v212
	s_nop 1
	v_cndmask_b32_e32 v208, v196, v82, vcc
	v_cmp_lt_i32_e32 vcc, 8, v212
	s_nop 1
	v_cndmask_b32_e32 v96, v196, v101, vcc
	v_cmp_lt_i32_e32 vcc, 7, v212
	s_nop 1
	v_cndmask_b32_e32 v98, v196, v100, vcc
	v_cmp_lt_i32_e32 vcc, 40, v212
	s_nop 1
	v_cndmask_b32_e32 v97, v196, v85, vcc
	v_cmp_lt_i32_e32 vcc, 39, v212
	s_nop 1
	v_cndmask_b32_e32 v100, v196, v84, vcc
	v_cmp_lt_i32_e32 vcc, 10, v212
	s_nop 1
	v_cndmask_b32_e32 v81, v196, v103, vcc
	v_cmp_lt_i32_e32 vcc, 9, v212
	s_nop 1
	v_cndmask_b32_e32 v84, v196, v102, vcc
	v_cmp_lt_i32_e32 vcc, 42, v212
	s_nop 1
	v_cndmask_b32_e32 v83, v196, v87, vcc
	v_cmp_lt_i32_e32 vcc, 41, v212
	v_max_f32_e32 v87, v209, v209
	s_nop 0
	v_cndmask_b32_e32 v85, v196, v86, vcc
	v_cmp_lt_i32_e32 vcc, 16, v212
	v_max_f32_e32 v86, v4, v4
	v_max_f32_e32 v86, v86, v87
	v_cndmask_b32_e32 v13, v196, v105, vcc
	v_cmp_lt_i32_e32 vcc, 15, v212
	v_max_f32_e32 v87, v207, v207
	v_max3_f32 v86, v210, v211, v86
	v_cndmask_b32_e32 v80, v196, v104, vcc
	v_cmp_lt_i32_e32 vcc, 48, v212
	s_nop 1
	v_cndmask_b32_e32 v15, v196, v89, vcc
	v_cmp_lt_i32_e32 vcc, 47, v212
	v_max_f32_e32 v89, v206, v206
	s_nop 0
	v_cndmask_b32_e32 v82, v196, v88, vcc
	v_max_f32_e32 v88, v208, v208
	v_max_f32_e32 v87, v87, v88
	v_max_f32_e32 v88, v99, v99
	v_max_f32_e32 v88, v88, v89
	v_max3_f32 v86, v86, v87, v88
	v_max_f32_e32 v87, v98, v98
	v_max_f32_e32 v88, v100, v100
	v_max_f32_e32 v87, v87, v88
	v_max_f32_e32 v88, v96, v96
	v_max_f32_e32 v89, v97, v97
	v_cmp_lt_i32_e32 vcc, 18, v212
	v_max_f32_e32 v88, v88, v89
	v_max3_f32 v86, v86, v87, v88
	v_cndmask_b32_e32 v9, v196, v107, vcc
	v_cmp_lt_i32_e32 vcc, 17, v212
	v_max_f32_e32 v87, v84, v84
	v_max_f32_e32 v88, v85, v85
	v_cndmask_b32_e32 v12, v196, v106, vcc
	v_cmp_lt_i32_e32 vcc, 50, v212
	v_max_f32_e32 v87, v87, v88
	v_max_f32_e32 v88, v81, v81
	v_max_f32_e32 v89, v83, v83
	v_cndmask_b32_e32 v11, v196, v91, vcc
	v_cmp_lt_i32_e32 vcc, 49, v212
	v_max_f32_e32 v88, v88, v89
	v_max3_f32 v86, v86, v87, v88
	v_cndmask_b32_e32 v14, v196, v90, vcc
	v_cmp_lt_i32_e32 vcc, 24, v212
	v_max_f32_e32 v87, v80, v80
	v_max_f32_e32 v88, v82, v82
	v_cndmask_b32_e32 v3, v196, v109, vcc
	v_cmp_lt_i32_e32 vcc, 23, v212
	v_max_f32_e32 v87, v87, v88
	v_max_f32_e32 v88, v13, v13
	v_max_f32_e32 v89, v15, v15
	v_cndmask_b32_e32 v8, v196, v108, vcc
	v_cmp_lt_i32_e32 vcc, 56, v212
	v_max_f32_e32 v88, v88, v89
	v_max3_f32 v86, v86, v87, v88
	v_cndmask_b32_e32 v7, v196, v93, vcc
	v_cmp_lt_i32_e32 vcc, 55, v212
	v_max_f32_e32 v87, v12, v12
	v_max_f32_e32 v88, v14, v14
	v_cndmask_b32_e32 v10, v196, v92, vcc
	v_cmp_lt_i32_e32 vcc, 26, v212
	v_max_f32_e32 v87, v87, v88
	v_max_f32_e32 v88, v9, v9
	v_max_f32_e32 v89, v11, v11
	v_cndmask_b32_e32 v0, v196, v111, vcc
	v_cmp_lt_i32_e32 vcc, 25, v212
	v_max_f32_e32 v88, v88, v89
	v_max3_f32 v86, v86, v87, v88
	v_cndmask_b32_e32 v2, v196, v110, vcc
	v_cmp_lt_i32_e32 vcc, 58, v212
	v_max_f32_e32 v87, v8, v8
	v_max_f32_e32 v88, v10, v10
	v_cndmask_b32_e32 v1, v196, v95, vcc
	v_cmp_lt_i32_e32 vcc, 57, v212
	v_max_f32_e32 v87, v87, v88
	v_max_f32_e32 v88, v3, v3
	v_max_f32_e32 v89, v7, v7
	v_cndmask_b32_e32 v6, v196, v94, vcc
	v_max_f32_e32 v88, v88, v89
	v_max3_f32 v86, v86, v87, v88
	v_max_f32_e32 v87, v2, v2
	v_max_f32_e32 v88, v6, v6
	v_max_f32_e32 v87, v87, v88
	v_max_f32_e32 v88, v0, v0
	v_max_f32_e32 v89, v1, v1
	v_max_f32_e32 v88, v88, v89
	v_max3_f32 v86, v86, v87, v88
	ds_bpermute_b32 v87, v174, v86
	s_and_b64 vcc, exec, s[18:19]
	s_waitcnt lgkmcnt(0)
	v_max_f32_e32 v87, v87, v87
	v_max_f32_e32 v86, v86, v87
	v_cmp_lt_f32_e64 s[44:45], s38, v86
	s_cbranch_vccnz .LBB0_675
	s_cmp_lg_u64 s[44:45], 0
	s_cselect_b64 s[20:21], -1, 0

.LBB0_677:
	v_exp_f32_e32 v104, v210
	v_exp_f32_e32 v105, v211
	v_exp_f32_e32 v4, v4
	v_exp_f32_e32 v86, v209
	v_exp_f32_e32 v106, v208
	v_add_f32_e32 v87, v105, v104
	v_exp_f32_e32 v90, v206
	v_add_f32_e32 v88, v86, v4
	v_add_f32_e32 v89, v87, v5
	v_exp_f32_e32 v87, v207
	v_add_f32_e32 v89, v88, v89
	v_exp_f32_e32 v88, v99
	v_exp_f32_e32 v94, v97
	v_add_f32_e32 v91, v106, v87
	v_exp_f32_e32 v102, v1
	v_add_f32_e32 v92, v90, v88
	v_add_f32_e32 v93, v91, v89
	v_exp_f32_e32 v89, v98
	v_add_f32_e32 v93, v92, v93
	v_exp_f32_e32 v91, v100
	v_exp_f32_e32 v92, v96
	v_exp_f32_e32 v100, v7
	v_add_f32_e32 v95, v91, v89
	v_add_f32_e32 v96, v94, v92
	v_add_f32_e32 v97, v95, v93
	v_exp_f32_e32 v93, v84
	v_add_f32_e32 v97, v96, v97
	v_exp_f32_e32 v95, v85
	v_exp_f32_e32 v96, v81
	v_exp_f32_e32 v84, v83
	v_add_f32_e32 v85, v95, v93
	v_add_f32_e32 v98, v84, v96
	v_add_f32_e32 v99, v85, v97
	s_nop 0
	v_add_f32_e32 v99, v98, v99
	v_exp_f32_e32 v85, v80
	v_exp_f32_e32 v97, v82
	v_exp_f32_e32 v98, v13
	v_exp_f32_e32 v80, v15
	v_add_f32_e32 v81, v97, v85
	v_add_f32_e32 v82, v80, v98
	v_add_f32_e32 v83, v81, v99
	s_nop 0
	v_add_f32_e32 v83, v82, v83
	v_exp_f32_e32 v81, v12
	v_exp_f32_e32 v99, v14
	v_exp_f32_e32 v82, v9
	v_exp_f32_e32 v14, v11
	v_add_f32_e32 v15, v99, v81
	v_add_f32_e32 v12, v14, v82
	v_add_f32_e32 v13, v15, v83
	s_nop 0
	v_add_f32_e32 v13, v12, v13
	v_exp_f32_e32 v15, v8
	v_exp_f32_e32 v83, v10
	v_exp_f32_e32 v12, v3
	v_add_f32_e32 v101, v83, v15
	v_add_f32_e32 v8, v100, v12
	v_add_f32_e32 v9, v101, v13
	v_exp_f32_e32 v101, v6
	v_add_f32_e32 v11, v8, v9
	v_exp_f32_e32 v9, v2
	v_exp_f32_e32 v10, v0
	v_add_f32_e32 v103, v101, v9
	v_add_f32_e32 v0, v102, v10
	v_add_f32_e32 v1, v103, v11
	s_nop 0
	v_add_f32_e32 v210, v0, v1
	v_cvt_pk_bf16_f32 v0, v104, v4
	v_cvt_pk_bf16_f32 v1, v87, v88
	v_cvt_pk_bf16_f32 v2, v89, v92
	v_cvt_pk_bf16_f32 v3, v93, v96
	v_cvt_pk_bf16_f32 v6, v85, v98
	v_cvt_pk_bf16_f32 v7, v81, v82
	v_cvt_pk_bf16_f32 v8, v15, v12
	v_cvt_pk_bf16_f32 v9, v9, v10
	v_cvt_pk_bf16_f32 v10, v105, v86
	v_cvt_pk_bf16_f32 v11, v106, v90
	v_cvt_pk_bf16_f32 v12, v91, v94
	v_cvt_pk_bf16_f32 v13, v95, v84
	v_cvt_pk_bf16_f32 v80, v97, v80
	v_cvt_pk_bf16_f32 v81, v99, v14
	v_cvt_pk_bf16_f32 v82, v83, v100
	v_cvt_pk_bf16_f32 v83, v101, v102
	ds_read_b64_tr_b16 v[84:85], v167 offset:38912
	ds_read_b64_tr_b16 v[86:87], v167 offset:41472
	ds_read_b64_tr_b16 v[88:89], v167 offset:38976
	ds_read_b64_tr_b16 v[90:91], v167 offset:41536
	ds_read_b64_tr_b16 v[92:93], v167 offset:39040
	ds_read_b64_tr_b16 v[94:95], v167 offset:41600
	ds_read_b64_tr_b16 v[96:97], v167 offset:39104
	ds_read_b64_tr_b16 v[98:99], v167 offset:41664
	ds_read_b64_tr_b16 v[100:101], v167 offset:44032
	ds_read_b64_tr_b16 v[102:103], v167 offset:46592
	ds_read_b64_tr_b16 v[104:105], v167 offset:44096
	ds_read_b64_tr_b16 v[106:107], v167 offset:46656
	ds_read_b64_tr_b16 v[108:109], v167 offset:44160
	ds_read_b64_tr_b16 v[110:111], v167 offset:46720
	ds_read_b64_tr_b16 v[206:207], v167 offset:44224
	ds_read_b64_tr_b16 v[208:209], v167 offset:46784
	s_setprio 1
	s_waitcnt lgkmcnt(14)
	v_mfma_f32_32x32x16_bf16 v[64:79], v[84:87], v[0:3], v[64:79]
	s_waitcnt lgkmcnt(12)
	v_mfma_f32_32x32x16_bf16 v[48:63], v[88:91], v[0:3], v[48:63]
	s_waitcnt lgkmcnt(10)
	v_mfma_f32_32x32x16_bf16 v[32:47], v[92:95], v[0:3], v[32:47]
	s_waitcnt lgkmcnt(8)
	v_mfma_f32_32x32x16_bf16 v[16:31], v[96:99], v[0:3], v[16:31]
	s_setprio 0
	ds_read_b64_tr_b16 v[0:1], v167 offset:49152
	ds_read_b64_tr_b16 v[84:85], v167 offset:49216
	ds_read_b64_tr_b16 v[88:89], v167 offset:49280
	ds_read_b64_tr_b16 v[92:93], v167 offset:49344
	ds_read_b64_tr_b16 v[2:3], v167 offset:51712
	ds_read_b64_tr_b16 v[86:87], v167 offset:51776
	ds_read_b64_tr_b16 v[90:91], v167 offset:51840
	ds_read_b64_tr_b16 v[94:95], v167 offset:51904
	s_setprio 1
	s_waitcnt lgkmcnt(14)
	v_mfma_f32_32x32x16_bf16 v[64:79], v[100:103], v[6:9], v[64:79]
	s_waitcnt lgkmcnt(12)
	v_mfma_f32_32x32x16_bf16 v[48:63], v[104:107], v[6:9], v[48:63]
	s_waitcnt lgkmcnt(10)
	v_mfma_f32_32x32x16_bf16 v[32:47], v[108:111], v[6:9], v[32:47]
	s_waitcnt lgkmcnt(8)
	v_mfma_f32_32x32x16_bf16 v[16:31], v[206:209], v[6:9], v[16:31]
	s_setprio 0
	ds_read_b64_tr_b16 v[6:7], v167 offset:54272
	ds_read_b64_tr_b16 v[96:97], v167 offset:54336
	ds_read_b64_tr_b16 v[100:101], v167 offset:54400
	ds_read_b64_tr_b16 v[104:105], v167 offset:54464
	ds_read_b64_tr_b16 v[8:9], v167 offset:56832
	ds_read_b64_tr_b16 v[98:99], v167 offset:56896
	ds_read_b64_tr_b16 v[102:103], v167 offset:56960
	ds_read_b64_tr_b16 v[106:107], v167 offset:57024
	s_setprio 1
	s_waitcnt lgkmcnt(11)
	v_mfma_f32_32x32x16_bf16 v[64:79], v[0:3], v[10:13], v[64:79]
	s_waitcnt lgkmcnt(10)
	v_mfma_f32_32x32x16_bf16 v[48:63], v[84:87], v[10:13], v[48:63]
	s_waitcnt lgkmcnt(9)
	v_mfma_f32_32x32x16_bf16 v[32:47], v[88:91], v[10:13], v[32:47]
	s_waitcnt lgkmcnt(8)
	v_mfma_f32_32x32x16_bf16 v[16:31], v[92:95], v[10:13], v[16:31]
	s_setprio 0
	s_setprio 1
	s_waitcnt lgkmcnt(3)
	v_mfma_f32_32x32x16_bf16 v[64:79], v[6:9], v[80:83], v[64:79]
	s_waitcnt lgkmcnt(2)
	v_mfma_f32_32x32x16_bf16 v[48:63], v[96:99], v[80:83], v[48:63]
	s_waitcnt lgkmcnt(1)
	v_mfma_f32_32x32x16_bf16 v[32:47], v[100:103], v[80:83], v[32:47]
	s_waitcnt lgkmcnt(0)
	v_mfma_f32_32x32x16_bf16 v[16:31], v[104:107], v[80:83], v[16:31]
	s_setprio 0
	v_add_f32_e32 v168, v168, v210
	s_andn2_b64 vcc, exec, s[16:17]
	s_cbranch_vccz .LBB0_663
	s_branch .LBB0_664

.LBB0_690:
	v_cvt_f32_i32_e32 v4, v0
	s_cmp_eq_u32 s60, s52
	s_cselect_b64 s[44:45], -1, 0
	v_cndmask_b32_e64 v10, v169, 0, s[44:45]
	v_add_u32_e32 v14, s4, v166
	v_fma_f32 v4, -v154, v4, -v10
	ds_read_b128 v[10:13], v14
	s_mov_b32 s20, 2.0
	s_mov_b32 s22, 0x41200000
	s_mov_b32 s24, 0x41800000
	s_mov_b32 s28, 0x41900000
	s_mov_b32 s21, 0x40400000
	s_mov_b32 s23, 0x41300000
	s_mov_b32 s25, 0x41880000
	s_mov_b32 s29, 0x41980000
	v_fma_f32 v80, 0, v154, v4
	v_add_f32_e32 v81, v154, v4
	v_fma_f32 v82, v154, s20, v4
	v_fma_f32 v83, v155, s21, v4
	v_fma_f32 v84, v154, s38, v4
	v_fma_f32 v85, v155, s39, v4
	v_fma_f32 v86, v154, s22, v4
	v_fma_f32 v87, v155, s23, v4
	v_fma_f32 v88, v154, s24, v4
	v_fma_f32 v89, v155, s25, v4
	v_fma_f32 v90, v154, s28, v4
	v_fma_f32 v91, v155, s29, v4
	v_fma_f32 v92, v154, s26, v4
	v_fma_f32 v93, v155, s27, v4
	v_fma_f32 v94, v154, s36, v4
	v_fma_f32 v95, v155, s37, v4
	v_add_f32_e32 v4, v153, v4
	v_fma_f32 v96, 0, v154, v4
	s_waitcnt vmcnt(6) lgkmcnt(0)
	v_mfma_f32_32x32x16_bf16 v[80:95], v[10:13], v[112:115], v[80:95]
	ds_read_b128 v[10:13], v14 offset:32
	v_add_f32_e32 v97, v154, v4
	v_fma_f32 v98, v154, s20, v4
	v_fma_f32 v99, v155, s21, v4
	v_fma_f32 v100, v154, s38, v4
	v_fma_f32 v101, v155, s39, v4
	v_fma_f32 v102, v154, s22, v4
	v_fma_f32 v103, v155, s23, v4
	v_fma_f32 v104, v154, s24, v4
	v_fma_f32 v105, v155, s25, v4
	v_fma_f32 v106, v154, s28, v4
	v_fma_f32 v107, v155, s29, v4
	s_waitcnt vmcnt(5) lgkmcnt(0)
	v_mfma_f32_32x32x16_bf16 v[80:95], v[10:13], v[116:119], v[80:95]
	ds_read_b128 v[10:13], v14 offset:64
	v_fma_f32 v108, v154, s26, v4
	v_fma_f32 v109, v155, s27, v4
	v_fma_f32 v110, v154, s36, v4
	v_fma_f32 v111, v155, s37, v4
	s_cmp_lg_u32 s60, s52
	s_waitcnt vmcnt(4) lgkmcnt(0)
	v_mfma_f32_32x32x16_bf16 v[80:95], v[10:13], v[120:123], v[80:95]
	ds_read_b128 v[10:13], v14 offset:96
	ds_read_b128 v[170:173], v14 offset:4608
	s_waitcnt vmcnt(3) lgkmcnt(1)
	v_mfma_f32_32x32x16_bf16 v[80:95], v[10:13], v[124:127], v[80:95]
	ds_read_b128 v[10:13], v14 offset:4640
	s_waitcnt lgkmcnt(1)
	v_mfma_f32_32x32x16_bf16 v[96:111], v[170:173], v[112:115], v[96:111]
	s_nop 8
	v_max_f32_e32 v4, v81, v81
	s_waitcnt lgkmcnt(0)
	v_mfma_f32_32x32x16_bf16 v[96:111], v[10:13], v[116:119], v[96:111]
	ds_read_b128 v[10:13], v14 offset:4672
	s_waitcnt lgkmcnt(0)
	v_mfma_f32_32x32x16_bf16 v[96:111], v[10:13], v[120:123], v[96:111]
	ds_read_b128 v[10:13], v14 offset:4704
	s_waitcnt lgkmcnt(0)
	v_mfma_f32_32x32x16_bf16 v[96:111], v[10:13], v[124:127], v[96:111]
	s_nop 11
	v_max_f32_e32 v10, v97, v97
	v_max_f32_e32 v4, v4, v10
	v_max_f32_e32 v10, v82, v82
	v_max_f32_e32 v11, v98, v98
	v_max_f32_e32 v10, v10, v11
	v_max_f32_e32 v11, v83, v83
	v_max_f32_e32 v12, v99, v99
	v_max3_f32 v4, v80, v96, v4
	v_max_f32_e32 v11, v11, v12
	v_max3_f32 v4, v4, v10, v11
	v_max_f32_e32 v10, v84, v84
	v_max_f32_e32 v11, v100, v100
	v_max_f32_e32 v10, v10, v11
	v_max_f32_e32 v11, v85, v85
	v_max_f32_e32 v12, v101, v101
	v_max_f32_e32 v11, v11, v12
	v_max3_f32 v4, v4, v10, v11
	v_max_f32_e32 v10, v86, v86
	v_max_f32_e32 v11, v102, v102
	v_max_f32_e32 v10, v10, v11
	v_max_f32_e32 v11, v87, v87
	v_max_f32_e32 v12, v103, v103
	v_max_f32_e32 v11, v11, v12
	v_max3_f32 v4, v4, v10, v11
	v_max_f32_e32 v10, v88, v88
	v_max_f32_e32 v11, v104, v104
	v_max_f32_e32 v10, v10, v11
	v_max_f32_e32 v11, v89, v89
	v_max_f32_e32 v12, v105, v105
	v_max_f32_e32 v11, v11, v12
	v_max3_f32 v4, v4, v10, v11
	v_max_f32_e32 v10, v90, v90
	v_max_f32_e32 v11, v106, v106
	v_max_f32_e32 v10, v10, v11
	v_max_f32_e32 v11, v91, v91
	v_max_f32_e32 v12, v107, v107
	v_max_f32_e32 v11, v11, v12
	v_max3_f32 v4, v4, v10, v11
	v_max_f32_e32 v10, v92, v92
	v_max_f32_e32 v11, v108, v108
	v_max_f32_e32 v10, v10, v11
	v_max_f32_e32 v11, v93, v93
	v_max_f32_e32 v12, v109, v109
	v_max_f32_e32 v11, v11, v12
	v_max3_f32 v4, v4, v10, v11
	v_max_f32_e32 v10, v94, v94
	v_max_f32_e32 v11, v110, v110
	v_max_f32_e32 v10, v10, v11
	v_max_f32_e32 v11, v95, v95
	v_max_f32_e32 v12, v111, v111
	v_max_f32_e32 v11, v11, v12
	v_max3_f32 v4, v4, v10, v11
	ds_bpermute_b32 v10, v174, v4
	s_waitcnt lgkmcnt(0)
	v_max_f32_e32 v10, v10, v10
	v_max_f32_e32 v4, v4, v10
	v_cmp_lt_f32_e32 vcc, s38, v4
	s_cbranch_scc0 .LBB0_695
	s_cmp_lg_u64 vcc, 0
	s_cselect_b64 s[20:21], -1, 0
	s_cbranch_execz .LBB0_696
	s_branch .LBB0_697

.LBB0_693:
	v_add_u32_e32 v4, 64, v0
	v_cvt_f32_i32_e32 v4, v4
	s_cmp_eq_u32 s5, s52
	s_cselect_b64 s[44:45], -1, 0
	v_cndmask_b32_e64 v7, v169, 0, s[44:45]
	v_fma_f32 v4, -v154, v4, -v7
	v_add_u32_e32 v7, s62, v166
	ds_read_b128 v[8:11], v7
	s_mov_b32 s20, 2.0
	s_mov_b32 s22, 0x41200000
	s_mov_b32 s24, 0x41800000
	s_mov_b32 s28, 0x41900000
	s_mov_b32 s21, 0x40400000
	s_mov_b32 s23, 0x41300000
	s_mov_b32 s25, 0x41880000
	s_mov_b32 s29, 0x41980000
	v_fma_f32 v80, 0, v154, v4
	v_add_f32_e32 v81, v154, v4
	v_fma_f32 v82, v154, s20, v4
	v_fma_f32 v83, v155, s21, v4
	v_fma_f32 v84, v154, s38, v4
	v_fma_f32 v85, v155, s39, v4
	v_fma_f32 v86, v154, s22, v4
	v_fma_f32 v87, v155, s23, v4
	v_fma_f32 v88, v154, s24, v4
	v_fma_f32 v89, v155, s25, v4
	v_fma_f32 v90, v154, s28, v4
	v_fma_f32 v91, v155, s29, v4
	v_fma_f32 v92, v154, s26, v4
	v_fma_f32 v93, v155, s27, v4
	v_fma_f32 v94, v154, s36, v4
	v_fma_f32 v95, v155, s37, v4
	v_add_f32_e32 v4, v153, v4
	v_fma_f32 v96, 0, v154, v4
	s_waitcnt vmcnt(6) lgkmcnt(0)
	v_mfma_f32_32x32x16_bf16 v[80:95], v[8:11], v[112:115], v[80:95]
	ds_read_b128 v[8:11], v7 offset:32
	v_add_f32_e32 v97, v154, v4
	v_fma_f32 v98, v154, s20, v4
	v_fma_f32 v99, v155, s21, v4
	v_fma_f32 v100, v154, s38, v4
	v_fma_f32 v101, v155, s39, v4
	v_fma_f32 v102, v154, s22, v4
	v_fma_f32 v103, v155, s23, v4
	v_fma_f32 v104, v154, s24, v4
	v_fma_f32 v105, v155, s25, v4
	v_fma_f32 v106, v154, s28, v4
	v_fma_f32 v107, v155, s29, v4
	s_waitcnt vmcnt(5) lgkmcnt(0)
	v_mfma_f32_32x32x16_bf16 v[80:95], v[8:11], v[116:119], v[80:95]
	ds_read_b128 v[8:11], v7 offset:64
	v_fma_f32 v108, v154, s26, v4
	v_fma_f32 v109, v155, s27, v4
	v_fma_f32 v110, v154, s36, v4
	v_fma_f32 v111, v155, s37, v4
	s_cmp_lg_u32 s5, s52
	s_waitcnt vmcnt(4) lgkmcnt(0)
	v_mfma_f32_32x32x16_bf16 v[80:95], v[8:11], v[120:123], v[80:95]
	ds_read_b128 v[8:11], v7 offset:96
	ds_read_b128 v[12:15], v7 offset:4608
	s_waitcnt vmcnt(3) lgkmcnt(1)
	v_mfma_f32_32x32x16_bf16 v[80:95], v[8:11], v[124:127], v[80:95]
	ds_read_b128 v[8:11], v7 offset:4640
	s_waitcnt lgkmcnt(1)
	v_mfma_f32_32x32x16_bf16 v[96:111], v[12:15], v[112:115], v[96:111]
	s_nop 8
	v_max_f32_e32 v4, v81, v81
	s_waitcnt lgkmcnt(0)
	v_mfma_f32_32x32x16_bf16 v[96:111], v[8:11], v[116:119], v[96:111]
	ds_read_b128 v[8:11], v7 offset:4672
	s_waitcnt lgkmcnt(0)
	v_mfma_f32_32x32x16_bf16 v[96:111], v[8:11], v[120:123], v[96:111]
	ds_read_b128 v[8:11], v7 offset:4704
	s_waitcnt lgkmcnt(0)
	v_mfma_f32_32x32x16_bf16 v[96:111], v[8:11], v[124:127], v[96:111]
	s_nop 11
	v_max_f32_e32 v7, v97, v97
	v_max_f32_e32 v4, v4, v7
	v_max_f32_e32 v7, v82, v82
	v_max_f32_e32 v8, v98, v98
	v_max_f32_e32 v7, v7, v8
	v_max_f32_e32 v8, v83, v83
	v_max_f32_e32 v9, v99, v99
	v_max3_f32 v4, v80, v96, v4
	v_max_f32_e32 v8, v8, v9
	v_max3_f32 v4, v4, v7, v8
	v_max_f32_e32 v7, v84, v84
	v_max_f32_e32 v8, v100, v100
	v_max_f32_e32 v7, v7, v8
	v_max_f32_e32 v8, v85, v85
	v_max_f32_e32 v9, v101, v101
	v_max_f32_e32 v8, v8, v9
	v_max3_f32 v4, v4, v7, v8
	v_max_f32_e32 v7, v86, v86
	v_max_f32_e32 v8, v102, v102
	v_max_f32_e32 v7, v7, v8
	v_max_f32_e32 v8, v87, v87
	v_max_f32_e32 v9, v103, v103
	v_max_f32_e32 v8, v8, v9
	v_max3_f32 v4, v4, v7, v8
	v_max_f32_e32 v7, v88, v88
	v_max_f32_e32 v8, v104, v104
	v_max_f32_e32 v7, v7, v8
	v_max_f32_e32 v8, v89, v89
	v_max_f32_e32 v9, v105, v105
	v_max_f32_e32 v8, v8, v9
	v_max3_f32 v4, v4, v7, v8
	v_max_f32_e32 v7, v90, v90
	v_max_f32_e32 v8, v106, v106
	v_max_f32_e32 v7, v7, v8
	v_max_f32_e32 v8, v91, v91
	v_max_f32_e32 v9, v107, v107
	v_max_f32_e32 v8, v8, v9
	v_max3_f32 v4, v4, v7, v8
	v_max_f32_e32 v7, v92, v92
	v_max_f32_e32 v8, v108, v108
	v_max_f32_e32 v7, v7, v8
	v_max_f32_e32 v8, v93, v93
	v_max_f32_e32 v9, v109, v109
	v_max_f32_e32 v8, v8, v9
	v_max3_f32 v4, v4, v7, v8
	v_max_f32_e32 v7, v94, v94
	v_max_f32_e32 v8, v110, v110
	v_max_f32_e32 v7, v7, v8
	v_max_f32_e32 v8, v95, v95
	v_max_f32_e32 v9, v111, v111
	v_max_f32_e32 v8, v8, v9
	v_max3_f32 v4, v4, v7, v8
	ds_bpermute_b32 v7, v174, v4
	s_waitcnt lgkmcnt(0)
	v_max_f32_e32 v7, v7, v7
	v_max_f32_e32 v4, v4, v7
	v_cmp_lt_f32_e32 vcc, s38, v4
	s_cbranch_scc0 .LBB0_700
	s_cmp_lg_u64 vcc, 0
	s_cselect_b64 s[20:21], -1, 0
	s_cbranch_execz .LBB0_701
	s_branch .LBB0_702

.LBB0_697:
	s_andn2_b64 vcc, exec, s[20:21]
	s_cbranch_vccnz .LBB0_699
	v_cmp_lt_f32_e32 vcc, s38, v4
	s_or_b64 vcc, s[44:45], vcc
	s_nop 0
	v_cndmask_b32_e32 v10, 0, v4, vcc
	v_add_f32_e32 v11, v169, v10
	v_cndmask_b32_e64 v169, v11, v4, s[44:45]
	v_exp_f32_e64 v4, -v10
	v_sub_f32_e32 v80, v80, v10
	v_sub_f32_e32 v81, v81, v10
	v_sub_f32_e32 v96, v96, v10
	v_sub_f32_e32 v97, v97, v10
	v_sub_f32_e32 v82, v82, v10
	v_sub_f32_e32 v83, v83, v10
	v_sub_f32_e32 v98, v98, v10
	v_sub_f32_e32 v99, v99, v10
	v_sub_f32_e32 v84, v84, v10
	v_sub_f32_e32 v85, v85, v10
	v_sub_f32_e32 v100, v100, v10
	v_sub_f32_e32 v101, v101, v10
	v_sub_f32_e32 v86, v86, v10
	v_sub_f32_e32 v87, v87, v10
	v_sub_f32_e32 v102, v102, v10
	v_sub_f32_e32 v103, v103, v10
	v_sub_f32_e32 v88, v88, v10
	v_sub_f32_e32 v89, v89, v10
	v_sub_f32_e32 v104, v104, v10
	v_sub_f32_e32 v105, v105, v10
	v_sub_f32_e32 v90, v90, v10
	v_sub_f32_e32 v91, v91, v10
	v_sub_f32_e32 v106, v106, v10
	v_sub_f32_e32 v107, v107, v10
	v_sub_f32_e32 v92, v92, v10
	v_sub_f32_e32 v93, v93, v10
	v_sub_f32_e32 v108, v108, v10
	v_sub_f32_e32 v109, v109, v10
	v_sub_f32_e32 v94, v94, v10
	v_sub_f32_e32 v95, v95, v10
	v_sub_f32_e32 v110, v110, v10
	v_sub_f32_e32 v111, v111, v10
	v_pk_mul_f32 v[78:79], v[4:5], v[78:79] op_sel_hi:[0,1]
	v_pk_mul_f32 v[76:77], v[4:5], v[76:77] op_sel_hi:[0,1]
	v_pk_mul_f32 v[74:75], v[4:5], v[74:75] op_sel_hi:[0,1]
	v_pk_mul_f32 v[72:73], v[4:5], v[72:73] op_sel_hi:[0,1]
	v_pk_mul_f32 v[70:71], v[4:5], v[70:71] op_sel_hi:[0,1]
	v_pk_mul_f32 v[68:69], v[4:5], v[68:69] op_sel_hi:[0,1]
	v_pk_mul_f32 v[66:67], v[4:5], v[66:67] op_sel_hi:[0,1]
	v_pk_mul_f32 v[64:65], v[4:5], v[64:65] op_sel_hi:[0,1]
	v_pk_mul_f32 v[62:63], v[4:5], v[62:63] op_sel_hi:[0,1]
	v_pk_mul_f32 v[60:61], v[4:5], v[60:61] op_sel_hi:[0,1]
	v_pk_mul_f32 v[58:59], v[4:5], v[58:59] op_sel_hi:[0,1]
	v_pk_mul_f32 v[56:57], v[4:5], v[56:57] op_sel_hi:[0,1]
	v_pk_mul_f32 v[54:55], v[4:5], v[54:55] op_sel_hi:[0,1]
	v_pk_mul_f32 v[52:53], v[4:5], v[52:53] op_sel_hi:[0,1]
	v_pk_mul_f32 v[50:51], v[4:5], v[50:51] op_sel_hi:[0,1]
	v_pk_mul_f32 v[48:49], v[4:5], v[48:49] op_sel_hi:[0,1]
	v_pk_mul_f32 v[46:47], v[4:5], v[46:47] op_sel_hi:[0,1]
	v_pk_mul_f32 v[44:45], v[4:5], v[44:45] op_sel_hi:[0,1]
	v_pk_mul_f32 v[42:43], v[4:5], v[42:43] op_sel_hi:[0,1]
	v_pk_mul_f32 v[40:41], v[4:5], v[40:41] op_sel_hi:[0,1]
	v_pk_mul_f32 v[38:39], v[4:5], v[38:39] op_sel_hi:[0,1]
	v_pk_mul_f32 v[36:37], v[4:5], v[36:37] op_sel_hi:[0,1]
	v_pk_mul_f32 v[34:35], v[4:5], v[34:35] op_sel_hi:[0,1]
	v_pk_mul_f32 v[32:33], v[4:5], v[32:33] op_sel_hi:[0,1]
	v_pk_mul_f32 v[30:31], v[4:5], v[30:31] op_sel_hi:[0,1]
	v_pk_mul_f32 v[28:29], v[4:5], v[28:29] op_sel_hi:[0,1]
	v_pk_mul_f32 v[26:27], v[4:5], v[26:27] op_sel_hi:[0,1]
	v_pk_mul_f32 v[24:25], v[4:5], v[24:25] op_sel_hi:[0,1]
	v_pk_mul_f32 v[22:23], v[4:5], v[22:23] op_sel_hi:[0,1]
	v_pk_mul_f32 v[20:21], v[4:5], v[20:21] op_sel_hi:[0,1]
	v_pk_mul_f32 v[18:19], v[4:5], v[18:19] op_sel_hi:[0,1]
	v_pk_mul_f32 v[16:17], v[4:5], v[16:17] op_sel_hi:[0,1]
	v_mul_f32_e32 v168, v168, v4
.LBB0_699:
	v_exp_f32_e32 v170, v80
	v_exp_f32_e32 v171, v96
	v_exp_f32_e32 v10, v81
	v_exp_f32_e32 v4, v97
	v_exp_f32_e32 v172, v98
	v_add_f32_e32 v11, v170, v171
	v_add_f32_e32 v12, v10, v4
	v_add_f32_e32 v13, v11, v5
	s_nop 0
	v_add_f32_e32 v15, v12, v13
	v_exp_f32_e32 v11, v82
	v_exp_f32_e32 v12, v83
	v_exp_f32_e32 v14, v99
	v_cvt_pk_bf16_f32 v10, v170, v10
	v_add_f32_e32 v13, v11, v172
	v_cvt_pk_bf16_f32 v11, v11, v12
	v_add_f32_e32 v80, v12, v14
	v_add_f32_e32 v81, v13, v15
	v_exp_f32_e32 v13, v84
	v_add_f32_e32 v97, v80, v81
	v_exp_f32_e32 v15, v100
	v_exp_f32_e32 v80, v85
	v_exp_f32_e32 v96, v101
	v_cvt_pk_bf16_f32 v12, v13, v80
	v_add_f32_e32 v81, v13, v15
	v_add_f32_e32 v82, v80, v96
	v_add_f32_e32 v83, v81, v97
	s_nop 0
	v_add_f32_e32 v99, v82, v83
	v_exp_f32_e32 v81, v86
	v_exp_f32_e32 v97, v102
	v_exp_f32_e32 v82, v87
	v_exp_f32_e32 v98, v103
	v_cvt_pk_bf16_f32 v13, v81, v82
	v_add_f32_e32 v83, v81, v97
	v_add_f32_e32 v84, v82, v98
	v_add_f32_e32 v85, v83, v99
	s_nop 0
	v_add_f32_e32 v101, v84, v85
	v_exp_f32_e32 v83, v88
	v_exp_f32_e32 v99, v104
	v_exp_f32_e32 v84, v89
	v_exp_f32_e32 v100, v105
	v_exp_f32_e32 v104, v95
	v_add_f32_e32 v85, v83, v99
	v_cvt_pk_bf16_f32 v80, v83, v84
	v_add_f32_e32 v86, v84, v100
	v_add_f32_e32 v87, v85, v101
	v_exp_f32_e32 v85, v90
	v_add_f32_e32 v103, v86, v87
	v_exp_f32_e32 v101, v106
	v_exp_f32_e32 v86, v91
	v_exp_f32_e32 v102, v107
	v_cvt_pk_bf16_f32 v81, v85, v86
	v_add_f32_e32 v87, v85, v101
	v_add_f32_e32 v88, v86, v102
	v_add_f32_e32 v89, v87, v103
	s_nop 0
	v_add_f32_e32 v91, v88, v89
	v_exp_f32_e32 v87, v92
	v_exp_f32_e32 v103, v108
	v_exp_f32_e32 v88, v93
	v_exp_f32_e32 v90, v109
	v_cvt_pk_bf16_f32 v82, v87, v88
	v_add_f32_e32 v89, v87, v103
	v_add_f32_e32 v92, v88, v90
	v_add_f32_e32 v93, v89, v91
	s_nop 0
	v_add_f32_e32 v93, v92, v93
	v_exp_f32_e32 v89, v94
	v_exp_f32_e32 v91, v110
	v_exp_f32_e32 v92, v111
	v_cvt_pk_bf16_f32 v83, v89, v104
	v_cvt_pk_bf16_f32 v84, v171, v4
	v_add_f32_e32 v105, v89, v91
	v_add_f32_e32 v94, v104, v92
	v_add_f32_e32 v95, v105, v93
	v_add_u32_e32 v4, s61, v167
	v_add_f32_e32 v180, v94, v95
	v_cvt_pk_bf16_f32 v85, v172, v14
	v_cvt_pk_bf16_f32 v86, v15, v96
	v_cvt_pk_bf16_f32 v87, v97, v98
	v_cvt_pk_bf16_f32 v88, v99, v100
	v_cvt_pk_bf16_f32 v89, v101, v102
	v_cvt_pk_bf16_f32 v90, v103, v90
	v_cvt_pk_bf16_f32 v91, v91, v92
	ds_read_b64_tr_b16 v[92:93], v4 offset:18432
	ds_read_b64_tr_b16 v[94:95], v4 offset:20992
	ds_read_b64_tr_b16 v[96:97], v4 offset:18496
	ds_read_b64_tr_b16 v[98:99], v4 offset:21056
	ds_read_b64_tr_b16 v[100:101], v4 offset:18560
	ds_read_b64_tr_b16 v[102:103], v4 offset:21120
	ds_read_b64_tr_b16 v[104:105], v4 offset:18624
	ds_read_b64_tr_b16 v[106:107], v4 offset:21184
	ds_read_b64_tr_b16 v[108:109], v4 offset:23552
	ds_read_b64_tr_b16 v[110:111], v4 offset:26112
	ds_read_b64_tr_b16 v[170:171], v4 offset:23616
	ds_read_b64_tr_b16 v[172:173], v4 offset:26176
	ds_read_b64_tr_b16 v[176:177], v4 offset:23680
	ds_read_b64_tr_b16 v[178:179], v4 offset:26240
	ds_read_b64_tr_b16 v[204:205], v4 offset:23744
	ds_read_b64_tr_b16 v[206:207], v4 offset:26304
	s_setprio 1
	s_waitcnt lgkmcnt(14)
	v_mfma_f32_32x32x16_bf16 v[64:79], v[92:95], v[10:13], v[64:79]
	s_waitcnt lgkmcnt(12)
	v_mfma_f32_32x32x16_bf16 v[48:63], v[96:99], v[10:13], v[48:63]
	s_waitcnt lgkmcnt(10)
	v_mfma_f32_32x32x16_bf16 v[32:47], v[100:103], v[10:13], v[32:47]
	s_waitcnt lgkmcnt(8)
	v_mfma_f32_32x32x16_bf16 v[16:31], v[104:107], v[10:13], v[16:31]
	s_setprio 0
	ds_read_b64_tr_b16 v[10:11], v4 offset:28672
	ds_read_b64_tr_b16 v[92:93], v4 offset:28736
	ds_read_b64_tr_b16 v[96:97], v4 offset:28800
	ds_read_b64_tr_b16 v[100:101], v4 offset:28864
	ds_read_b64_tr_b16 v[12:13], v4 offset:31232
	ds_read_b64_tr_b16 v[94:95], v4 offset:31296
	ds_read_b64_tr_b16 v[98:99], v4 offset:31360
	ds_read_b64_tr_b16 v[102:103], v4 offset:31424
	s_setprio 1
	s_waitcnt lgkmcnt(14)
	v_mfma_f32_32x32x16_bf16 v[64:79], v[108:111], v[80:83], v[64:79]
	s_waitcnt lgkmcnt(12)
	v_mfma_f32_32x32x16_bf16 v[48:63], v[170:173], v[80:83], v[48:63]
	s_waitcnt lgkmcnt(10)
	v_mfma_f32_32x32x16_bf16 v[32:47], v[176:179], v[80:83], v[32:47]
	s_waitcnt lgkmcnt(8)
	v_mfma_f32_32x32x16_bf16 v[16:31], v[204:207], v[80:83], v[16:31]
	s_setprio 0
	ds_read_b64_tr_b16 v[80:81], v4 offset:33792
	ds_read_b64_tr_b16 v[104:105], v4 offset:33856
	ds_read_b64_tr_b16 v[108:109], v4 offset:33920
	ds_read_b64_tr_b16 v[170:171], v4 offset:33984
	ds_read_b64_tr_b16 v[82:83], v4 offset:36352
	ds_read_b64_tr_b16 v[106:107], v4 offset:36416
	ds_read_b64_tr_b16 v[110:111], v4 offset:36480
	ds_read_b64_tr_b16 v[172:173], v4 offset:36544
	s_setprio 1
	s_waitcnt lgkmcnt(11)
	v_mfma_f32_32x32x16_bf16 v[64:79], v[10:13], v[84:87], v[64:79]
	s_waitcnt lgkmcnt(10)
	v_mfma_f32_32x32x16_bf16 v[48:63], v[92:95], v[84:87], v[48:63]
	s_waitcnt lgkmcnt(9)
	v_mfma_f32_32x32x16_bf16 v[32:47], v[96:99], v[84:87], v[32:47]
	s_waitcnt lgkmcnt(8)
	v_mfma_f32_32x32x16_bf16 v[16:31], v[100:103], v[84:87], v[16:31]
	s_setprio 0
	s_setprio 1
	s_waitcnt lgkmcnt(3)
	v_mfma_f32_32x32x16_bf16 v[64:79], v[80:83], v[88:91], v[64:79]
	s_waitcnt lgkmcnt(2)
	v_mfma_f32_32x32x16_bf16 v[48:63], v[104:107], v[88:91], v[48:63]
	s_waitcnt lgkmcnt(1)
	v_mfma_f32_32x32x16_bf16 v[32:47], v[108:111], v[88:91], v[32:47]
	s_waitcnt lgkmcnt(0)
	v_mfma_f32_32x32x16_bf16 v[16:31], v[170:173], v[88:91], v[16:31]
	s_setprio 0
	v_add_f32_e32 v168, v168, v180
	s_cmp_eq_u32 s52, 0
	s_cbranch_scc0 .LBB0_685
	s_branch .LBB0_686

.LBB0_702:
	s_andn2_b64 vcc, exec, s[20:21]
	s_cbranch_vccnz .LBB0_704
	v_cmp_lt_f32_e32 vcc, s38, v4
	s_or_b64 vcc, s[44:45], vcc
	s_nop 0
	v_cndmask_b32_e32 v8, 0, v4, vcc
	v_add_f32_e32 v7, v169, v8
	v_cndmask_b32_e64 v169, v7, v4, s[44:45]
	v_exp_f32_e64 v4, -v8
	v_sub_f32_e32 v80, v80, v8
	v_sub_f32_e32 v81, v81, v8
	v_sub_f32_e32 v96, v96, v8
	v_sub_f32_e32 v97, v97, v8
	v_sub_f32_e32 v82, v82, v8
	v_sub_f32_e32 v83, v83, v8
	v_sub_f32_e32 v98, v98, v8
	v_sub_f32_e32 v99, v99, v8
	v_sub_f32_e32 v84, v84, v8
	v_sub_f32_e32 v85, v85, v8
	v_sub_f32_e32 v100, v100, v8
	v_sub_f32_e32 v101, v101, v8
	v_sub_f32_e32 v86, v86, v8
	v_sub_f32_e32 v87, v87, v8
	v_sub_f32_e32 v102, v102, v8
	v_sub_f32_e32 v103, v103, v8
	v_sub_f32_e32 v88, v88, v8
	v_sub_f32_e32 v89, v89, v8
	v_sub_f32_e32 v104, v104, v8
	v_sub_f32_e32 v105, v105, v8
	v_sub_f32_e32 v90, v90, v8
	v_sub_f32_e32 v91, v91, v8
	v_sub_f32_e32 v106, v106, v8
	v_sub_f32_e32 v107, v107, v8
	v_sub_f32_e32 v92, v92, v8
	v_sub_f32_e32 v93, v93, v8
	v_sub_f32_e32 v108, v108, v8
	v_sub_f32_e32 v109, v109, v8
	v_sub_f32_e32 v94, v94, v8
	v_sub_f32_e32 v95, v95, v8
	v_sub_f32_e32 v110, v110, v8
	v_sub_f32_e32 v111, v111, v8
	v_pk_mul_f32 v[78:79], v[4:5], v[78:79] op_sel_hi:[0,1]
	v_pk_mul_f32 v[76:77], v[4:5], v[76:77] op_sel_hi:[0,1]
	v_pk_mul_f32 v[74:75], v[4:5], v[74:75] op_sel_hi:[0,1]
	v_pk_mul_f32 v[72:73], v[4:5], v[72:73] op_sel_hi:[0,1]
	v_pk_mul_f32 v[70:71], v[4:5], v[70:71] op_sel_hi:[0,1]
	v_pk_mul_f32 v[68:69], v[4:5], v[68:69] op_sel_hi:[0,1]
	v_pk_mul_f32 v[66:67], v[4:5], v[66:67] op_sel_hi:[0,1]
	v_pk_mul_f32 v[64:65], v[4:5], v[64:65] op_sel_hi:[0,1]
	v_pk_mul_f32 v[62:63], v[4:5], v[62:63] op_sel_hi:[0,1]
	v_pk_mul_f32 v[60:61], v[4:5], v[60:61] op_sel_hi:[0,1]
	v_pk_mul_f32 v[58:59], v[4:5], v[58:59] op_sel_hi:[0,1]
	v_pk_mul_f32 v[56:57], v[4:5], v[56:57] op_sel_hi:[0,1]
	v_pk_mul_f32 v[54:55], v[4:5], v[54:55] op_sel_hi:[0,1]
	v_pk_mul_f32 v[52:53], v[4:5], v[52:53] op_sel_hi:[0,1]
	v_pk_mul_f32 v[50:51], v[4:5], v[50:51] op_sel_hi:[0,1]
	v_pk_mul_f32 v[48:49], v[4:5], v[48:49] op_sel_hi:[0,1]
	v_pk_mul_f32 v[46:47], v[4:5], v[46:47] op_sel_hi:[0,1]
	v_pk_mul_f32 v[44:45], v[4:5], v[44:45] op_sel_hi:[0,1]
	v_pk_mul_f32 v[42:43], v[4:5], v[42:43] op_sel_hi:[0,1]
	v_pk_mul_f32 v[40:41], v[4:5], v[40:41] op_sel_hi:[0,1]
	v_pk_mul_f32 v[38:39], v[4:5], v[38:39] op_sel_hi:[0,1]
	v_pk_mul_f32 v[36:37], v[4:5], v[36:37] op_sel_hi:[0,1]
	v_pk_mul_f32 v[34:35], v[4:5], v[34:35] op_sel_hi:[0,1]
	v_pk_mul_f32 v[32:33], v[4:5], v[32:33] op_sel_hi:[0,1]
	v_pk_mul_f32 v[30:31], v[4:5], v[30:31] op_sel_hi:[0,1]
	v_pk_mul_f32 v[28:29], v[4:5], v[28:29] op_sel_hi:[0,1]
	v_pk_mul_f32 v[26:27], v[4:5], v[26:27] op_sel_hi:[0,1]
	v_pk_mul_f32 v[24:25], v[4:5], v[24:25] op_sel_hi:[0,1]
	v_pk_mul_f32 v[22:23], v[4:5], v[22:23] op_sel_hi:[0,1]
	v_pk_mul_f32 v[20:21], v[4:5], v[20:21] op_sel_hi:[0,1]
	v_pk_mul_f32 v[18:19], v[4:5], v[18:19] op_sel_hi:[0,1]
	v_pk_mul_f32 v[16:17], v[4:5], v[16:17] op_sel_hi:[0,1]
	v_mul_f32_e32 v168, v168, v4
.LBB0_704:
	v_exp_f32_e32 v7, v80
	v_exp_f32_e32 v170, v96
	v_exp_f32_e32 v8, v81
	v_exp_f32_e32 v4, v97
	v_exp_f32_e32 v171, v98
	v_add_f32_e32 v9, v7, v170
	v_exp_f32_e32 v98, v91
	v_add_f32_e32 v10, v8, v4
	v_add_f32_e32 v11, v9, v5
	v_exp_f32_e32 v9, v82
	v_add_f32_e32 v97, v10, v11
	v_exp_f32_e32 v10, v83
	v_exp_f32_e32 v96, v99
	v_add_f32_e32 v11, v9, v171
	v_cvt_pk_bf16_f32 v8, v7, v8
	v_cvt_pk_bf16_f32 v9, v9, v10
	v_add_f32_e32 v12, v10, v96
	v_add_f32_e32 v13, v11, v97
	v_exp_f32_e32 v11, v84
	v_add_f32_e32 v83, v12, v13
	v_exp_f32_e32 v97, v100
	v_exp_f32_e32 v12, v85
	v_exp_f32_e32 v82, v101
	v_exp_f32_e32 v100, v93
	v_add_f32_e32 v13, v11, v97
	v_cvt_pk_bf16_f32 v10, v11, v12
	v_add_f32_e32 v14, v12, v82
	v_add_f32_e32 v15, v13, v83
	v_exp_f32_e32 v13, v86
	v_add_f32_e32 v85, v14, v15
	v_exp_f32_e32 v83, v102
	v_exp_f32_e32 v14, v87
	v_exp_f32_e32 v84, v103
	v_exp_f32_e32 v102, v95
	v_add_f32_e32 v15, v13, v83
	v_cvt_pk_bf16_f32 v11, v13, v14
	v_add_f32_e32 v80, v14, v84
	v_add_f32_e32 v81, v15, v85
	v_exp_f32_e32 v15, v88
	v_add_f32_e32 v87, v80, v81
	v_exp_f32_e32 v85, v104
	v_exp_f32_e32 v80, v89
	v_exp_f32_e32 v86, v105
	v_cvt_pk_bf16_f32 v12, v15, v80
	v_add_f32_e32 v81, v15, v85
	v_add_f32_e32 v88, v80, v86
	v_add_f32_e32 v89, v81, v87
	s_nop 0
	v_add_f32_e32 v89, v88, v89
	v_exp_f32_e32 v81, v90
	v_exp_f32_e32 v87, v106
	v_exp_f32_e32 v88, v107
	v_cvt_pk_bf16_f32 v13, v81, v98
	v_add_f32_e32 v99, v81, v87
	v_add_f32_e32 v90, v98, v88
	v_add_f32_e32 v91, v99, v89
	v_exp_f32_e32 v89, v92
	v_add_f32_e32 v91, v90, v91
	v_exp_f32_e32 v99, v108
	v_exp_f32_e32 v90, v109
	v_cvt_pk_bf16_f32 v14, v89, v100
	v_add_f32_e32 v101, v89, v99
	v_add_f32_e32 v92, v100, v90
	v_add_f32_e32 v93, v101, v91
	v_exp_f32_e32 v91, v94
	v_add_f32_e32 v93, v92, v93
	v_exp_f32_e32 v101, v110
	v_exp_f32_e32 v92, v111
	v_cvt_pk_bf16_f32 v15, v91, v102
	v_cvt_pk_bf16_f32 v80, v170, v4
	v_add_f32_e32 v103, v91, v101
	v_add_f32_e32 v94, v102, v92
	v_add_f32_e32 v95, v103, v93
	v_add_u32_e32 v4, s63, v167
	v_add_f32_e32 v180, v94, v95
	v_cvt_pk_bf16_f32 v81, v171, v96
	v_cvt_pk_bf16_f32 v82, v97, v82
	v_cvt_pk_bf16_f32 v83, v83, v84
	v_cvt_pk_bf16_f32 v84, v85, v86
	v_cvt_pk_bf16_f32 v85, v87, v88
	v_cvt_pk_bf16_f32 v86, v99, v90
	v_cvt_pk_bf16_f32 v87, v101, v92
	ds_read_b64_tr_b16 v[88:89], v4 offset:18432
	ds_read_b64_tr_b16 v[90:91], v4 offset:20992
	ds_read_b64_tr_b16 v[92:93], v4 offset:18496
	ds_read_b64_tr_b16 v[94:95], v4 offset:21056
	ds_read_b64_tr_b16 v[96:97], v4 offset:18560
	ds_read_b64_tr_b16 v[98:99], v4 offset:21120
	ds_read_b64_tr_b16 v[100:101], v4 offset:18624
	ds_read_b64_tr_b16 v[102:103], v4 offset:21184
	ds_read_b64_tr_b16 v[104:105], v4 offset:23552
	ds_read_b64_tr_b16 v[106:107], v4 offset:26112
	ds_read_b64_tr_b16 v[108:109], v4 offset:23616
	ds_read_b64_tr_b16 v[110:111], v4 offset:26176
	ds_read_b64_tr_b16 v[170:171], v4 offset:23680
	ds_read_b64_tr_b16 v[172:173], v4 offset:26240
	ds_read_b64_tr_b16 v[176:177], v4 offset:23744
	ds_read_b64_tr_b16 v[178:179], v4 offset:26304
	s_setprio 1
	s_waitcnt lgkmcnt(14)
	v_mfma_f32_32x32x16_bf16 v[64:79], v[88:91], v[8:11], v[64:79]
	s_waitcnt lgkmcnt(12)
	v_mfma_f32_32x32x16_bf16 v[48:63], v[92:95], v[8:11], v[48:63]
	s_waitcnt lgkmcnt(10)
	v_mfma_f32_32x32x16_bf16 v[32:47], v[96:99], v[8:11], v[32:47]
	s_waitcnt lgkmcnt(8)
	v_mfma_f32_32x32x16_bf16 v[16:31], v[100:103], v[8:11], v[16:31]
	s_setprio 0
	ds_read_b64_tr_b16 v[8:9], v4 offset:28672
	ds_read_b64_tr_b16 v[88:89], v4 offset:28736
	ds_read_b64_tr_b16 v[92:93], v4 offset:28800
	ds_read_b64_tr_b16 v[96:97], v4 offset:28864
	ds_read_b64_tr_b16 v[10:11], v4 offset:31232
	ds_read_b64_tr_b16 v[90:91], v4 offset:31296
	ds_read_b64_tr_b16 v[94:95], v4 offset:31360
	ds_read_b64_tr_b16 v[98:99], v4 offset:31424
	s_setprio 1
	s_waitcnt lgkmcnt(14)
	v_mfma_f32_32x32x16_bf16 v[64:79], v[104:107], v[12:15], v[64:79]
	s_waitcnt lgkmcnt(12)
	v_mfma_f32_32x32x16_bf16 v[48:63], v[108:111], v[12:15], v[48:63]
	s_waitcnt lgkmcnt(10)
	v_mfma_f32_32x32x16_bf16 v[32:47], v[170:173], v[12:15], v[32:47]
	s_waitcnt lgkmcnt(8)
	v_mfma_f32_32x32x16_bf16 v[16:31], v[176:179], v[12:15], v[16:31]
	s_setprio 0
	ds_read_b64_tr_b16 v[12:13], v4 offset:33792
	ds_read_b64_tr_b16 v[100:101], v4 offset:33856
	ds_read_b64_tr_b16 v[104:105], v4 offset:33920
	ds_read_b64_tr_b16 v[108:109], v4 offset:33984
	ds_read_b64_tr_b16 v[14:15], v4 offset:36352
	ds_read_b64_tr_b16 v[102:103], v4 offset:36416
	ds_read_b64_tr_b16 v[106:107], v4 offset:36480
	ds_read_b64_tr_b16 v[110:111], v4 offset:36544
	s_setprio 1
	s_waitcnt lgkmcnt(11)
	v_mfma_f32_32x32x16_bf16 v[64:79], v[8:11], v[80:83], v[64:79]
	s_waitcnt lgkmcnt(10)
	v_mfma_f32_32x32x16_bf16 v[48:63], v[88:91], v[80:83], v[48:63]
	s_waitcnt lgkmcnt(9)
	v_mfma_f32_32x32x16_bf16 v[32:47], v[92:95], v[80:83], v[32:47]
	s_waitcnt lgkmcnt(8)
	v_mfma_f32_32x32x16_bf16 v[16:31], v[96:99], v[80:83], v[16:31]
	s_setprio 0
	s_setprio 1
	s_waitcnt lgkmcnt(3)
	v_mfma_f32_32x32x16_bf16 v[64:79], v[12:15], v[84:87], v[64:79]
	s_waitcnt lgkmcnt(2)
	v_mfma_f32_32x32x16_bf16 v[48:63], v[100:103], v[84:87], v[48:63]
	s_waitcnt lgkmcnt(1)
	v_mfma_f32_32x32x16_bf16 v[32:47], v[104:107], v[84:87], v[32:47]
	s_waitcnt lgkmcnt(0)
	v_mfma_f32_32x32x16_bf16 v[16:31], v[108:111], v[84:87], v[16:31]
	s_setprio 0
	v_add_f32_e32 v168, v168, v180
	s_andn2_b64 vcc, exec, s[18:19]
	s_cbranch_vccnz .LBB0_681

.LBB0_720:
	v_cvt_f32_i32_e32 v4, v234
	s_cmp_eq_u32 s7, -1
	s_cselect_b64 s[16:17], -1, 0
	v_cndmask_b32_e64 v3, v225, 0, s[16:17]
	v_fma_f32 v4, -v154, v4, -v3
	s_mov_b32 s18, 2.0
	v_add_f32_e32 v6, v153, v4
	s_mov_b32 s19, 0x40400000
	v_fma_f32 v98, v154, s18, v4
	v_fma_f32 v99, v155, s19, v4
	v_fma_f32 v82, v154, s18, v6
	v_fma_f32 v83, v155, s19, v6
	s_mov_b32 s18, 0x41200000
	s_mov_b32 s19, 0x41300000
	v_fma_f32 v102, v154, s18, v4
	v_fma_f32 v103, v155, s19, v4
	v_fma_f32 v86, v154, s18, v6
	v_fma_f32 v87, v155, s19, v6
	s_mov_b32 s18, 0x41800000
	s_mov_b32 s19, 0x41880000
	v_fma_f32 v104, v154, s18, v4
	v_fma_f32 v105, v155, s19, v4
	v_fma_f32 v88, v154, s18, v6
	v_fma_f32 v89, v155, s19, v6
	s_mov_b32 s18, 0x41900000
	s_mov_b32 s19, 0x41980000
	v_fma_f32 v80, 0, v154, v6
	v_add_f32_e32 v81, v154, v6
	v_fma_f32 v84, v154, s38, v6
	v_fma_f32 v85, v155, s39, v6
	v_fma_f32 v90, v154, s18, v6
	v_fma_f32 v91, v155, s19, v6
	v_fma_f32 v92, v154, s26, v6
	v_fma_f32 v93, v155, s27, v6
	v_fma_f32 v94, v154, s36, v6
	v_fma_f32 v95, v155, s37, v6
	ds_read_b128 v[6:9], v222 offset:4608
	ds_read_b128 v[10:13], v222
	ds_read_b128 v[238:241], v222 offset:32
	v_fma_f32 v96, 0, v154, v4
	v_add_f32_e32 v97, v154, v4
	v_fma_f32 v100, v154, s38, v4
	v_fma_f32 v101, v155, s39, v4
	v_fma_f32 v106, v154, s18, v4
	v_fma_f32 v107, v155, s19, v4
	v_fma_f32 v108, v154, s26, v4
	v_fma_f32 v109, v155, s27, v4
	v_fma_f32 v110, v154, s36, v4
	v_fma_f32 v111, v155, s37, v4
	s_waitcnt lgkmcnt(2)
	v_mfma_f32_32x32x16_bf16 v[80:95], v[6:9], v[112:115], v[80:95]
	ds_read_b128 v[6:9], v222 offset:4640
	v_cmp_lt_i32_e32 vcc, 0, v234
	s_mov_b64 s[18:19], s[16:17]
	s_waitcnt lgkmcnt(2)
	v_mfma_f32_32x32x16_bf16 v[96:111], v[10:13], v[112:115], v[96:111]
	s_waitcnt lgkmcnt(1)
	v_mfma_f32_32x32x16_bf16 v[96:111], v[238:241], v[116:119], v[96:111]
	s_waitcnt lgkmcnt(0)
	v_mfma_f32_32x32x16_bf16 v[80:95], v[6:9], v[116:119], v[80:95]
	ds_read_b128 v[6:9], v222 offset:64
	ds_read_b128 v[10:13], v222 offset:4672
	s_waitcnt lgkmcnt(1)
	v_mfma_f32_32x32x16_bf16 v[96:111], v[6:9], v[120:123], v[96:111]
	s_waitcnt lgkmcnt(0)
	v_mfma_f32_32x32x16_bf16 v[80:95], v[10:13], v[120:123], v[80:95]
	ds_read_b128 v[6:9], v222 offset:96
	ds_read_b128 v[10:13], v222 offset:4704
	s_waitcnt lgkmcnt(1)
	v_mfma_f32_32x32x16_bf16 v[96:111], v[6:9], v[124:127], v[96:111]
	s_waitcnt lgkmcnt(0)
	v_mfma_f32_32x32x16_bf16 v[80:95], v[10:13], v[124:127], v[80:95]
	s_nop 9
	v_cndmask_b32_e32 v4, v196, v97, vcc
	v_cmp_lt_i32_e32 vcc, -1, v234
	s_nop 1
	v_cndmask_b32_e32 v243, v196, v96, vcc
	v_cmp_lt_i32_e32 vcc, 32, v234
	s_nop 1
	v_cndmask_b32_e32 v242, v196, v81, vcc
	v_cmp_lt_i32_e32 vcc, 31, v234
	s_nop 1
	v_cndmask_b32_e32 v244, v196, v80, vcc
	v_cmp_lt_i32_e32 vcc, 2, v234
	s_nop 1
	v_cndmask_b32_e32 v238, v196, v99, vcc
	v_cmp_lt_i32_e32 vcc, 1, v234
	s_nop 1
	v_cndmask_b32_e32 v240, v196, v98, vcc
	v_cmp_lt_i32_e32 vcc, 34, v234
	s_nop 1
	v_cndmask_b32_e32 v239, v196, v83, vcc
	v_cmp_lt_i32_e32 vcc, 33, v234
	s_nop 1
	v_cndmask_b32_e32 v241, v196, v82, vcc
	v_cmp_lt_i32_e32 vcc, 8, v234
	s_nop 1
	v_cndmask_b32_e32 v97, v196, v101, vcc
	v_cmp_lt_i32_e32 vcc, 7, v234
	s_nop 1
	v_cndmask_b32_e32 v99, v196, v100, vcc
	v_cmp_lt_i32_e32 vcc, 40, v234
	s_nop 1
	v_cndmask_b32_e32 v98, v196, v85, vcc
	v_cmp_lt_i32_e32 vcc, 39, v234
	s_nop 1
	v_cndmask_b32_e32 v100, v196, v84, vcc
	v_cmp_lt_i32_e32 vcc, 10, v234
	s_nop 1
	v_cndmask_b32_e32 v84, v196, v103, vcc
	v_cmp_lt_i32_e32 vcc, 9, v234
	s_nop 1
	v_cndmask_b32_e32 v96, v196, v102, vcc
	v_cmp_lt_i32_e32 vcc, 42, v234
	s_nop 1
	v_cndmask_b32_e32 v87, v196, v87, vcc
	v_cmp_lt_i32_e32 vcc, 41, v234
	s_nop 1
	v_cndmask_b32_e32 v86, v196, v86, vcc
	v_cmp_lt_i32_e32 vcc, 16, v234
	s_nop 1
	v_cndmask_b32_e32 v80, v196, v105, vcc
	v_cmp_lt_i32_e32 vcc, 15, v234
	s_nop 1
	v_cndmask_b32_e32 v83, v196, v104, vcc
	v_cmp_lt_i32_e32 vcc, 48, v234
	s_nop 1
	v_cndmask_b32_e32 v82, v196, v89, vcc
	v_cmp_lt_i32_e32 vcc, 47, v234
	v_max_f32_e32 v89, v242, v242
	s_nop 0
	v_cndmask_b32_e32 v85, v196, v88, vcc
	v_cmp_lt_i32_e32 vcc, 18, v234
	v_max_f32_e32 v88, v4, v4
	v_max_f32_e32 v88, v88, v89
	v_cndmask_b32_e32 v12, v196, v107, vcc
	v_cmp_lt_i32_e32 vcc, 17, v234
	v_max_f32_e32 v89, v240, v240
	v_max3_f32 v88, v243, v244, v88
	v_cndmask_b32_e32 v15, v196, v106, vcc
	v_cmp_lt_i32_e32 vcc, 50, v234
	s_nop 1
	v_cndmask_b32_e32 v14, v196, v91, vcc
	v_cmp_lt_i32_e32 vcc, 49, v234
	v_max_f32_e32 v91, v239, v239
	s_nop 0
	v_cndmask_b32_e32 v81, v196, v90, vcc
	v_max_f32_e32 v90, v241, v241
	v_max_f32_e32 v89, v89, v90
	v_max_f32_e32 v90, v238, v238
	v_max_f32_e32 v90, v90, v91
	v_max3_f32 v88, v88, v89, v90
	v_max_f32_e32 v89, v99, v99
	v_max_f32_e32 v90, v100, v100
	v_max_f32_e32 v89, v89, v90
	v_max_f32_e32 v90, v97, v97
	v_max_f32_e32 v91, v98, v98
	v_max_f32_e32 v90, v90, v91
	v_max3_f32 v88, v88, v89, v90
	v_max_f32_e32 v89, v96, v96
	v_max_f32_e32 v90, v86, v86
	v_max_f32_e32 v89, v89, v90
	v_max_f32_e32 v90, v84, v84
	v_max_f32_e32 v91, v87, v87
	v_max_f32_e32 v90, v90, v91
	v_cmp_lt_i32_e32 vcc, 24, v234
	v_max3_f32 v88, v88, v89, v90
	v_max_f32_e32 v89, v83, v83
	v_max_f32_e32 v90, v85, v85
	v_cndmask_b32_e32 v8, v196, v109, vcc
	v_cmp_lt_i32_e32 vcc, 23, v234
	v_max_f32_e32 v89, v89, v90
	v_max_f32_e32 v90, v80, v80
	v_max_f32_e32 v91, v82, v82
	v_cndmask_b32_e32 v11, v196, v108, vcc
	v_cmp_lt_i32_e32 vcc, 56, v234
	v_max_f32_e32 v90, v90, v91
	v_max3_f32 v88, v88, v89, v90
	v_cndmask_b32_e32 v10, v196, v93, vcc
	v_cmp_lt_i32_e32 vcc, 55, v234
	v_max_f32_e32 v89, v15, v15
	v_max_f32_e32 v90, v81, v81
	v_cndmask_b32_e32 v13, v196, v92, vcc
	v_cmp_lt_i32_e32 vcc, 26, v234
	v_max_f32_e32 v89, v89, v90
	v_max_f32_e32 v90, v12, v12
	v_max_f32_e32 v91, v14, v14
	v_cndmask_b32_e32 v3, v196, v111, vcc
	v_cmp_lt_i32_e32 vcc, 25, v234
	v_max_f32_e32 v90, v90, v91
	v_max3_f32 v88, v88, v89, v90
	v_cndmask_b32_e32 v7, v196, v110, vcc
	v_cmp_lt_i32_e32 vcc, 58, v234
	v_max_f32_e32 v89, v11, v11
	v_max_f32_e32 v90, v13, v13
	v_cndmask_b32_e32 v6, v196, v95, vcc
	v_cmp_lt_i32_e32 vcc, 57, v234
	v_max_f32_e32 v89, v89, v90
	v_max_f32_e32 v90, v8, v8
	v_max_f32_e32 v91, v10, v10
	v_cndmask_b32_e32 v9, v196, v94, vcc
	v_max_f32_e32 v90, v90, v91
	v_max3_f32 v88, v88, v89, v90
	v_max_f32_e32 v89, v7, v7
	v_max_f32_e32 v90, v9, v9
	v_max_f32_e32 v89, v89, v90
	v_max_f32_e32 v90, v3, v3
	v_max_f32_e32 v91, v6, v6
	v_max_f32_e32 v90, v90, v91
	v_max3_f32 v88, v88, v89, v90
	ds_bpermute_b32 v89, v174, v88
	s_and_b64 vcc, exec, s[16:17]
	s_waitcnt lgkmcnt(0)
	v_max_f32_e32 v89, v89, v89
	v_max_f32_e32 v88, v88, v89
	v_cmp_lt_f32_e64 s[44:45], s38, v88
	s_cbranch_vccnz .LBB0_722
	s_cmp_lg_u64 s[44:45], 0
	s_cselect_b64 s[18:19], -1, 0

.LBB0_724:
	v_exp_f32_e32 v108, v243
	v_exp_f32_e32 v109, v244
	v_exp_f32_e32 v4, v4
	v_exp_f32_e32 v88, v242
	v_exp_f32_e32 v110, v241
	v_add_f32_e32 v89, v109, v108
	v_exp_f32_e32 v92, v239
	v_add_f32_e32 v90, v88, v4
	v_add_f32_e32 v91, v89, v5
	v_exp_f32_e32 v89, v240
	v_add_f32_e32 v91, v90, v91
	v_exp_f32_e32 v90, v238
	v_exp_f32_e32 v98, v98
	v_add_f32_e32 v93, v110, v89
	v_exp_f32_e32 v14, v14
	v_add_f32_e32 v94, v92, v90
	v_add_f32_e32 v95, v93, v91
	v_exp_f32_e32 v91, v99
	v_add_f32_e32 v95, v94, v95
	v_exp_f32_e32 v93, v100
	v_exp_f32_e32 v94, v97
	v_exp_f32_e32 v102, v10
	v_exp_f32_e32 v106, v6
	v_add_f32_e32 v99, v93, v91
	v_add_f32_e32 v100, v98, v94
	v_add_f32_e32 v101, v99, v95
	v_exp_f32_e32 v95, v96
	v_add_f32_e32 v101, v100, v101
	v_exp_f32_e32 v99, v86
	v_exp_f32_e32 v100, v84
	v_exp_f32_e32 v96, v87
	v_exp_f32_e32 v84, v82
	v_add_f32_e32 v97, v99, v95
	v_add_f32_e32 v86, v96, v100
	v_add_f32_e32 v87, v97, v101
	s_nop 0
	v_add_f32_e32 v87, v86, v87
	v_exp_f32_e32 v97, v83
	v_exp_f32_e32 v101, v85
	v_exp_f32_e32 v86, v80
	v_add_f32_e32 v85, v101, v97
	v_add_f32_e32 v82, v84, v86
	v_add_f32_e32 v83, v85, v87
	v_exp_f32_e32 v85, v15
	v_add_f32_e32 v83, v82, v83
	v_exp_f32_e32 v87, v81
	v_exp_f32_e32 v82, v12
	v_exp_f32_e32 v12, v11
	v_add_f32_e32 v15, v87, v85
	v_add_f32_e32 v80, v14, v82
	v_add_f32_e32 v81, v15, v83
	v_exp_f32_e32 v15, v13
	v_add_f32_e32 v81, v80, v81
	v_exp_f32_e32 v80, v8
	v_exp_f32_e32 v13, v7
	v_add_f32_e32 v103, v15, v12
	v_add_f32_e32 v10, v102, v80
	v_add_f32_e32 v11, v103, v81
	s_nop 0
	v_add_f32_e32 v105, v10, v11
	v_exp_f32_e32 v103, v9
	v_exp_f32_e32 v104, v3
	v_add_f32_e32 v107, v103, v13
	v_add_f32_e32 v6, v106, v104
	v_add_f32_e32 v7, v107, v105
	s_nop 0
	v_add_f32_e32 v3, v6, v7
	v_cvt_pk_bf16_f32 v6, v108, v4
	v_cvt_pk_bf16_f32 v7, v89, v90
	v_cvt_pk_bf16_f32 v8, v91, v94
	v_cvt_pk_bf16_f32 v9, v95, v100
	v_cvt_pk_bf16_f32 v10, v97, v86
	v_cvt_pk_bf16_f32 v11, v85, v82
	v_cvt_pk_bf16_f32 v12, v12, v80
	v_cvt_pk_bf16_f32 v13, v13, v104
	v_cvt_pk_bf16_f32 v80, v109, v88
	v_cvt_pk_bf16_f32 v81, v110, v92
	v_cvt_pk_bf16_f32 v82, v93, v98
	v_cvt_pk_bf16_f32 v83, v99, v96
	v_cvt_pk_bf16_f32 v84, v101, v84
	v_cvt_pk_bf16_f32 v85, v87, v14
	v_cvt_pk_bf16_f32 v86, v15, v102
	v_cvt_pk_bf16_f32 v87, v103, v106
	ds_read_b64_tr_b16 v[88:89], v223 offset:18432
	ds_read_b64_tr_b16 v[90:91], v223 offset:20992
	ds_read_b64_tr_b16 v[92:93], v223 offset:18496
	ds_read_b64_tr_b16 v[94:95], v223 offset:21056
	ds_read_b64_tr_b16 v[96:97], v223 offset:18560
	ds_read_b64_tr_b16 v[98:99], v223 offset:21120
	ds_read_b64_tr_b16 v[100:101], v223 offset:18624
	ds_read_b64_tr_b16 v[102:103], v223 offset:21184
	ds_read_b64_tr_b16 v[104:105], v223 offset:23552
	ds_read_b64_tr_b16 v[106:107], v223 offset:26112
	ds_read_b64_tr_b16 v[108:109], v223 offset:23616
	ds_read_b64_tr_b16 v[110:111], v223 offset:26176
	ds_read_b64_tr_b16 v[238:239], v223 offset:23680
	ds_read_b64_tr_b16 v[240:241], v223 offset:26240
	ds_read_b64_tr_b16 v[242:243], v223 offset:23744
	ds_read_b64_tr_b16 v[244:245], v223 offset:26304
	s_setprio 1
	s_waitcnt lgkmcnt(14)
	v_mfma_f32_32x32x16_bf16 v[64:79], v[88:91], v[6:9], v[64:79]
	s_waitcnt lgkmcnt(12)
	v_mfma_f32_32x32x16_bf16 v[48:63], v[92:95], v[6:9], v[48:63]
	s_waitcnt lgkmcnt(10)
	v_mfma_f32_32x32x16_bf16 v[32:47], v[96:99], v[6:9], v[32:47]
	s_waitcnt lgkmcnt(8)
	v_mfma_f32_32x32x16_bf16 v[16:31], v[100:103], v[6:9], v[16:31]
	s_setprio 0
	ds_read_b64_tr_b16 v[6:7], v223 offset:28672
	ds_read_b64_tr_b16 v[88:89], v223 offset:28736
	ds_read_b64_tr_b16 v[92:93], v223 offset:28800
	ds_read_b64_tr_b16 v[96:97], v223 offset:28864
	ds_read_b64_tr_b16 v[8:9], v223 offset:31232
	ds_read_b64_tr_b16 v[90:91], v223 offset:31296
	ds_read_b64_tr_b16 v[94:95], v223 offset:31360
	ds_read_b64_tr_b16 v[98:99], v223 offset:31424
	s_setprio 1
	s_waitcnt lgkmcnt(14)
	v_mfma_f32_32x32x16_bf16 v[64:79], v[104:107], v[10:13], v[64:79]
	s_waitcnt lgkmcnt(12)
	v_mfma_f32_32x32x16_bf16 v[48:63], v[108:111], v[10:13], v[48:63]
	s_waitcnt lgkmcnt(10)
	v_mfma_f32_32x32x16_bf16 v[32:47], v[238:241], v[10:13], v[32:47]
	s_waitcnt lgkmcnt(8)
	v_mfma_f32_32x32x16_bf16 v[16:31], v[242:245], v[10:13], v[16:31]
	s_setprio 0
	ds_read_b64_tr_b16 v[10:11], v223 offset:33792
	ds_read_b64_tr_b16 v[100:101], v223 offset:33856
	ds_read_b64_tr_b16 v[104:105], v223 offset:33920
	ds_read_b64_tr_b16 v[108:109], v223 offset:33984
	ds_read_b64_tr_b16 v[12:13], v223 offset:36352
	ds_read_b64_tr_b16 v[102:103], v223 offset:36416
	ds_read_b64_tr_b16 v[106:107], v223 offset:36480
	ds_read_b64_tr_b16 v[110:111], v223 offset:36544
	s_setprio 1
	s_waitcnt lgkmcnt(11)
	v_mfma_f32_32x32x16_bf16 v[64:79], v[6:9], v[80:83], v[64:79]
	s_waitcnt lgkmcnt(10)
	v_mfma_f32_32x32x16_bf16 v[48:63], v[88:91], v[80:83], v[48:63]
	s_waitcnt lgkmcnt(9)
	v_mfma_f32_32x32x16_bf16 v[32:47], v[92:95], v[80:83], v[32:47]
	s_waitcnt lgkmcnt(8)
	v_mfma_f32_32x32x16_bf16 v[16:31], v[96:99], v[80:83], v[16:31]
	s_setprio 0
	s_setprio 1
	s_waitcnt lgkmcnt(3)
	v_mfma_f32_32x32x16_bf16 v[64:79], v[10:13], v[84:87], v[64:79]
	s_waitcnt lgkmcnt(2)
	v_mfma_f32_32x32x16_bf16 v[48:63], v[100:103], v[84:87], v[48:63]
	s_waitcnt lgkmcnt(1)
	v_mfma_f32_32x32x16_bf16 v[32:47], v[104:107], v[84:87], v[32:47]
	s_waitcnt lgkmcnt(0)
	v_mfma_f32_32x32x16_bf16 v[16:31], v[108:111], v[84:87], v[16:31]
	s_setprio 0
	v_add_f32_e32 v224, v224, v3
	s_cmp_lt_i32 s21, 1
	s_cbranch_scc0 .LBB0_712
	s_branch .LBB0_713

.LBB0_726:
	v_add_u32_e32 v244, 64, v234
	v_cvt_f32_i32_e32 v1, v244
	s_cmp_eq_u32 s7, 0
	s_cselect_b64 s[16:17], -1, 0
	v_cndmask_b32_e64 v0, v225, 0, s[16:17]
	v_fma_f32 v0, -v154, v1, -v0
	s_mov_b32 s18, 2.0
	v_add_f32_e32 v2, v153, v0
	s_mov_b32 s19, 0x40400000
	v_fma_f32 v98, v154, s18, v0
	v_fma_f32 v99, v155, s19, v0
	v_fma_f32 v82, v154, s18, v2
	v_fma_f32 v83, v155, s19, v2
	s_mov_b32 s18, 0x41200000
	s_mov_b32 s19, 0x41300000
	v_fma_f32 v102, v154, s18, v0
	v_fma_f32 v103, v155, s19, v0
	v_fma_f32 v86, v154, s18, v2
	v_fma_f32 v87, v155, s19, v2
	s_mov_b32 s18, 0x41800000
	s_mov_b32 s19, 0x41880000
	v_fma_f32 v104, v154, s18, v0
	v_fma_f32 v105, v155, s19, v0
	v_fma_f32 v88, v154, s18, v2
	v_fma_f32 v89, v155, s19, v2
	s_mov_b32 s18, 0x41900000
	s_mov_b32 s19, 0x41980000
	v_fma_f32 v96, 0, v154, v0
	v_fma_f32 v80, 0, v154, v2
	v_add_f32_e32 v97, v154, v0
	v_add_f32_e32 v81, v154, v2
	v_fma_f32 v100, v154, s38, v0
	v_fma_f32 v101, v155, s39, v0
	v_fma_f32 v84, v154, s38, v2
	v_fma_f32 v85, v155, s39, v2
	v_fma_f32 v106, v154, s18, v0
	v_fma_f32 v107, v155, s19, v0
	v_fma_f32 v90, v154, s18, v2
	v_fma_f32 v91, v155, s19, v2
	v_fma_f32 v108, v154, s26, v0
	v_fma_f32 v109, v155, s27, v0
	v_fma_f32 v92, v154, s26, v2
	v_fma_f32 v93, v155, s27, v2
	v_fma_f32 v110, v154, s36, v0
	v_fma_f32 v111, v155, s37, v0
	v_fma_f32 v94, v154, s36, v2
	v_fma_f32 v95, v155, s37, v2
	ds_read_b128 v[0:3], v222 offset:13824
	ds_read_b128 v[6:9], v222 offset:9216
	ds_read_b128 v[10:13], v222 offset:9248
	s_waitcnt lgkmcnt(1)
	v_mfma_f32_32x32x16_bf16 v[96:111], v[6:9], v[112:115], v[96:111]
	v_cmp_lt_i32_e32 vcc, 0, v244
	s_mov_b64 s[18:19], s[16:17]
	v_mfma_f32_32x32x16_bf16 v[80:95], v[0:3], v[112:115], v[80:95]
	ds_read_b128 v[0:3], v222 offset:13856
	s_waitcnt lgkmcnt(1)
	v_mfma_f32_32x32x16_bf16 v[96:111], v[10:13], v[116:119], v[96:111]
	s_waitcnt lgkmcnt(0)
	v_mfma_f32_32x32x16_bf16 v[80:95], v[0:3], v[116:119], v[80:95]
	ds_read_b128 v[0:3], v222 offset:9280
	ds_read_b128 v[6:9], v222 offset:13888
	s_waitcnt lgkmcnt(1)
	v_mfma_f32_32x32x16_bf16 v[96:111], v[0:3], v[120:123], v[96:111]
	s_waitcnt lgkmcnt(0)
	v_mfma_f32_32x32x16_bf16 v[80:95], v[6:9], v[120:123], v[80:95]
	ds_read_b128 v[0:3], v222 offset:9312
	ds_read_b128 v[6:9], v222 offset:13920
	s_waitcnt lgkmcnt(1)
	v_mfma_f32_32x32x16_bf16 v[96:111], v[0:3], v[124:127], v[96:111]
	s_waitcnt lgkmcnt(0)
	v_mfma_f32_32x32x16_bf16 v[80:95], v[6:9], v[124:127], v[80:95]
	s_nop 9
	v_cndmask_b32_e32 v4, v196, v97, vcc
	v_cmp_lt_i32_e32 vcc, -1, v244
	s_nop 1
	v_cndmask_b32_e32 v242, v196, v96, vcc
	v_cmp_lt_i32_e32 vcc, 32, v244
	s_nop 1
	v_cndmask_b32_e32 v241, v196, v81, vcc
	v_cmp_lt_i32_e32 vcc, 31, v244
	s_nop 1
	v_cndmask_b32_e32 v243, v196, v80, vcc
	v_cmp_lt_i32_e32 vcc, 2, v244
	s_nop 1
	v_cndmask_b32_e32 v99, v196, v99, vcc
	v_cmp_lt_i32_e32 vcc, 1, v244
	s_nop 1
	v_cndmask_b32_e32 v239, v196, v98, vcc
	v_cmp_lt_i32_e32 vcc, 34, v244
	s_nop 1
	v_cndmask_b32_e32 v238, v196, v83, vcc
	v_cmp_lt_i32_e32 vcc, 33, v244
	s_nop 1
	v_cndmask_b32_e32 v240, v196, v82, vcc
	v_cmp_lt_i32_e32 vcc, 8, v244
	s_nop 1
	v_cndmask_b32_e32 v96, v196, v101, vcc
	v_cmp_lt_i32_e32 vcc, 7, v244
	s_nop 1
	v_cndmask_b32_e32 v98, v196, v100, vcc
	v_cmp_lt_i32_e32 vcc, 40, v244
	s_nop 1
	v_cndmask_b32_e32 v97, v196, v85, vcc
	v_cmp_lt_i32_e32 vcc, 39, v244
	s_nop 1
	v_cndmask_b32_e32 v100, v196, v84, vcc
	v_cmp_lt_i32_e32 vcc, 10, v244
	s_nop 1
	v_cndmask_b32_e32 v81, v196, v103, vcc
	v_cmp_lt_i32_e32 vcc, 9, v244
	s_nop 1
	v_cndmask_b32_e32 v84, v196, v102, vcc
	v_cmp_lt_i32_e32 vcc, 42, v244
	s_nop 1
	v_cndmask_b32_e32 v83, v196, v87, vcc
	v_cmp_lt_i32_e32 vcc, 41, v244
	v_max_f32_e32 v87, v241, v241
	s_nop 0
	v_cndmask_b32_e32 v85, v196, v86, vcc
	v_cmp_lt_i32_e32 vcc, 16, v244
	v_max_f32_e32 v86, v4, v4
	v_max_f32_e32 v86, v86, v87
	v_cndmask_b32_e32 v13, v196, v105, vcc
	v_cmp_lt_i32_e32 vcc, 15, v244
	v_max_f32_e32 v87, v239, v239
	v_max3_f32 v86, v242, v243, v86
	v_cndmask_b32_e32 v80, v196, v104, vcc
	v_cmp_lt_i32_e32 vcc, 48, v244
	s_nop 1
	v_cndmask_b32_e32 v15, v196, v89, vcc
	v_cmp_lt_i32_e32 vcc, 47, v244
	v_max_f32_e32 v89, v238, v238
	s_nop 0
	v_cndmask_b32_e32 v82, v196, v88, vcc
	v_max_f32_e32 v88, v240, v240
	v_max_f32_e32 v87, v87, v88
	v_max_f32_e32 v88, v99, v99
	v_max_f32_e32 v88, v88, v89
	v_max3_f32 v86, v86, v87, v88
	v_max_f32_e32 v87, v98, v98
	v_max_f32_e32 v88, v100, v100
	v_max_f32_e32 v87, v87, v88
	v_max_f32_e32 v88, v96, v96
	v_max_f32_e32 v89, v97, v97
	v_cmp_lt_i32_e32 vcc, 18, v244
	v_max_f32_e32 v88, v88, v89
	v_max3_f32 v86, v86, v87, v88
	v_cndmask_b32_e32 v9, v196, v107, vcc
	v_cmp_lt_i32_e32 vcc, 17, v244
	v_max_f32_e32 v87, v84, v84
	v_max_f32_e32 v88, v85, v85
	v_cndmask_b32_e32 v12, v196, v106, vcc
	v_cmp_lt_i32_e32 vcc, 50, v244
	v_max_f32_e32 v87, v87, v88
	v_max_f32_e32 v88, v81, v81
	v_max_f32_e32 v89, v83, v83
	v_cndmask_b32_e32 v11, v196, v91, vcc
	v_cmp_lt_i32_e32 vcc, 49, v244
	v_max_f32_e32 v88, v88, v89
	v_max3_f32 v86, v86, v87, v88
	v_cndmask_b32_e32 v14, v196, v90, vcc
	v_cmp_lt_i32_e32 vcc, 24, v244
	v_max_f32_e32 v87, v80, v80
	v_max_f32_e32 v88, v82, v82
	v_cndmask_b32_e32 v3, v196, v109, vcc
	v_cmp_lt_i32_e32 vcc, 23, v244
	v_max_f32_e32 v87, v87, v88
	v_max_f32_e32 v88, v13, v13
	v_max_f32_e32 v89, v15, v15
	v_cndmask_b32_e32 v8, v196, v108, vcc
	v_cmp_lt_i32_e32 vcc, 56, v244
	v_max_f32_e32 v88, v88, v89
	v_max3_f32 v86, v86, v87, v88
	v_cndmask_b32_e32 v7, v196, v93, vcc
	v_cmp_lt_i32_e32 vcc, 55, v244
	v_max_f32_e32 v87, v12, v12
	v_max_f32_e32 v88, v14, v14
	v_cndmask_b32_e32 v10, v196, v92, vcc
	v_cmp_lt_i32_e32 vcc, 26, v244
	v_max_f32_e32 v87, v87, v88
	v_max_f32_e32 v88, v9, v9
	v_max_f32_e32 v89, v11, v11
	v_cndmask_b32_e32 v0, v196, v111, vcc
	v_cmp_lt_i32_e32 vcc, 25, v244
	v_max_f32_e32 v88, v88, v89
	v_max3_f32 v86, v86, v87, v88
	v_cndmask_b32_e32 v2, v196, v110, vcc
	v_cmp_lt_i32_e32 vcc, 58, v244
	v_max_f32_e32 v87, v8, v8
	v_max_f32_e32 v88, v10, v10
	v_cndmask_b32_e32 v1, v196, v95, vcc
	v_cmp_lt_i32_e32 vcc, 57, v244
	v_max_f32_e32 v87, v87, v88
	v_max_f32_e32 v88, v3, v3
	v_max_f32_e32 v89, v7, v7
	v_cndmask_b32_e32 v6, v196, v94, vcc
	v_max_f32_e32 v88, v88, v89
	v_max3_f32 v86, v86, v87, v88
	v_max_f32_e32 v87, v2, v2
	v_max_f32_e32 v88, v6, v6
	v_max_f32_e32 v87, v87, v88
	v_max_f32_e32 v88, v0, v0
	v_max_f32_e32 v89, v1, v1
	v_max_f32_e32 v88, v88, v89
	v_max3_f32 v86, v86, v87, v88
	ds_bpermute_b32 v87, v174, v86
	s_and_b64 vcc, exec, s[16:17]
	s_waitcnt lgkmcnt(0)
	v_max_f32_e32 v87, v87, v87
	v_max_f32_e32 v86, v86, v87
	v_cmp_lt_f32_e64 s[44:45], s38, v86
	s_cbranch_vccnz .LBB0_728
	s_cmp_lg_u64 s[44:45], 0
	s_cselect_b64 s[18:19], -1, 0

.LBB0_730:
	v_exp_f32_e32 v104, v242
	v_exp_f32_e32 v105, v243
	v_exp_f32_e32 v4, v4
	v_exp_f32_e32 v86, v241
	v_exp_f32_e32 v106, v240
	v_add_f32_e32 v87, v105, v104
	v_exp_f32_e32 v90, v238
	v_add_f32_e32 v88, v86, v4
	v_add_f32_e32 v89, v87, v5
	v_exp_f32_e32 v87, v239
	v_add_f32_e32 v89, v88, v89
	v_exp_f32_e32 v88, v99
	v_exp_f32_e32 v94, v97
	v_add_f32_e32 v91, v106, v87
	v_exp_f32_e32 v102, v1
	v_add_f32_e32 v92, v90, v88
	v_add_f32_e32 v93, v91, v89
	v_exp_f32_e32 v89, v98
	v_add_f32_e32 v93, v92, v93
	v_exp_f32_e32 v91, v100
	v_exp_f32_e32 v92, v96
	v_exp_f32_e32 v100, v7
	v_add_f32_e32 v95, v91, v89
	v_add_f32_e32 v96, v94, v92
	v_add_f32_e32 v97, v95, v93
	v_exp_f32_e32 v93, v84
	v_add_f32_e32 v97, v96, v97
	v_exp_f32_e32 v95, v85
	v_exp_f32_e32 v96, v81
	v_exp_f32_e32 v84, v83
	v_add_f32_e32 v85, v95, v93
	v_add_f32_e32 v98, v84, v96
	v_add_f32_e32 v99, v85, v97
	s_nop 0
	v_add_f32_e32 v99, v98, v99
	v_exp_f32_e32 v85, v80
	v_exp_f32_e32 v97, v82
	v_exp_f32_e32 v98, v13
	v_exp_f32_e32 v80, v15
	v_add_f32_e32 v81, v97, v85
	v_add_f32_e32 v82, v80, v98
	v_add_f32_e32 v83, v81, v99
	s_nop 0
	v_add_f32_e32 v83, v82, v83
	v_exp_f32_e32 v81, v12
	v_exp_f32_e32 v99, v14
	v_exp_f32_e32 v82, v9
	v_exp_f32_e32 v14, v11
	v_add_f32_e32 v15, v99, v81
	v_add_f32_e32 v12, v14, v82
	v_add_f32_e32 v13, v15, v83
	s_nop 0
	v_add_f32_e32 v13, v12, v13
	v_exp_f32_e32 v15, v8
	v_exp_f32_e32 v83, v10
	v_exp_f32_e32 v12, v3
	v_add_f32_e32 v101, v83, v15
	v_add_f32_e32 v8, v100, v12
	v_add_f32_e32 v9, v101, v13
	v_exp_f32_e32 v101, v6
	v_add_f32_e32 v11, v8, v9
	v_exp_f32_e32 v9, v2
	v_exp_f32_e32 v10, v0
	v_add_f32_e32 v103, v101, v9
	v_add_f32_e32 v0, v102, v10
	v_add_f32_e32 v1, v103, v11
	s_nop 0
	v_add_f32_e32 v242, v0, v1
	v_cvt_pk_bf16_f32 v0, v104, v4
	v_cvt_pk_bf16_f32 v1, v87, v88
	v_cvt_pk_bf16_f32 v2, v89, v92
	v_cvt_pk_bf16_f32 v3, v93, v96
	v_cvt_pk_bf16_f32 v6, v85, v98
	v_cvt_pk_bf16_f32 v7, v81, v82
	v_cvt_pk_bf16_f32 v8, v15, v12
	v_cvt_pk_bf16_f32 v9, v9, v10
	v_cvt_pk_bf16_f32 v10, v105, v86
	v_cvt_pk_bf16_f32 v11, v106, v90
	v_cvt_pk_bf16_f32 v12, v91, v94
	v_cvt_pk_bf16_f32 v13, v95, v84
	v_cvt_pk_bf16_f32 v80, v97, v80
	v_cvt_pk_bf16_f32 v81, v99, v14
	v_cvt_pk_bf16_f32 v82, v83, v100
	v_cvt_pk_bf16_f32 v83, v101, v102
	ds_read_b64_tr_b16 v[84:85], v223 offset:38912
	ds_read_b64_tr_b16 v[86:87], v223 offset:41472
	ds_read_b64_tr_b16 v[88:89], v223 offset:38976
	ds_read_b64_tr_b16 v[90:91], v223 offset:41536
	ds_read_b64_tr_b16 v[92:93], v223 offset:39040
	ds_read_b64_tr_b16 v[94:95], v223 offset:41600
	ds_read_b64_tr_b16 v[96:97], v223 offset:39104
	ds_read_b64_tr_b16 v[98:99], v223 offset:41664
	ds_read_b64_tr_b16 v[100:101], v223 offset:44032
	ds_read_b64_tr_b16 v[102:103], v223 offset:46592
	ds_read_b64_tr_b16 v[104:105], v223 offset:44096
	ds_read_b64_tr_b16 v[106:107], v223 offset:46656
	ds_read_b64_tr_b16 v[108:109], v223 offset:44160
	ds_read_b64_tr_b16 v[110:111], v223 offset:46720
	ds_read_b64_tr_b16 v[238:239], v223 offset:44224
	ds_read_b64_tr_b16 v[240:241], v223 offset:46784
	s_setprio 1
	s_waitcnt lgkmcnt(14)
	v_mfma_f32_32x32x16_bf16 v[64:79], v[84:87], v[0:3], v[64:79]
	s_waitcnt lgkmcnt(12)
	v_mfma_f32_32x32x16_bf16 v[48:63], v[88:91], v[0:3], v[48:63]
	s_waitcnt lgkmcnt(10)
	v_mfma_f32_32x32x16_bf16 v[32:47], v[92:95], v[0:3], v[32:47]
	s_waitcnt lgkmcnt(8)
	v_mfma_f32_32x32x16_bf16 v[16:31], v[96:99], v[0:3], v[16:31]
	s_setprio 0
	ds_read_b64_tr_b16 v[0:1], v223 offset:49152
	ds_read_b64_tr_b16 v[84:85], v223 offset:49216
	ds_read_b64_tr_b16 v[88:89], v223 offset:49280
	ds_read_b64_tr_b16 v[92:93], v223 offset:49344
	ds_read_b64_tr_b16 v[2:3], v223 offset:51712
	ds_read_b64_tr_b16 v[86:87], v223 offset:51776
	ds_read_b64_tr_b16 v[90:91], v223 offset:51840
	ds_read_b64_tr_b16 v[94:95], v223 offset:51904
	s_setprio 1
	s_waitcnt lgkmcnt(14)
	v_mfma_f32_32x32x16_bf16 v[64:79], v[100:103], v[6:9], v[64:79]
	s_waitcnt lgkmcnt(12)
	v_mfma_f32_32x32x16_bf16 v[48:63], v[104:107], v[6:9], v[48:63]
	s_waitcnt lgkmcnt(10)
	v_mfma_f32_32x32x16_bf16 v[32:47], v[108:111], v[6:9], v[32:47]
	s_waitcnt lgkmcnt(8)
	v_mfma_f32_32x32x16_bf16 v[16:31], v[238:241], v[6:9], v[16:31]
	s_setprio 0
	ds_read_b64_tr_b16 v[6:7], v223 offset:54272
	ds_read_b64_tr_b16 v[96:97], v223 offset:54336
	ds_read_b64_tr_b16 v[100:101], v223 offset:54400
	ds_read_b64_tr_b16 v[104:105], v223 offset:54464
	ds_read_b64_tr_b16 v[8:9], v223 offset:56832
	ds_read_b64_tr_b16 v[98:99], v223 offset:56896
	ds_read_b64_tr_b16 v[102:103], v223 offset:56960
	ds_read_b64_tr_b16 v[106:107], v223 offset:57024
	s_setprio 1
	s_waitcnt lgkmcnt(11)
	v_mfma_f32_32x32x16_bf16 v[64:79], v[0:3], v[10:13], v[64:79]
	s_waitcnt lgkmcnt(10)
	v_mfma_f32_32x32x16_bf16 v[48:63], v[84:87], v[10:13], v[48:63]
	s_waitcnt lgkmcnt(9)
	v_mfma_f32_32x32x16_bf16 v[32:47], v[88:91], v[10:13], v[32:47]
	s_waitcnt lgkmcnt(8)
	v_mfma_f32_32x32x16_bf16 v[16:31], v[92:95], v[10:13], v[16:31]
	s_setprio 0
	s_setprio 1
	s_waitcnt lgkmcnt(3)
	v_mfma_f32_32x32x16_bf16 v[64:79], v[6:9], v[80:83], v[64:79]
	s_waitcnt lgkmcnt(2)
	v_mfma_f32_32x32x16_bf16 v[48:63], v[96:99], v[80:83], v[48:63]
	s_waitcnt lgkmcnt(1)
	v_mfma_f32_32x32x16_bf16 v[32:47], v[100:103], v[80:83], v[32:47]
	s_waitcnt lgkmcnt(0)
	v_mfma_f32_32x32x16_bf16 v[16:31], v[104:107], v[80:83], v[16:31]
	s_setprio 0
	v_add_f32_e32 v224, v224, v242
	s_andn2_b64 vcc, exec, s[14:15]
	s_cbranch_vccz .LBB0_716
	s_branch .LBB0_717

.LBB0_743:
	v_cvt_f32_i32_e32 v4, v0
	s_cmp_eq_u32 s22, s7
	s_cselect_b64 s[44:45], -1, 0
	v_cndmask_b32_e64 v10, v225, 0, s[44:45]
	v_add_u32_e32 v14, s4, v222
	v_fma_f32 v4, -v154, v4, -v10
	ds_read_b128 v[10:13], v14
	s_mov_b32 s18, 2.0
	s_mov_b32 s20, 0x41200000
	s_mov_b32 s24, 0x41800000
	s_mov_b32 s28, 0x41900000
	s_mov_b32 s19, 0x40400000
	s_mov_b32 s21, 0x41300000
	s_mov_b32 s25, 0x41880000
	s_mov_b32 s29, 0x41980000
	v_fma_f32 v80, 0, v154, v4
	v_add_f32_e32 v81, v154, v4
	v_fma_f32 v82, v154, s18, v4
	v_fma_f32 v83, v155, s19, v4
	v_fma_f32 v84, v154, s38, v4
	v_fma_f32 v85, v155, s39, v4
	v_fma_f32 v86, v154, s20, v4
	v_fma_f32 v87, v155, s21, v4
	v_fma_f32 v88, v154, s24, v4
	v_fma_f32 v89, v155, s25, v4
	v_fma_f32 v90, v154, s28, v4
	v_fma_f32 v91, v155, s29, v4
	v_fma_f32 v92, v154, s26, v4
	v_fma_f32 v93, v155, s27, v4
	v_fma_f32 v94, v154, s36, v4
	v_fma_f32 v95, v155, s37, v4
	v_add_f32_e32 v4, v153, v4
	v_fma_f32 v96, 0, v154, v4
	s_waitcnt lgkmcnt(0)
	v_mfma_f32_32x32x16_bf16 v[80:95], v[10:13], v[112:115], v[80:95]
	ds_read_b128 v[10:13], v14 offset:32
	v_add_f32_e32 v97, v154, v4
	v_fma_f32 v98, v154, s18, v4
	v_fma_f32 v99, v155, s19, v4
	v_fma_f32 v100, v154, s38, v4
	v_fma_f32 v101, v155, s39, v4
	v_fma_f32 v102, v154, s20, v4
	v_fma_f32 v103, v155, s21, v4
	v_fma_f32 v104, v154, s24, v4
	v_fma_f32 v105, v155, s25, v4
	v_fma_f32 v106, v154, s28, v4
	v_fma_f32 v107, v155, s29, v4
	s_waitcnt lgkmcnt(0)
	v_mfma_f32_32x32x16_bf16 v[80:95], v[10:13], v[116:119], v[80:95]
	ds_read_b128 v[10:13], v14 offset:64
	v_fma_f32 v108, v154, s26, v4
	v_fma_f32 v109, v155, s27, v4
	v_fma_f32 v110, v154, s36, v4
	v_fma_f32 v111, v155, s37, v4
	s_cmp_lg_u32 s22, s7
	s_waitcnt lgkmcnt(0)
	v_mfma_f32_32x32x16_bf16 v[80:95], v[10:13], v[120:123], v[80:95]
	ds_read_b128 v[10:13], v14 offset:96
	ds_read_b128 v[226:229], v14 offset:4608
	s_waitcnt lgkmcnt(1)
	v_mfma_f32_32x32x16_bf16 v[80:95], v[10:13], v[124:127], v[80:95]
	ds_read_b128 v[10:13], v14 offset:4640
	s_waitcnt lgkmcnt(1)
	v_mfma_f32_32x32x16_bf16 v[96:111], v[226:229], v[112:115], v[96:111]
	s_nop 8
	v_max_f32_e32 v4, v81, v81
	s_waitcnt lgkmcnt(0)
	v_mfma_f32_32x32x16_bf16 v[96:111], v[10:13], v[116:119], v[96:111]
	ds_read_b128 v[10:13], v14 offset:4672
	s_waitcnt lgkmcnt(0)
	v_mfma_f32_32x32x16_bf16 v[96:111], v[10:13], v[120:123], v[96:111]
	ds_read_b128 v[10:13], v14 offset:4704
	s_waitcnt lgkmcnt(0)
	v_mfma_f32_32x32x16_bf16 v[96:111], v[10:13], v[124:127], v[96:111]
	s_nop 11
	v_max_f32_e32 v10, v97, v97
	v_max_f32_e32 v4, v4, v10
	v_max_f32_e32 v10, v82, v82
	v_max_f32_e32 v11, v98, v98
	v_max_f32_e32 v10, v10, v11
	v_max_f32_e32 v11, v83, v83
	v_max_f32_e32 v12, v99, v99
	v_max3_f32 v4, v80, v96, v4
	v_max_f32_e32 v11, v11, v12
	v_max3_f32 v4, v4, v10, v11
	v_max_f32_e32 v10, v84, v84
	v_max_f32_e32 v11, v100, v100
	v_max_f32_e32 v10, v10, v11
	v_max_f32_e32 v11, v85, v85
	v_max_f32_e32 v12, v101, v101
	v_max_f32_e32 v11, v11, v12
	v_max3_f32 v4, v4, v10, v11
	v_max_f32_e32 v10, v86, v86
	v_max_f32_e32 v11, v102, v102
	v_max_f32_e32 v10, v10, v11
	v_max_f32_e32 v11, v87, v87
	v_max_f32_e32 v12, v103, v103
	v_max_f32_e32 v11, v11, v12
	v_max3_f32 v4, v4, v10, v11
	v_max_f32_e32 v10, v88, v88
	v_max_f32_e32 v11, v104, v104
	v_max_f32_e32 v10, v10, v11
	v_max_f32_e32 v11, v89, v89
	v_max_f32_e32 v12, v105, v105
	v_max_f32_e32 v11, v11, v12
	v_max3_f32 v4, v4, v10, v11
	v_max_f32_e32 v10, v90, v90
	v_max_f32_e32 v11, v106, v106
	v_max_f32_e32 v10, v10, v11
	v_max_f32_e32 v11, v91, v91
	v_max_f32_e32 v12, v107, v107
	v_max_f32_e32 v11, v11, v12
	v_max3_f32 v4, v4, v10, v11
	v_max_f32_e32 v10, v92, v92
	v_max_f32_e32 v11, v108, v108
	v_max_f32_e32 v10, v10, v11
	v_max_f32_e32 v11, v93, v93
	v_max_f32_e32 v12, v109, v109
	v_max_f32_e32 v11, v11, v12
	v_max3_f32 v4, v4, v10, v11
	v_max_f32_e32 v10, v94, v94
	v_max_f32_e32 v11, v110, v110
	v_max_f32_e32 v10, v10, v11
	v_max_f32_e32 v11, v95, v95
	v_max_f32_e32 v12, v111, v111
	v_max_f32_e32 v11, v11, v12
	v_max3_f32 v4, v4, v10, v11
	ds_bpermute_b32 v10, v174, v4
	s_waitcnt lgkmcnt(0)
	v_max_f32_e32 v10, v10, v10
	v_max_f32_e32 v4, v4, v10
	v_cmp_lt_f32_e32 vcc, s38, v4
	s_cbranch_scc0 .LBB0_748
	s_cmp_lg_u64 vcc, 0
	s_cselect_b64 s[18:19], -1, 0
	s_cbranch_execz .LBB0_749
	s_branch .LBB0_750

.LBB0_746:
	v_add_u32_e32 v4, 64, v0
	v_cvt_f32_i32_e32 v4, v4
	s_cmp_eq_u32 s48, s7
	s_cselect_b64 s[44:45], -1, 0
	v_cndmask_b32_e64 v7, v225, 0, s[44:45]
	v_fma_f32 v4, -v154, v4, -v7
	v_add_u32_e32 v7, s23, v222
	ds_read_b128 v[8:11], v7
	s_mov_b32 s18, 2.0
	s_mov_b32 s20, 0x41200000
	s_mov_b32 s24, 0x41800000
	s_mov_b32 s28, 0x41900000
	s_mov_b32 s19, 0x40400000
	s_mov_b32 s21, 0x41300000
	s_mov_b32 s25, 0x41880000
	s_mov_b32 s29, 0x41980000
	v_fma_f32 v80, 0, v154, v4
	v_add_f32_e32 v81, v154, v4
	v_fma_f32 v82, v154, s18, v4
	v_fma_f32 v83, v155, s19, v4
	v_fma_f32 v84, v154, s38, v4
	v_fma_f32 v85, v155, s39, v4
	v_fma_f32 v86, v154, s20, v4
	v_fma_f32 v87, v155, s21, v4
	v_fma_f32 v88, v154, s24, v4
	v_fma_f32 v89, v155, s25, v4
	v_fma_f32 v90, v154, s28, v4
	v_fma_f32 v91, v155, s29, v4
	v_fma_f32 v92, v154, s26, v4
	v_fma_f32 v93, v155, s27, v4
	v_fma_f32 v94, v154, s36, v4
	v_fma_f32 v95, v155, s37, v4
	v_add_f32_e32 v4, v153, v4
	v_fma_f32 v96, 0, v154, v4
	s_waitcnt lgkmcnt(0)
	v_mfma_f32_32x32x16_bf16 v[80:95], v[8:11], v[112:115], v[80:95]
	ds_read_b128 v[8:11], v7 offset:32
	v_add_f32_e32 v97, v154, v4
	v_fma_f32 v98, v154, s18, v4
	v_fma_f32 v99, v155, s19, v4
	v_fma_f32 v100, v154, s38, v4
	v_fma_f32 v101, v155, s39, v4
	v_fma_f32 v102, v154, s20, v4
	v_fma_f32 v103, v155, s21, v4
	v_fma_f32 v104, v154, s24, v4
	v_fma_f32 v105, v155, s25, v4
	v_fma_f32 v106, v154, s28, v4
	v_fma_f32 v107, v155, s29, v4
	s_waitcnt lgkmcnt(0)
	v_mfma_f32_32x32x16_bf16 v[80:95], v[8:11], v[116:119], v[80:95]
	ds_read_b128 v[8:11], v7 offset:64
	v_fma_f32 v108, v154, s26, v4
	v_fma_f32 v109, v155, s27, v4
	v_fma_f32 v110, v154, s36, v4
	v_fma_f32 v111, v155, s37, v4
	s_cmp_lg_u32 s48, s7
	s_waitcnt lgkmcnt(0)
	v_mfma_f32_32x32x16_bf16 v[80:95], v[8:11], v[120:123], v[80:95]
	ds_read_b128 v[8:11], v7 offset:96
	ds_read_b128 v[12:15], v7 offset:4608
	s_waitcnt lgkmcnt(1)
	v_mfma_f32_32x32x16_bf16 v[80:95], v[8:11], v[124:127], v[80:95]
	ds_read_b128 v[8:11], v7 offset:4640
	s_waitcnt lgkmcnt(1)
	v_mfma_f32_32x32x16_bf16 v[96:111], v[12:15], v[112:115], v[96:111]
	s_nop 8
	v_max_f32_e32 v4, v81, v81
	s_waitcnt lgkmcnt(0)
	v_mfma_f32_32x32x16_bf16 v[96:111], v[8:11], v[116:119], v[96:111]
	ds_read_b128 v[8:11], v7 offset:4672
	s_waitcnt lgkmcnt(0)
	v_mfma_f32_32x32x16_bf16 v[96:111], v[8:11], v[120:123], v[96:111]
	ds_read_b128 v[8:11], v7 offset:4704
	s_waitcnt lgkmcnt(0)
	v_mfma_f32_32x32x16_bf16 v[96:111], v[8:11], v[124:127], v[96:111]
	s_nop 11
	v_max_f32_e32 v7, v97, v97
	v_max_f32_e32 v4, v4, v7
	v_max_f32_e32 v7, v82, v82
	v_max_f32_e32 v8, v98, v98
	v_max_f32_e32 v7, v7, v8
	v_max_f32_e32 v8, v83, v83
	v_max_f32_e32 v9, v99, v99
	v_max3_f32 v4, v80, v96, v4
	v_max_f32_e32 v8, v8, v9
	v_max3_f32 v4, v4, v7, v8
	v_max_f32_e32 v7, v84, v84
	v_max_f32_e32 v8, v100, v100
	v_max_f32_e32 v7, v7, v8
	v_max_f32_e32 v8, v85, v85
	v_max_f32_e32 v9, v101, v101
	v_max_f32_e32 v8, v8, v9
	v_max3_f32 v4, v4, v7, v8
	v_max_f32_e32 v7, v86, v86
	v_max_f32_e32 v8, v102, v102
	v_max_f32_e32 v7, v7, v8
	v_max_f32_e32 v8, v87, v87
	v_max_f32_e32 v9, v103, v103
	v_max_f32_e32 v8, v8, v9
	v_max3_f32 v4, v4, v7, v8
	v_max_f32_e32 v7, v88, v88
	v_max_f32_e32 v8, v104, v104
	v_max_f32_e32 v7, v7, v8
	v_max_f32_e32 v8, v89, v89
	v_max_f32_e32 v9, v105, v105
	v_max_f32_e32 v8, v8, v9
	v_max3_f32 v4, v4, v7, v8
	v_max_f32_e32 v7, v90, v90
	v_max_f32_e32 v8, v106, v106
	v_max_f32_e32 v7, v7, v8
	v_max_f32_e32 v8, v91, v91
	v_max_f32_e32 v9, v107, v107
	v_max_f32_e32 v8, v8, v9
	v_max3_f32 v4, v4, v7, v8
	v_max_f32_e32 v7, v92, v92
	v_max_f32_e32 v8, v108, v108
	v_max_f32_e32 v7, v7, v8
	v_max_f32_e32 v8, v93, v93
	v_max_f32_e32 v9, v109, v109
	v_max_f32_e32 v8, v8, v9
	v_max3_f32 v4, v4, v7, v8
	v_max_f32_e32 v7, v94, v94
	v_max_f32_e32 v8, v110, v110
	v_max_f32_e32 v7, v7, v8
	v_max_f32_e32 v8, v95, v95
	v_max_f32_e32 v9, v111, v111
	v_max_f32_e32 v8, v8, v9
	v_max3_f32 v4, v4, v7, v8
	ds_bpermute_b32 v7, v174, v4
	s_waitcnt lgkmcnt(0)
	v_max_f32_e32 v7, v7, v7
	v_max_f32_e32 v4, v4, v7
	v_cmp_lt_f32_e32 vcc, s38, v4
	s_cbranch_scc0 .LBB0_753
	s_cmp_lg_u64 vcc, 0
	s_cselect_b64 s[18:19], -1, 0
	s_cbranch_execz .LBB0_754
	s_branch .LBB0_755

.LBB0_750:
	s_andn2_b64 vcc, exec, s[18:19]
	s_cbranch_vccnz .LBB0_752
	v_cmp_lt_f32_e32 vcc, s38, v4
	s_or_b64 vcc, s[44:45], vcc
	s_nop 0
	v_cndmask_b32_e32 v10, 0, v4, vcc
	v_add_f32_e32 v11, v225, v10
	v_cndmask_b32_e64 v225, v11, v4, s[44:45]
	v_exp_f32_e64 v4, -v10
	v_sub_f32_e32 v80, v80, v10
	v_sub_f32_e32 v81, v81, v10
	v_sub_f32_e32 v96, v96, v10
	v_sub_f32_e32 v97, v97, v10
	v_sub_f32_e32 v82, v82, v10
	v_sub_f32_e32 v83, v83, v10
	v_sub_f32_e32 v98, v98, v10
	v_sub_f32_e32 v99, v99, v10
	v_sub_f32_e32 v84, v84, v10
	v_sub_f32_e32 v85, v85, v10
	v_sub_f32_e32 v100, v100, v10
	v_sub_f32_e32 v101, v101, v10
	v_sub_f32_e32 v86, v86, v10
	v_sub_f32_e32 v87, v87, v10
	v_sub_f32_e32 v102, v102, v10
	v_sub_f32_e32 v103, v103, v10
	v_sub_f32_e32 v88, v88, v10
	v_sub_f32_e32 v89, v89, v10
	v_sub_f32_e32 v104, v104, v10
	v_sub_f32_e32 v105, v105, v10
	v_sub_f32_e32 v90, v90, v10
	v_sub_f32_e32 v91, v91, v10
	v_sub_f32_e32 v106, v106, v10
	v_sub_f32_e32 v107, v107, v10
	v_sub_f32_e32 v92, v92, v10
	v_sub_f32_e32 v93, v93, v10
	v_sub_f32_e32 v108, v108, v10
	v_sub_f32_e32 v109, v109, v10
	v_sub_f32_e32 v94, v94, v10
	v_sub_f32_e32 v95, v95, v10
	v_sub_f32_e32 v110, v110, v10
	v_sub_f32_e32 v111, v111, v10
	v_pk_mul_f32 v[78:79], v[4:5], v[78:79] op_sel_hi:[0,1]
	v_pk_mul_f32 v[76:77], v[4:5], v[76:77] op_sel_hi:[0,1]
	v_pk_mul_f32 v[74:75], v[4:5], v[74:75] op_sel_hi:[0,1]
	v_pk_mul_f32 v[72:73], v[4:5], v[72:73] op_sel_hi:[0,1]
	v_pk_mul_f32 v[70:71], v[4:5], v[70:71] op_sel_hi:[0,1]
	v_pk_mul_f32 v[68:69], v[4:5], v[68:69] op_sel_hi:[0,1]
	v_pk_mul_f32 v[66:67], v[4:5], v[66:67] op_sel_hi:[0,1]
	v_pk_mul_f32 v[64:65], v[4:5], v[64:65] op_sel_hi:[0,1]
	v_pk_mul_f32 v[62:63], v[4:5], v[62:63] op_sel_hi:[0,1]
	v_pk_mul_f32 v[60:61], v[4:5], v[60:61] op_sel_hi:[0,1]
	v_pk_mul_f32 v[58:59], v[4:5], v[58:59] op_sel_hi:[0,1]
	v_pk_mul_f32 v[56:57], v[4:5], v[56:57] op_sel_hi:[0,1]
	v_pk_mul_f32 v[54:55], v[4:5], v[54:55] op_sel_hi:[0,1]
	v_pk_mul_f32 v[52:53], v[4:5], v[52:53] op_sel_hi:[0,1]
	v_pk_mul_f32 v[50:51], v[4:5], v[50:51] op_sel_hi:[0,1]
	v_pk_mul_f32 v[48:49], v[4:5], v[48:49] op_sel_hi:[0,1]
	v_pk_mul_f32 v[46:47], v[4:5], v[46:47] op_sel_hi:[0,1]
	v_pk_mul_f32 v[44:45], v[4:5], v[44:45] op_sel_hi:[0,1]
	v_pk_mul_f32 v[42:43], v[4:5], v[42:43] op_sel_hi:[0,1]
	v_pk_mul_f32 v[40:41], v[4:5], v[40:41] op_sel_hi:[0,1]
	v_pk_mul_f32 v[38:39], v[4:5], v[38:39] op_sel_hi:[0,1]
	v_pk_mul_f32 v[36:37], v[4:5], v[36:37] op_sel_hi:[0,1]
	v_pk_mul_f32 v[34:35], v[4:5], v[34:35] op_sel_hi:[0,1]
	v_pk_mul_f32 v[32:33], v[4:5], v[32:33] op_sel_hi:[0,1]
	v_pk_mul_f32 v[30:31], v[4:5], v[30:31] op_sel_hi:[0,1]
	v_pk_mul_f32 v[28:29], v[4:5], v[28:29] op_sel_hi:[0,1]
	v_pk_mul_f32 v[26:27], v[4:5], v[26:27] op_sel_hi:[0,1]
	v_pk_mul_f32 v[24:25], v[4:5], v[24:25] op_sel_hi:[0,1]
	v_pk_mul_f32 v[22:23], v[4:5], v[22:23] op_sel_hi:[0,1]
	v_pk_mul_f32 v[20:21], v[4:5], v[20:21] op_sel_hi:[0,1]
	v_pk_mul_f32 v[18:19], v[4:5], v[18:19] op_sel_hi:[0,1]
	v_pk_mul_f32 v[16:17], v[4:5], v[16:17] op_sel_hi:[0,1]
	v_mul_f32_e32 v224, v224, v4
.LBB0_752:
	v_exp_f32_e32 v226, v80
	v_exp_f32_e32 v227, v96
	v_exp_f32_e32 v10, v81
	v_exp_f32_e32 v4, v97
	v_exp_f32_e32 v228, v98
	v_add_f32_e32 v11, v226, v227
	v_add_f32_e32 v12, v10, v4
	v_add_f32_e32 v13, v11, v5
	s_nop 0
	v_add_f32_e32 v15, v12, v13
	v_exp_f32_e32 v11, v82
	v_exp_f32_e32 v12, v83
	v_exp_f32_e32 v14, v99
	v_cvt_pk_bf16_f32 v10, v226, v10
	v_add_f32_e32 v13, v11, v228
	v_cvt_pk_bf16_f32 v11, v11, v12
	v_add_f32_e32 v80, v12, v14
	v_add_f32_e32 v81, v13, v15
	v_exp_f32_e32 v13, v84
	v_add_f32_e32 v97, v80, v81
	v_exp_f32_e32 v15, v100
	v_exp_f32_e32 v80, v85
	v_exp_f32_e32 v96, v101
	v_cvt_pk_bf16_f32 v12, v13, v80
	v_add_f32_e32 v81, v13, v15
	v_add_f32_e32 v82, v80, v96
	v_add_f32_e32 v83, v81, v97
	s_nop 0
	v_add_f32_e32 v99, v82, v83
	v_exp_f32_e32 v81, v86
	v_exp_f32_e32 v97, v102
	v_exp_f32_e32 v82, v87
	v_exp_f32_e32 v98, v103
	v_cvt_pk_bf16_f32 v13, v81, v82
	v_add_f32_e32 v83, v81, v97
	v_add_f32_e32 v84, v82, v98
	v_add_f32_e32 v85, v83, v99
	s_nop 0
	v_add_f32_e32 v101, v84, v85
	v_exp_f32_e32 v83, v88
	v_exp_f32_e32 v99, v104
	v_exp_f32_e32 v84, v89
	v_exp_f32_e32 v100, v105
	v_exp_f32_e32 v104, v95
	v_add_f32_e32 v85, v83, v99
	v_cvt_pk_bf16_f32 v80, v83, v84
	v_add_f32_e32 v86, v84, v100
	v_add_f32_e32 v87, v85, v101
	v_exp_f32_e32 v85, v90
	v_add_f32_e32 v103, v86, v87
	v_exp_f32_e32 v101, v106
	v_exp_f32_e32 v86, v91
	v_exp_f32_e32 v102, v107
	v_cvt_pk_bf16_f32 v81, v85, v86
	v_add_f32_e32 v87, v85, v101
	v_add_f32_e32 v88, v86, v102
	v_add_f32_e32 v89, v87, v103
	s_nop 0
	v_add_f32_e32 v91, v88, v89
	v_exp_f32_e32 v87, v92
	v_exp_f32_e32 v103, v108
	v_exp_f32_e32 v88, v93
	v_exp_f32_e32 v90, v109
	v_cvt_pk_bf16_f32 v82, v87, v88
	v_add_f32_e32 v89, v87, v103
	v_add_f32_e32 v92, v88, v90
	v_add_f32_e32 v93, v89, v91
	s_nop 0
	v_add_f32_e32 v93, v92, v93
	v_exp_f32_e32 v89, v94
	v_exp_f32_e32 v91, v110
	v_exp_f32_e32 v92, v111
	v_cvt_pk_bf16_f32 v83, v89, v104
	v_cvt_pk_bf16_f32 v84, v227, v4
	v_add_f32_e32 v105, v89, v91
	v_add_f32_e32 v94, v104, v92
	v_add_f32_e32 v95, v105, v93
	v_add_u32_e32 v4, s5, v223
	v_add_f32_e32 v238, v94, v95
	v_cvt_pk_bf16_f32 v85, v228, v14
	v_cvt_pk_bf16_f32 v86, v15, v96
	v_cvt_pk_bf16_f32 v87, v97, v98
	v_cvt_pk_bf16_f32 v88, v99, v100
	v_cvt_pk_bf16_f32 v89, v101, v102
	v_cvt_pk_bf16_f32 v90, v103, v90
	v_cvt_pk_bf16_f32 v91, v91, v92
	ds_read_b64_tr_b16 v[92:93], v4 offset:18432
	ds_read_b64_tr_b16 v[94:95], v4 offset:20992
	ds_read_b64_tr_b16 v[96:97], v4 offset:18496
	ds_read_b64_tr_b16 v[98:99], v4 offset:21056
	ds_read_b64_tr_b16 v[100:101], v4 offset:18560
	ds_read_b64_tr_b16 v[102:103], v4 offset:21120
	ds_read_b64_tr_b16 v[104:105], v4 offset:18624
	ds_read_b64_tr_b16 v[106:107], v4 offset:21184
	ds_read_b64_tr_b16 v[108:109], v4 offset:23552
	ds_read_b64_tr_b16 v[110:111], v4 offset:26112
	ds_read_b64_tr_b16 v[226:227], v4 offset:23616
	ds_read_b64_tr_b16 v[228:229], v4 offset:26176
	ds_read_b64_tr_b16 v[230:231], v4 offset:23680
	ds_read_b64_tr_b16 v[232:233], v4 offset:26240
	ds_read_b64_tr_b16 v[234:235], v4 offset:23744
	ds_read_b64_tr_b16 v[236:237], v4 offset:26304
	s_setprio 1
	s_waitcnt lgkmcnt(14)
	v_mfma_f32_32x32x16_bf16 v[64:79], v[92:95], v[10:13], v[64:79]
	s_waitcnt lgkmcnt(12)
	v_mfma_f32_32x32x16_bf16 v[48:63], v[96:99], v[10:13], v[48:63]
	s_waitcnt lgkmcnt(10)
	v_mfma_f32_32x32x16_bf16 v[32:47], v[100:103], v[10:13], v[32:47]
	s_waitcnt lgkmcnt(8)
	v_mfma_f32_32x32x16_bf16 v[16:31], v[104:107], v[10:13], v[16:31]
	s_setprio 0
	ds_read_b64_tr_b16 v[10:11], v4 offset:28672
	ds_read_b64_tr_b16 v[92:93], v4 offset:28736
	ds_read_b64_tr_b16 v[96:97], v4 offset:28800
	ds_read_b64_tr_b16 v[100:101], v4 offset:28864
	ds_read_b64_tr_b16 v[12:13], v4 offset:31232
	ds_read_b64_tr_b16 v[94:95], v4 offset:31296
	ds_read_b64_tr_b16 v[98:99], v4 offset:31360
	ds_read_b64_tr_b16 v[102:103], v4 offset:31424
	s_setprio 1
	s_waitcnt lgkmcnt(14)
	v_mfma_f32_32x32x16_bf16 v[64:79], v[108:111], v[80:83], v[64:79]
	s_waitcnt lgkmcnt(12)
	v_mfma_f32_32x32x16_bf16 v[48:63], v[226:229], v[80:83], v[48:63]
	s_waitcnt lgkmcnt(10)
	v_mfma_f32_32x32x16_bf16 v[32:47], v[230:233], v[80:83], v[32:47]
	s_waitcnt lgkmcnt(8)
	v_mfma_f32_32x32x16_bf16 v[16:31], v[234:237], v[80:83], v[16:31]
	s_setprio 0
	ds_read_b64_tr_b16 v[80:81], v4 offset:33792
	ds_read_b64_tr_b16 v[104:105], v4 offset:33856
	ds_read_b64_tr_b16 v[108:109], v4 offset:33920
	ds_read_b64_tr_b16 v[226:227], v4 offset:33984
	ds_read_b64_tr_b16 v[82:83], v4 offset:36352
	ds_read_b64_tr_b16 v[106:107], v4 offset:36416
	ds_read_b64_tr_b16 v[110:111], v4 offset:36480
	ds_read_b64_tr_b16 v[228:229], v4 offset:36544
	s_setprio 1
	s_waitcnt lgkmcnt(11)
	v_mfma_f32_32x32x16_bf16 v[64:79], v[10:13], v[84:87], v[64:79]
	s_waitcnt lgkmcnt(10)
	v_mfma_f32_32x32x16_bf16 v[48:63], v[92:95], v[84:87], v[48:63]
	s_waitcnt lgkmcnt(9)
	v_mfma_f32_32x32x16_bf16 v[32:47], v[96:99], v[84:87], v[32:47]
	s_waitcnt lgkmcnt(8)
	v_mfma_f32_32x32x16_bf16 v[16:31], v[100:103], v[84:87], v[16:31]
	s_setprio 0
	s_setprio 1
	s_waitcnt lgkmcnt(3)
	v_mfma_f32_32x32x16_bf16 v[64:79], v[80:83], v[88:91], v[64:79]
	s_waitcnt lgkmcnt(2)
	v_mfma_f32_32x32x16_bf16 v[48:63], v[104:107], v[88:91], v[48:63]
	s_waitcnt lgkmcnt(1)
	v_mfma_f32_32x32x16_bf16 v[32:47], v[108:111], v[88:91], v[32:47]
	s_waitcnt lgkmcnt(0)
	v_mfma_f32_32x32x16_bf16 v[16:31], v[226:229], v[88:91], v[16:31]
	s_setprio 0
	v_add_f32_e32 v224, v224, v238
	s_cmp_eq_u32 s7, 0
	s_cbranch_scc0 .LBB0_738
	s_branch .LBB0_739

.LBB0_755:
	s_andn2_b64 vcc, exec, s[18:19]
	s_cbranch_vccnz .LBB0_757
	v_cmp_lt_f32_e32 vcc, s38, v4
	s_or_b64 vcc, s[44:45], vcc
	s_nop 0
	v_cndmask_b32_e32 v8, 0, v4, vcc
	v_add_f32_e32 v7, v225, v8
	v_cndmask_b32_e64 v225, v7, v4, s[44:45]
	v_exp_f32_e64 v4, -v8
	v_sub_f32_e32 v80, v80, v8
	v_sub_f32_e32 v81, v81, v8
	v_sub_f32_e32 v96, v96, v8
	v_sub_f32_e32 v97, v97, v8
	v_sub_f32_e32 v82, v82, v8
	v_sub_f32_e32 v83, v83, v8
	v_sub_f32_e32 v98, v98, v8
	v_sub_f32_e32 v99, v99, v8
	v_sub_f32_e32 v84, v84, v8
	v_sub_f32_e32 v85, v85, v8
	v_sub_f32_e32 v100, v100, v8
	v_sub_f32_e32 v101, v101, v8
	v_sub_f32_e32 v86, v86, v8
	v_sub_f32_e32 v87, v87, v8
	v_sub_f32_e32 v102, v102, v8
	v_sub_f32_e32 v103, v103, v8
	v_sub_f32_e32 v88, v88, v8
	v_sub_f32_e32 v89, v89, v8
	v_sub_f32_e32 v104, v104, v8
	v_sub_f32_e32 v105, v105, v8
	v_sub_f32_e32 v90, v90, v8
	v_sub_f32_e32 v91, v91, v8
	v_sub_f32_e32 v106, v106, v8
	v_sub_f32_e32 v107, v107, v8
	v_sub_f32_e32 v92, v92, v8
	v_sub_f32_e32 v93, v93, v8
	v_sub_f32_e32 v108, v108, v8
	v_sub_f32_e32 v109, v109, v8
	v_sub_f32_e32 v94, v94, v8
	v_sub_f32_e32 v95, v95, v8
	v_sub_f32_e32 v110, v110, v8
	v_sub_f32_e32 v111, v111, v8
	v_pk_mul_f32 v[78:79], v[4:5], v[78:79] op_sel_hi:[0,1]
	v_pk_mul_f32 v[76:77], v[4:5], v[76:77] op_sel_hi:[0,1]
	v_pk_mul_f32 v[74:75], v[4:5], v[74:75] op_sel_hi:[0,1]
	v_pk_mul_f32 v[72:73], v[4:5], v[72:73] op_sel_hi:[0,1]
	v_pk_mul_f32 v[70:71], v[4:5], v[70:71] op_sel_hi:[0,1]
	v_pk_mul_f32 v[68:69], v[4:5], v[68:69] op_sel_hi:[0,1]
	v_pk_mul_f32 v[66:67], v[4:5], v[66:67] op_sel_hi:[0,1]
	v_pk_mul_f32 v[64:65], v[4:5], v[64:65] op_sel_hi:[0,1]
	v_pk_mul_f32 v[62:63], v[4:5], v[62:63] op_sel_hi:[0,1]
	v_pk_mul_f32 v[60:61], v[4:5], v[60:61] op_sel_hi:[0,1]
	v_pk_mul_f32 v[58:59], v[4:5], v[58:59] op_sel_hi:[0,1]
	v_pk_mul_f32 v[56:57], v[4:5], v[56:57] op_sel_hi:[0,1]
	v_pk_mul_f32 v[54:55], v[4:5], v[54:55] op_sel_hi:[0,1]
	v_pk_mul_f32 v[52:53], v[4:5], v[52:53] op_sel_hi:[0,1]
	v_pk_mul_f32 v[50:51], v[4:5], v[50:51] op_sel_hi:[0,1]
	v_pk_mul_f32 v[48:49], v[4:5], v[48:49] op_sel_hi:[0,1]
	v_pk_mul_f32 v[46:47], v[4:5], v[46:47] op_sel_hi:[0,1]
	v_pk_mul_f32 v[44:45], v[4:5], v[44:45] op_sel_hi:[0,1]
	v_pk_mul_f32 v[42:43], v[4:5], v[42:43] op_sel_hi:[0,1]
	v_pk_mul_f32 v[40:41], v[4:5], v[40:41] op_sel_hi:[0,1]
	v_pk_mul_f32 v[38:39], v[4:5], v[38:39] op_sel_hi:[0,1]
	v_pk_mul_f32 v[36:37], v[4:5], v[36:37] op_sel_hi:[0,1]
	v_pk_mul_f32 v[34:35], v[4:5], v[34:35] op_sel_hi:[0,1]
	v_pk_mul_f32 v[32:33], v[4:5], v[32:33] op_sel_hi:[0,1]
	v_pk_mul_f32 v[30:31], v[4:5], v[30:31] op_sel_hi:[0,1]
	v_pk_mul_f32 v[28:29], v[4:5], v[28:29] op_sel_hi:[0,1]
	v_pk_mul_f32 v[26:27], v[4:5], v[26:27] op_sel_hi:[0,1]
	v_pk_mul_f32 v[24:25], v[4:5], v[24:25] op_sel_hi:[0,1]
	v_pk_mul_f32 v[22:23], v[4:5], v[22:23] op_sel_hi:[0,1]
	v_pk_mul_f32 v[20:21], v[4:5], v[20:21] op_sel_hi:[0,1]
	v_pk_mul_f32 v[18:19], v[4:5], v[18:19] op_sel_hi:[0,1]
	v_pk_mul_f32 v[16:17], v[4:5], v[16:17] op_sel_hi:[0,1]
	v_mul_f32_e32 v224, v224, v4
.LBB0_757:
	v_exp_f32_e32 v7, v80
	v_exp_f32_e32 v226, v96
	v_exp_f32_e32 v8, v81
	v_exp_f32_e32 v4, v97
	v_exp_f32_e32 v227, v98
	v_add_f32_e32 v9, v7, v226
	v_exp_f32_e32 v98, v91
	v_add_f32_e32 v10, v8, v4
	v_add_f32_e32 v11, v9, v5
	v_exp_f32_e32 v9, v82
	v_add_f32_e32 v97, v10, v11
	v_exp_f32_e32 v10, v83
	v_exp_f32_e32 v96, v99
	v_add_f32_e32 v11, v9, v227
	v_cvt_pk_bf16_f32 v8, v7, v8
	v_cvt_pk_bf16_f32 v9, v9, v10
	v_add_f32_e32 v12, v10, v96
	v_add_f32_e32 v13, v11, v97
	v_exp_f32_e32 v11, v84
	v_add_f32_e32 v83, v12, v13
	v_exp_f32_e32 v97, v100
	v_exp_f32_e32 v12, v85
	v_exp_f32_e32 v82, v101
	v_exp_f32_e32 v100, v93
	v_add_f32_e32 v13, v11, v97
	v_cvt_pk_bf16_f32 v10, v11, v12
	v_add_f32_e32 v14, v12, v82
	v_add_f32_e32 v15, v13, v83
	v_exp_f32_e32 v13, v86
	v_add_f32_e32 v85, v14, v15
	v_exp_f32_e32 v83, v102
	v_exp_f32_e32 v14, v87
	v_exp_f32_e32 v84, v103
	v_exp_f32_e32 v102, v95
	v_add_f32_e32 v15, v13, v83
	v_cvt_pk_bf16_f32 v11, v13, v14
	v_add_f32_e32 v80, v14, v84
	v_add_f32_e32 v81, v15, v85
	v_exp_f32_e32 v15, v88
	v_add_f32_e32 v87, v80, v81
	v_exp_f32_e32 v85, v104
	v_exp_f32_e32 v80, v89
	v_exp_f32_e32 v86, v105
	v_cvt_pk_bf16_f32 v12, v15, v80
	v_add_f32_e32 v81, v15, v85
	v_add_f32_e32 v88, v80, v86
	v_add_f32_e32 v89, v81, v87
	s_nop 0
	v_add_f32_e32 v89, v88, v89
	v_exp_f32_e32 v81, v90
	v_exp_f32_e32 v87, v106
	v_exp_f32_e32 v88, v107
	v_cvt_pk_bf16_f32 v13, v81, v98
	v_add_f32_e32 v99, v81, v87
	v_add_f32_e32 v90, v98, v88
	v_add_f32_e32 v91, v99, v89
	v_exp_f32_e32 v89, v92
	v_add_f32_e32 v91, v90, v91
	v_exp_f32_e32 v99, v108
	v_exp_f32_e32 v90, v109
	v_cvt_pk_bf16_f32 v14, v89, v100
	v_add_f32_e32 v101, v89, v99
	v_add_f32_e32 v92, v100, v90
	v_add_f32_e32 v93, v101, v91
	v_exp_f32_e32 v91, v94
	v_add_f32_e32 v93, v92, v93
	v_exp_f32_e32 v101, v110
	v_exp_f32_e32 v92, v111
	v_cvt_pk_bf16_f32 v15, v91, v102
	v_cvt_pk_bf16_f32 v80, v226, v4
	v_add_f32_e32 v103, v91, v101
	v_add_f32_e32 v94, v102, v92
	v_add_f32_e32 v95, v103, v93
	v_add_u32_e32 v4, s46, v223
	v_add_f32_e32 v234, v94, v95
	v_cvt_pk_bf16_f32 v81, v227, v96
	v_cvt_pk_bf16_f32 v82, v97, v82
	v_cvt_pk_bf16_f32 v83, v83, v84
	v_cvt_pk_bf16_f32 v84, v85, v86
	v_cvt_pk_bf16_f32 v85, v87, v88
	v_cvt_pk_bf16_f32 v86, v99, v90
	v_cvt_pk_bf16_f32 v87, v101, v92
	ds_read_b64_tr_b16 v[88:89], v4 offset:18432
	ds_read_b64_tr_b16 v[90:91], v4 offset:20992
	ds_read_b64_tr_b16 v[92:93], v4 offset:18496
	ds_read_b64_tr_b16 v[94:95], v4 offset:21056
	ds_read_b64_tr_b16 v[96:97], v4 offset:18560
	ds_read_b64_tr_b16 v[98:99], v4 offset:21120
	ds_read_b64_tr_b16 v[100:101], v4 offset:18624
	ds_read_b64_tr_b16 v[102:103], v4 offset:21184
	ds_read_b64_tr_b16 v[104:105], v4 offset:23552
	ds_read_b64_tr_b16 v[106:107], v4 offset:26112
	ds_read_b64_tr_b16 v[108:109], v4 offset:23616
	ds_read_b64_tr_b16 v[110:111], v4 offset:26176
	ds_read_b64_tr_b16 v[226:227], v4 offset:23680
	ds_read_b64_tr_b16 v[228:229], v4 offset:26240
	ds_read_b64_tr_b16 v[230:231], v4 offset:23744
	ds_read_b64_tr_b16 v[232:233], v4 offset:26304
	s_setprio 1
	s_waitcnt lgkmcnt(14)
	v_mfma_f32_32x32x16_bf16 v[64:79], v[88:91], v[8:11], v[64:79]
	s_waitcnt lgkmcnt(12)
	v_mfma_f32_32x32x16_bf16 v[48:63], v[92:95], v[8:11], v[48:63]
	s_waitcnt lgkmcnt(10)
	v_mfma_f32_32x32x16_bf16 v[32:47], v[96:99], v[8:11], v[32:47]
	s_waitcnt lgkmcnt(8)
	v_mfma_f32_32x32x16_bf16 v[16:31], v[100:103], v[8:11], v[16:31]
	s_setprio 0
	ds_read_b64_tr_b16 v[8:9], v4 offset:28672
	ds_read_b64_tr_b16 v[88:89], v4 offset:28736
	ds_read_b64_tr_b16 v[92:93], v4 offset:28800
	ds_read_b64_tr_b16 v[96:97], v4 offset:28864
	ds_read_b64_tr_b16 v[10:11], v4 offset:31232
	ds_read_b64_tr_b16 v[90:91], v4 offset:31296
	ds_read_b64_tr_b16 v[94:95], v4 offset:31360
	ds_read_b64_tr_b16 v[98:99], v4 offset:31424
	s_setprio 1
	s_waitcnt lgkmcnt(14)
	v_mfma_f32_32x32x16_bf16 v[64:79], v[104:107], v[12:15], v[64:79]
	s_waitcnt lgkmcnt(12)
	v_mfma_f32_32x32x16_bf16 v[48:63], v[108:111], v[12:15], v[48:63]
	s_waitcnt lgkmcnt(10)
	v_mfma_f32_32x32x16_bf16 v[32:47], v[226:229], v[12:15], v[32:47]
	s_waitcnt lgkmcnt(8)
	v_mfma_f32_32x32x16_bf16 v[16:31], v[230:233], v[12:15], v[16:31]
	s_setprio 0
	ds_read_b64_tr_b16 v[12:13], v4 offset:33792
	ds_read_b64_tr_b16 v[100:101], v4 offset:33856
	ds_read_b64_tr_b16 v[104:105], v4 offset:33920
	ds_read_b64_tr_b16 v[108:109], v4 offset:33984
	ds_read_b64_tr_b16 v[14:15], v4 offset:36352
	ds_read_b64_tr_b16 v[102:103], v4 offset:36416
	ds_read_b64_tr_b16 v[106:107], v4 offset:36480
	ds_read_b64_tr_b16 v[110:111], v4 offset:36544
	s_setprio 1
	s_waitcnt lgkmcnt(11)
	v_mfma_f32_32x32x16_bf16 v[64:79], v[8:11], v[80:83], v[64:79]
	s_waitcnt lgkmcnt(10)
	v_mfma_f32_32x32x16_bf16 v[48:63], v[88:91], v[80:83], v[48:63]
	s_waitcnt lgkmcnt(9)
	v_mfma_f32_32x32x16_bf16 v[32:47], v[92:95], v[80:83], v[32:47]
	s_waitcnt lgkmcnt(8)
	v_mfma_f32_32x32x16_bf16 v[16:31], v[96:99], v[80:83], v[16:31]
	s_setprio 0
	s_setprio 1
	s_waitcnt lgkmcnt(3)
	v_mfma_f32_32x32x16_bf16 v[64:79], v[12:15], v[84:87], v[64:79]
	s_waitcnt lgkmcnt(2)
	v_mfma_f32_32x32x16_bf16 v[48:63], v[100:103], v[84:87], v[48:63]
	s_waitcnt lgkmcnt(1)
	v_mfma_f32_32x32x16_bf16 v[32:47], v[104:107], v[84:87], v[32:47]
	s_waitcnt lgkmcnt(0)
	v_mfma_f32_32x32x16_bf16 v[16:31], v[108:111], v[84:87], v[16:31]
	s_setprio 0
	v_add_f32_e32 v224, v224, v234
	s_andn2_b64 vcc, exec, s[16:17]
	s_cbranch_vccnz .LBB0_734

.LBB0_771:
	s_cmp_eq_u32 s92, s84
	s_cselect_b64 s[16:17], -1, 0
	s_cmp_lg_u32 s92, s84
	s_cselect_b64 s[18:19], -1, 0
	s_lshl_b32 s5, s92, 6
	v_or_b32_e32 v0, s5, v179
	v_sub_u32_e32 v4, v153, v0
	v_cvt_f32_i32_e32 v0, v4
	v_cndmask_b32_e64 v1, v206, 0, s[16:17]
	v_add_u32_e32 v15, s46, v180
	s_mov_b32 s20, 2.0
	v_fma_f32 v10, -v144, v0, -v1
	ds_read_b128 v[0:3], v15
	s_mov_b32 s22, 0x41200000
	s_mov_b32 s24, 0x41800000
	s_mov_b32 s28, 0x41900000
	s_mov_b32 s21, 0x40400000
	s_mov_b32 s23, 0x41300000
	s_mov_b32 s25, 0x41880000
	s_mov_b32 s29, 0x41980000
	v_add_f32_e32 v14, v204, v10
	v_fma_f32 v96, 0, v144, v10
	v_add_f32_e32 v97, v144, v10
	v_fma_f32 v98, v144, s20, v10
	v_fma_f32 v99, v145, s21, v10
	v_fma_f32 v100, v144, s38, v10
	v_fma_f32 v101, v145, s39, v10
	v_fma_f32 v102, v144, s22, v10
	v_fma_f32 v103, v145, s23, v10
	v_fma_f32 v104, v144, s24, v10
	v_fma_f32 v105, v145, s25, v10
	v_fma_f32 v106, v144, s28, v10
	v_fma_f32 v107, v145, s29, v10
	v_fma_f32 v108, v144, s26, v10
	v_fma_f32 v109, v145, s27, v10
	v_fma_f32 v110, v144, s36, v10
	v_fma_f32 v111, v145, s37, v10
	ds_read_b128 v[10:13], v15 offset:8704
	ds_read_b128 v[6:9], v176
	s_waitcnt lgkmcnt(0)
	v_mfma_f32_32x32x16_bf16 v[96:111], v[0:3], v[6:9], v[96:111]
	v_fma_f32 v80, 0, v144, v14
	v_add_f32_e32 v81, v144, v14
	v_fma_f32 v82, v144, s20, v14
	v_fma_f32 v83, v145, s21, v14
	v_fma_f32 v84, v144, s38, v14
	v_fma_f32 v85, v145, s39, v14
	v_fma_f32 v86, v144, s22, v14
	v_fma_f32 v87, v145, s23, v14
	v_fma_f32 v88, v144, s24, v14
	v_fma_f32 v89, v145, s25, v14
	v_fma_f32 v90, v144, s28, v14
	v_fma_f32 v91, v145, s29, v14
	v_fma_f32 v92, v144, s26, v14
	v_fma_f32 v93, v145, s27, v14
	v_fma_f32 v94, v144, s36, v14
	v_fma_f32 v95, v145, s37, v14
	s_or_b32 s4, s5, 63
	s_sub_i32 s20, s49, s4
	v_mfma_f32_32x32x16_bf16 v[80:95], v[10:13], v[6:9], v[80:95]
	ds_read_b128 v[0:3], v15 offset:32
	ds_read_b128 v[6:9], v176 offset:32
	s_mov_b32 s4, 0
	s_cmpk_gt_i32 s20, 0x200
	s_waitcnt lgkmcnt(0)
	v_mfma_f32_32x32x16_bf16 v[96:111], v[0:3], v[6:9], v[96:111]
	ds_read_b128 v[0:3], v15 offset:8736
	s_waitcnt lgkmcnt(0)
	v_mfma_f32_32x32x16_bf16 v[80:95], v[0:3], v[6:9], v[80:95]
	ds_read_b128 v[0:3], v15 offset:64
	ds_read_b128 v[6:9], v176 offset:64
	s_waitcnt lgkmcnt(0)
	v_mfma_f32_32x32x16_bf16 v[96:111], v[0:3], v[6:9], v[96:111]
	ds_read_b128 v[0:3], v15 offset:8768
	s_waitcnt lgkmcnt(0)
	v_mfma_f32_32x32x16_bf16 v[80:95], v[0:3], v[6:9], v[80:95]
	ds_read_b128 v[0:3], v15 offset:96
	ds_read_b128 v[6:9], v176 offset:96
	s_waitcnt lgkmcnt(0)
	v_mfma_f32_32x32x16_bf16 v[96:111], v[0:3], v[6:9], v[96:111]
	ds_read_b128 v[0:3], v15 offset:8800
	s_waitcnt lgkmcnt(0)
	v_mfma_f32_32x32x16_bf16 v[80:95], v[0:3], v[6:9], v[80:95]
	ds_read_b128 v[0:3], v15 offset:128
	ds_read_b128 v[6:9], v176 offset:128
	s_waitcnt lgkmcnt(0)
	v_mfma_f32_32x32x16_bf16 v[96:111], v[0:3], v[6:9], v[96:111]
	ds_read_b128 v[0:3], v15 offset:8832
	s_waitcnt lgkmcnt(0)
	v_mfma_f32_32x32x16_bf16 v[80:95], v[0:3], v[6:9], v[80:95]
	ds_read_b128 v[0:3], v15 offset:160
	ds_read_b128 v[6:9], v176 offset:160
	s_waitcnt lgkmcnt(0)
	v_mfma_f32_32x32x16_bf16 v[96:111], v[0:3], v[6:9], v[96:111]
	ds_read_b128 v[0:3], v15 offset:8864
	s_waitcnt lgkmcnt(0)
	v_mfma_f32_32x32x16_bf16 v[80:95], v[0:3], v[6:9], v[80:95]
	ds_read_b128 v[0:3], v15 offset:192
	ds_read_b128 v[6:9], v176 offset:192
	s_waitcnt lgkmcnt(0)
	v_mfma_f32_32x32x16_bf16 v[96:111], v[0:3], v[6:9], v[96:111]
	ds_read_b128 v[0:3], v15 offset:8896
	s_waitcnt lgkmcnt(0)
	v_mfma_f32_32x32x16_bf16 v[80:95], v[0:3], v[6:9], v[80:95]
	ds_read_b128 v[0:3], v15 offset:224
	ds_read_b128 v[6:9], v176 offset:224
	s_waitcnt lgkmcnt(0)
	v_mfma_f32_32x32x16_bf16 v[96:111], v[0:3], v[6:9], v[96:111]
	ds_read_b128 v[0:3], v15 offset:8928
	s_waitcnt lgkmcnt(0)
	v_mfma_f32_32x32x16_bf16 v[80:95], v[0:3], v[6:9], v[80:95]
	s_cbranch_scc1 .LBB0_773
	s_sub_i32 s24, s93, s5
	s_cmpk_gt_i32 s20, 0x80
	s_cselect_b64 s[4:5], -1, 0
	s_cmpk_lt_i32 s24, 0x201
	s_cselect_b64 s[22:23], -1, 0
	s_and_b64 s[4:5], s[4:5], s[22:23]
	s_cmp_gt_i32 s20, -1
	s_cselect_b64 s[20:21], -1, 0
	s_cmpk_lt_i32 s24, 0x81
	s_cselect_b64 s[22:23], -1, 0
	s_and_b64 s[20:21], s[20:21], s[22:23]
	s_and_b64 s[20:21], s[20:21], exec
	s_cselect_b32 s20, 2, 3
	s_and_b64 s[4:5], s[4:5], exec
	s_cselect_b32 s4, 1, s20

.LBB0_972:
	s_cmp_eq_u32 s4, s84
	s_cselect_b64 s[16:17], -1, 0
	s_cmp_lg_u32 s4, s84
	s_cselect_b64 s[18:19], -1, 0
	s_lshl_b32 s5, s4, 6
	v_or_b32_e32 v0, s5, v179
	v_sub_u32_e32 v4, v153, v0
	v_cvt_f32_i32_e32 v0, v4
	v_cndmask_b32_e64 v1, v206, 0, s[16:17]
	v_add_u32_e32 v15, s44, v180
	s_mov_b32 s20, 2.0
	v_fma_f32 v10, -v144, v0, -v1
	ds_read_b128 v[0:3], v15
	s_mov_b32 s22, 0x41200000
	s_mov_b32 s24, 0x41800000
	s_mov_b32 s28, 0x41900000
	s_mov_b32 s21, 0x40400000
	s_mov_b32 s23, 0x41300000
	s_mov_b32 s25, 0x41880000
	s_mov_b32 s29, 0x41980000
	v_add_f32_e32 v14, v204, v10
	v_fma_f32 v96, 0, v144, v10
	v_add_f32_e32 v97, v144, v10
	v_fma_f32 v98, v144, s20, v10
	v_fma_f32 v99, v145, s21, v10
	v_fma_f32 v100, v144, s38, v10
	v_fma_f32 v101, v145, s39, v10
	v_fma_f32 v102, v144, s22, v10
	v_fma_f32 v103, v145, s23, v10
	v_fma_f32 v104, v144, s24, v10
	v_fma_f32 v105, v145, s25, v10
	v_fma_f32 v106, v144, s28, v10
	v_fma_f32 v107, v145, s29, v10
	v_fma_f32 v108, v144, s26, v10
	v_fma_f32 v109, v145, s27, v10
	v_fma_f32 v110, v144, s36, v10
	v_fma_f32 v111, v145, s37, v10
	ds_read_b128 v[10:13], v15 offset:8704
	ds_read_b128 v[6:9], v176
	s_waitcnt lgkmcnt(0)
	v_mfma_f32_32x32x16_bf16 v[96:111], v[0:3], v[6:9], v[96:111]
	v_fma_f32 v80, 0, v144, v14
	v_add_f32_e32 v81, v144, v14
	v_fma_f32 v82, v144, s20, v14
	v_fma_f32 v83, v145, s21, v14
	v_fma_f32 v84, v144, s38, v14
	v_fma_f32 v85, v145, s39, v14
	v_fma_f32 v86, v144, s22, v14
	v_fma_f32 v87, v145, s23, v14
	v_fma_f32 v88, v144, s24, v14
	v_fma_f32 v89, v145, s25, v14
	v_fma_f32 v90, v144, s28, v14
	v_fma_f32 v91, v145, s29, v14
	v_fma_f32 v92, v144, s26, v14
	v_fma_f32 v93, v145, s27, v14
	v_fma_f32 v94, v144, s36, v14
	v_fma_f32 v95, v145, s37, v14
	s_or_b32 s4, s5, 63
	s_sub_i32 s20, s49, s4
	v_mfma_f32_32x32x16_bf16 v[80:95], v[10:13], v[6:9], v[80:95]
	ds_read_b128 v[0:3], v15 offset:32
	ds_read_b128 v[6:9], v176 offset:32
	s_mov_b32 s4, 0
	s_cmpk_gt_i32 s20, 0x200
	s_waitcnt lgkmcnt(0)
	v_mfma_f32_32x32x16_bf16 v[96:111], v[0:3], v[6:9], v[96:111]
	ds_read_b128 v[0:3], v15 offset:8736
	s_waitcnt lgkmcnt(0)
	v_mfma_f32_32x32x16_bf16 v[80:95], v[0:3], v[6:9], v[80:95]
	ds_read_b128 v[0:3], v15 offset:64
	ds_read_b128 v[6:9], v176 offset:64
	s_waitcnt lgkmcnt(0)
	v_mfma_f32_32x32x16_bf16 v[96:111], v[0:3], v[6:9], v[96:111]
	ds_read_b128 v[0:3], v15 offset:8768
	s_waitcnt lgkmcnt(0)
	v_mfma_f32_32x32x16_bf16 v[80:95], v[0:3], v[6:9], v[80:95]
	ds_read_b128 v[0:3], v15 offset:96
	ds_read_b128 v[6:9], v176 offset:96
	s_waitcnt lgkmcnt(0)
	v_mfma_f32_32x32x16_bf16 v[96:111], v[0:3], v[6:9], v[96:111]
	ds_read_b128 v[0:3], v15 offset:8800
	s_waitcnt lgkmcnt(0)
	v_mfma_f32_32x32x16_bf16 v[80:95], v[0:3], v[6:9], v[80:95]
	ds_read_b128 v[0:3], v15 offset:128
	ds_read_b128 v[6:9], v176 offset:128
	s_waitcnt lgkmcnt(0)
	v_mfma_f32_32x32x16_bf16 v[96:111], v[0:3], v[6:9], v[96:111]
	ds_read_b128 v[0:3], v15 offset:8832
	s_waitcnt lgkmcnt(0)
	v_mfma_f32_32x32x16_bf16 v[80:95], v[0:3], v[6:9], v[80:95]
	ds_read_b128 v[0:3], v15 offset:160
	ds_read_b128 v[6:9], v176 offset:160
	s_waitcnt lgkmcnt(0)
	v_mfma_f32_32x32x16_bf16 v[96:111], v[0:3], v[6:9], v[96:111]
	ds_read_b128 v[0:3], v15 offset:8864
	s_waitcnt lgkmcnt(0)
	v_mfma_f32_32x32x16_bf16 v[80:95], v[0:3], v[6:9], v[80:95]
	ds_read_b128 v[0:3], v15 offset:192
	ds_read_b128 v[6:9], v176 offset:192
	s_waitcnt lgkmcnt(0)
	v_mfma_f32_32x32x16_bf16 v[96:111], v[0:3], v[6:9], v[96:111]
	ds_read_b128 v[0:3], v15 offset:8896
	s_waitcnt lgkmcnt(0)
	v_mfma_f32_32x32x16_bf16 v[80:95], v[0:3], v[6:9], v[80:95]
	ds_read_b128 v[0:3], v15 offset:224
	ds_read_b128 v[6:9], v176 offset:224
	s_waitcnt lgkmcnt(0)
	v_mfma_f32_32x32x16_bf16 v[96:111], v[0:3], v[6:9], v[96:111]
	ds_read_b128 v[0:3], v15 offset:8928
	s_waitcnt lgkmcnt(0)
	v_mfma_f32_32x32x16_bf16 v[80:95], v[0:3], v[6:9], v[80:95]
	s_cbranch_scc1 .LBB0_974
	s_sub_i32 s24, s93, s5
	s_cmpk_gt_i32 s20, 0x80
	s_cselect_b64 s[4:5], -1, 0
	s_cmpk_lt_i32 s24, 0x201
	s_cselect_b64 s[22:23], -1, 0
	s_and_b64 s[4:5], s[4:5], s[22:23]
	s_cmp_gt_i32 s20, -1
	s_cselect_b64 s[20:21], -1, 0
	s_cmpk_lt_i32 s24, 0x81
	s_cselect_b64 s[22:23], -1, 0
	s_and_b64 s[20:21], s[20:21], s[22:23]
	s_and_b64 s[20:21], s[20:21], exec
	s_cselect_b32 s20, 2, 3
	s_and_b64 s[4:5], s[4:5], exec
	s_cselect_b32 s4, 1, s20

.LBB0_1182:
	v_exp_f32_e32 v100, v160
	v_exp_f32_e32 v101, v2
	v_exp_f32_e32 v4, v161
	v_exp_f32_e32 v80, v3
	v_exp_f32_e32 v102, v6
	v_add_f32_e32 v81, v101, v100
	v_exp_f32_e32 v82, v7
	v_add_f32_e32 v2, v80, v4
	v_add_f32_e32 v3, v81, v5
	v_exp_f32_e32 v81, v164
	v_add_f32_e32 v3, v2, v3
	v_exp_f32_e32 v2, v165
	v_exp_f32_e32 v84, v11
	v_add_f32_e32 v83, v102, v81
	v_exp_f32_e32 v86, v157
	v_add_f32_e32 v6, v82, v2
	v_add_f32_e32 v7, v83, v3
	v_exp_f32_e32 v3, v168
	v_add_f32_e32 v7, v6, v7
	v_exp_f32_e32 v83, v10
	v_exp_f32_e32 v6, v169
	v_exp_f32_e32 v90, v15
	v_exp_f32_e32 v92, v13
	v_add_f32_e32 v85, v83, v3
	v_add_f32_e32 v10, v84, v6
	v_add_f32_e32 v11, v85, v7
	v_exp_f32_e32 v7, v172
	v_add_f32_e32 v11, v10, v11
	v_exp_f32_e32 v85, v156
	v_exp_f32_e32 v10, v173
	v_exp_f32_e32 v94, v9
	v_exp_f32_e32 v98, v1
	v_add_f32_e32 v87, v85, v7
	v_add_f32_e32 v88, v86, v10
	v_add_f32_e32 v89, v87, v11
	v_exp_f32_e32 v11, v170
	v_add_f32_e32 v89, v88, v89
	v_exp_f32_e32 v87, v14
	v_exp_f32_e32 v88, v171
	v_add_f32_e32 v91, v87, v11
	v_add_f32_e32 v14, v90, v88
	v_add_f32_e32 v15, v91, v89
	v_exp_f32_e32 v89, v166
	v_add_f32_e32 v15, v14, v15
	v_exp_f32_e32 v91, v12
	v_exp_f32_e32 v14, v167
	v_add_f32_e32 v93, v91, v89
	v_add_f32_e32 v12, v92, v14
	v_add_f32_e32 v13, v93, v15
	v_exp_f32_e32 v15, v162
	v_add_f32_e32 v13, v12, v13
	v_exp_f32_e32 v93, v8
	v_exp_f32_e32 v12, v163
	v_add_f32_e32 v95, v93, v15
	v_add_f32_e32 v8, v94, v12
	v_add_f32_e32 v9, v95, v13
	v_exp_f32_e32 v95, v0
	v_add_f32_e32 v97, v8, v9
	v_exp_f32_e32 v9, v158
	v_exp_f32_e32 v96, v159
	v_add_f32_e32 v99, v95, v9
	v_add_f32_e32 v0, v98, v96
	v_add_f32_e32 v1, v99, v97
	s_nop 0
	v_add_f32_e32 v160, v0, v1
	v_cvt_pk_bf16_f32 v0, v100, v4
	v_add_u32_e32 v4, s47, v181
	v_cvt_pk_bf16_f32 v1, v81, v2
	v_cvt_pk_bf16_f32 v2, v3, v6
	v_cvt_pk_bf16_f32 v3, v7, v10
	v_cvt_pk_bf16_f32 v6, v11, v88
	v_cvt_pk_bf16_f32 v7, v89, v14
	v_cvt_pk_bf16_f32 v8, v15, v12
	v_cvt_pk_bf16_f32 v9, v9, v96
	v_cvt_pk_bf16_f32 v10, v101, v80
	v_cvt_pk_bf16_f32 v11, v102, v82
	v_cvt_pk_bf16_f32 v12, v83, v84
	v_cvt_pk_bf16_f32 v13, v85, v86
	v_cvt_pk_bf16_f32 v80, v87, v90
	v_cvt_pk_bf16_f32 v81, v91, v92
	v_cvt_pk_bf16_f32 v82, v93, v94
	v_cvt_pk_bf16_f32 v83, v95, v98
	ds_read_b64_tr_b16 v[84:85], v4 offset:34816
	ds_read_b64_tr_b16 v[86:87], v4 offset:37376
	ds_read_b64_tr_b16 v[88:89], v4 offset:34880
	ds_read_b64_tr_b16 v[90:91], v4 offset:37440
	ds_read_b64_tr_b16 v[92:93], v4 offset:34944
	ds_read_b64_tr_b16 v[94:95], v4 offset:37504
	ds_read_b64_tr_b16 v[96:97], v4 offset:35008
	ds_read_b64_tr_b16 v[98:99], v4 offset:37568
	ds_read_b64_tr_b16 v[100:101], v4 offset:39936
	ds_read_b64_tr_b16 v[102:103], v4 offset:42496
	ds_read_b64_tr_b16 v[104:105], v4 offset:40000
	ds_read_b64_tr_b16 v[106:107], v4 offset:42560
	ds_read_b64_tr_b16 v[108:109], v4 offset:40064
	ds_read_b64_tr_b16 v[110:111], v4 offset:42624
	ds_read_b64_tr_b16 v[156:157], v4 offset:40128
	ds_read_b64_tr_b16 v[158:159], v4 offset:42688
	s_setprio 1
	s_waitcnt lgkmcnt(14)
	v_mfma_f32_32x32x16_bf16 v[64:79], v[84:87], v[0:3], v[64:79]
	s_waitcnt lgkmcnt(12)
	v_mfma_f32_32x32x16_bf16 v[48:63], v[88:91], v[0:3], v[48:63]
	s_waitcnt lgkmcnt(10)
	v_mfma_f32_32x32x16_bf16 v[32:47], v[92:95], v[0:3], v[32:47]
	s_waitcnt lgkmcnt(8)
	v_mfma_f32_32x32x16_bf16 v[16:31], v[96:99], v[0:3], v[16:31]
	s_setprio 0
	ds_read_b64_tr_b16 v[0:1], v4 offset:45056
	ds_read_b64_tr_b16 v[84:85], v4 offset:45120
	ds_read_b64_tr_b16 v[88:89], v4 offset:45184
	ds_read_b64_tr_b16 v[92:93], v4 offset:45248
	ds_read_b64_tr_b16 v[2:3], v4 offset:47616
	ds_read_b64_tr_b16 v[86:87], v4 offset:47680
	ds_read_b64_tr_b16 v[90:91], v4 offset:47744
	ds_read_b64_tr_b16 v[94:95], v4 offset:47808
	s_setprio 1
	s_waitcnt lgkmcnt(14)
	v_mfma_f32_32x32x16_bf16 v[64:79], v[100:103], v[6:9], v[64:79]
	s_waitcnt lgkmcnt(12)
	v_mfma_f32_32x32x16_bf16 v[48:63], v[104:107], v[6:9], v[48:63]
	s_waitcnt lgkmcnt(10)
	v_mfma_f32_32x32x16_bf16 v[32:47], v[108:111], v[6:9], v[32:47]
	s_waitcnt lgkmcnt(8)
	v_mfma_f32_32x32x16_bf16 v[16:31], v[156:159], v[6:9], v[16:31]
	s_setprio 0
	ds_read_b64_tr_b16 v[6:7], v4 offset:50176
	ds_read_b64_tr_b16 v[96:97], v4 offset:50240
	ds_read_b64_tr_b16 v[100:101], v4 offset:50304
	ds_read_b64_tr_b16 v[104:105], v4 offset:50368
	ds_read_b64_tr_b16 v[8:9], v4 offset:52736
	ds_read_b64_tr_b16 v[98:99], v4 offset:52800
	ds_read_b64_tr_b16 v[102:103], v4 offset:52864
	ds_read_b64_tr_b16 v[106:107], v4 offset:52928
	s_setprio 1
	s_waitcnt lgkmcnt(11)
	v_mfma_f32_32x32x16_bf16 v[64:79], v[0:3], v[10:13], v[64:79]
	s_waitcnt lgkmcnt(10)
	v_mfma_f32_32x32x16_bf16 v[48:63], v[84:87], v[10:13], v[48:63]
	s_waitcnt lgkmcnt(9)
	v_mfma_f32_32x32x16_bf16 v[32:47], v[88:91], v[10:13], v[32:47]
	s_waitcnt lgkmcnt(8)
	v_mfma_f32_32x32x16_bf16 v[16:31], v[92:95], v[10:13], v[16:31]
	s_setprio 0
	s_setprio 1
	s_waitcnt lgkmcnt(3)
	v_mfma_f32_32x32x16_bf16 v[64:79], v[6:9], v[80:83], v[64:79]
	s_waitcnt lgkmcnt(2)
	v_mfma_f32_32x32x16_bf16 v[48:63], v[96:99], v[80:83], v[48:63]
	s_waitcnt lgkmcnt(1)
	v_mfma_f32_32x32x16_bf16 v[32:47], v[100:103], v[80:83], v[32:47]
	s_waitcnt lgkmcnt(0)
	v_mfma_f32_32x32x16_bf16 v[16:31], v[104:107], v[80:83], v[16:31]
	s_setprio 0
	v_add_f32_e32 v205, v205, v160
	s_cmp_eq_u32 s92, 0
	s_cbranch_scc0 .LBB0_766
	s_branch .LBB0_767

.LBB0_1193:
	v_exp_f32_e32 v100, v160
	v_exp_f32_e32 v101, v2
	v_exp_f32_e32 v80, v161
	v_exp_f32_e32 v4, v3
	v_exp_f32_e32 v102, v6
	v_add_f32_e32 v81, v100, v101
	v_exp_f32_e32 v90, v171
	v_add_f32_e32 v2, v80, v4
	v_add_f32_e32 v3, v81, v5
	v_exp_f32_e32 v81, v164
	v_add_f32_e32 v83, v2, v3
	v_exp_f32_e32 v2, v165
	v_exp_f32_e32 v82, v7
	v_add_f32_e32 v3, v81, v102
	v_exp_f32_e32 v92, v167
	v_exp_f32_e32 v98, v159
	v_add_f32_e32 v6, v2, v82
	v_add_f32_e32 v7, v3, v83
	v_exp_f32_e32 v3, v168
	v_add_f32_e32 v85, v6, v7
	v_exp_f32_e32 v83, v10
	v_exp_f32_e32 v6, v169
	v_exp_f32_e32 v84, v11
	v_add_f32_e32 v7, v3, v83
	v_add_f32_e32 v10, v6, v84
	v_add_f32_e32 v11, v7, v85
	s_nop 0
	v_add_f32_e32 v87, v10, v11
	v_exp_f32_e32 v7, v172
	v_exp_f32_e32 v85, v156
	v_exp_f32_e32 v10, v173
	v_exp_f32_e32 v86, v157
	v_add_f32_e32 v11, v7, v85
	v_add_f32_e32 v88, v10, v86
	v_add_f32_e32 v89, v11, v87
	s_nop 0
	v_add_f32_e32 v89, v88, v89
	v_exp_f32_e32 v11, v170
	v_exp_f32_e32 v87, v14
	v_exp_f32_e32 v88, v15
	v_add_f32_e32 v91, v11, v87
	v_add_f32_e32 v14, v90, v88
	v_add_f32_e32 v15, v91, v89
	v_exp_f32_e32 v89, v166
	v_add_f32_e32 v15, v14, v15
	v_exp_f32_e32 v91, v12
	v_exp_f32_e32 v14, v13
	v_add_f32_e32 v93, v89, v91
	v_add_f32_e32 v12, v92, v14
	v_add_f32_e32 v13, v93, v15
	v_exp_f32_e32 v15, v162
	v_add_f32_e32 v95, v12, v13
	v_exp_f32_e32 v93, v8
	v_exp_f32_e32 v12, v163
	v_exp_f32_e32 v94, v9
	v_add_f32_e32 v13, v15, v93
	v_add_f32_e32 v8, v12, v94
	v_add_f32_e32 v9, v13, v95
	s_nop 0
	v_add_f32_e32 v97, v8, v9
	v_exp_f32_e32 v9, v158
	v_exp_f32_e32 v95, v0
	v_exp_f32_e32 v96, v1
	v_add_f32_e32 v99, v9, v95
	v_add_f32_e32 v0, v98, v96
	v_add_f32_e32 v1, v99, v97
	s_nop 0
	v_add_f32_e32 v160, v0, v1
	v_cvt_pk_bf16_f32 v0, v100, v80
	v_cvt_pk_bf16_f32 v1, v81, v2
	v_cvt_pk_bf16_f32 v2, v3, v6
	v_cvt_pk_bf16_f32 v3, v7, v10
	v_cvt_pk_bf16_f32 v6, v11, v90
	v_cvt_pk_bf16_f32 v7, v89, v92
	v_cvt_pk_bf16_f32 v8, v15, v12
	v_cvt_pk_bf16_f32 v9, v9, v98
	v_cvt_pk_bf16_f32 v10, v101, v4
	v_add_u32_e32 v4, s45, v181
	v_cvt_pk_bf16_f32 v11, v102, v82
	v_cvt_pk_bf16_f32 v12, v83, v84
	v_cvt_pk_bf16_f32 v13, v85, v86
	v_cvt_pk_bf16_f32 v80, v87, v88
	v_cvt_pk_bf16_f32 v81, v91, v14
	v_cvt_pk_bf16_f32 v82, v93, v94
	v_cvt_pk_bf16_f32 v83, v95, v96
	ds_read_b64_tr_b16 v[84:85], v4 offset:34816
	ds_read_b64_tr_b16 v[86:87], v4 offset:37376
	ds_read_b64_tr_b16 v[88:89], v4 offset:34880
	ds_read_b64_tr_b16 v[90:91], v4 offset:37440
	ds_read_b64_tr_b16 v[92:93], v4 offset:34944
	ds_read_b64_tr_b16 v[94:95], v4 offset:37504
	ds_read_b64_tr_b16 v[96:97], v4 offset:35008
	ds_read_b64_tr_b16 v[98:99], v4 offset:37568
	ds_read_b64_tr_b16 v[100:101], v4 offset:39936
	ds_read_b64_tr_b16 v[102:103], v4 offset:42496
	ds_read_b64_tr_b16 v[104:105], v4 offset:40000
	ds_read_b64_tr_b16 v[106:107], v4 offset:42560
	ds_read_b64_tr_b16 v[108:109], v4 offset:40064
	ds_read_b64_tr_b16 v[110:111], v4 offset:42624
	ds_read_b64_tr_b16 v[156:157], v4 offset:40128
	ds_read_b64_tr_b16 v[158:159], v4 offset:42688
	s_setprio 1
	s_waitcnt lgkmcnt(14)
	v_mfma_f32_32x32x16_bf16 v[64:79], v[84:87], v[0:3], v[64:79]
	s_waitcnt lgkmcnt(12)
	v_mfma_f32_32x32x16_bf16 v[48:63], v[88:91], v[0:3], v[48:63]
	s_waitcnt lgkmcnt(10)
	v_mfma_f32_32x32x16_bf16 v[32:47], v[92:95], v[0:3], v[32:47]
	s_waitcnt lgkmcnt(8)
	v_mfma_f32_32x32x16_bf16 v[16:31], v[96:99], v[0:3], v[16:31]
	s_setprio 0
	ds_read_b64_tr_b16 v[0:1], v4 offset:45056
	ds_read_b64_tr_b16 v[84:85], v4 offset:45120
	ds_read_b64_tr_b16 v[88:89], v4 offset:45184
	ds_read_b64_tr_b16 v[92:93], v4 offset:45248
	ds_read_b64_tr_b16 v[2:3], v4 offset:47616
	ds_read_b64_tr_b16 v[86:87], v4 offset:47680
	ds_read_b64_tr_b16 v[90:91], v4 offset:47744
	ds_read_b64_tr_b16 v[94:95], v4 offset:47808
	s_setprio 1
	s_waitcnt lgkmcnt(14)
	v_mfma_f32_32x32x16_bf16 v[64:79], v[100:103], v[6:9], v[64:79]
	s_waitcnt lgkmcnt(12)
	v_mfma_f32_32x32x16_bf16 v[48:63], v[104:107], v[6:9], v[48:63]
	s_waitcnt lgkmcnt(10)
	v_mfma_f32_32x32x16_bf16 v[32:47], v[108:111], v[6:9], v[32:47]
	s_waitcnt lgkmcnt(8)
	v_mfma_f32_32x32x16_bf16 v[16:31], v[156:159], v[6:9], v[16:31]
	s_setprio 0
	ds_read_b64_tr_b16 v[6:7], v4 offset:50176
	ds_read_b64_tr_b16 v[96:97], v4 offset:50240
	ds_read_b64_tr_b16 v[100:101], v4 offset:50304
	ds_read_b64_tr_b16 v[104:105], v4 offset:50368
	ds_read_b64_tr_b16 v[8:9], v4 offset:52736
	ds_read_b64_tr_b16 v[98:99], v4 offset:52800
	ds_read_b64_tr_b16 v[102:103], v4 offset:52864
	ds_read_b64_tr_b16 v[106:107], v4 offset:52928
	s_setprio 1
	s_waitcnt lgkmcnt(11)
	v_mfma_f32_32x32x16_bf16 v[64:79], v[0:3], v[10:13], v[64:79]
	s_waitcnt lgkmcnt(10)
	v_mfma_f32_32x32x16_bf16 v[48:63], v[84:87], v[10:13], v[48:63]
	s_waitcnt lgkmcnt(9)
	v_mfma_f32_32x32x16_bf16 v[32:47], v[88:91], v[10:13], v[32:47]
	s_waitcnt lgkmcnt(8)
	v_mfma_f32_32x32x16_bf16 v[16:31], v[92:95], v[10:13], v[16:31]
	s_setprio 0
	s_setprio 1
	s_waitcnt lgkmcnt(3)
	v_mfma_f32_32x32x16_bf16 v[64:79], v[6:9], v[80:83], v[64:79]
	s_waitcnt lgkmcnt(2)
	v_mfma_f32_32x32x16_bf16 v[48:63], v[96:99], v[80:83], v[48:63]
	s_waitcnt lgkmcnt(1)
	v_mfma_f32_32x32x16_bf16 v[32:47], v[100:103], v[80:83], v[32:47]
	s_waitcnt lgkmcnt(0)
	v_mfma_f32_32x32x16_bf16 v[16:31], v[104:107], v[80:83], v[16:31]
	s_setprio 0
	v_add_f32_e32 v205, v205, v160
	s_andn2_b64 vcc, exec, s[14:15]
	s_cbranch_vccnz .LBB0_762

; __global__ void __launch_bounds__(512, 2) mega(Args a) {
	.amdhsa_kernel _Z4mega4Args
		.amdhsa_group_segment_fixed_size 0
		.amdhsa_private_segment_fixed_size 0
		.amdhsa_kernarg_size 432
		.amdhsa_user_sgpr_count 2
		.amdhsa_user_sgpr_dispatch_ptr 0
		.amdhsa_user_sgpr_queue_ptr 0
		.amdhsa_user_sgpr_kernarg_segment_ptr 1
		.amdhsa_user_sgpr_dispatch_id 0
		.amdhsa_user_sgpr_kernarg_preload_length 0
		.amdhsa_user_sgpr_kernarg_preload_offset 0
		.amdhsa_user_sgpr_private_segment_size 0
		.amdhsa_uses_dynamic_stack 0
		.amdhsa_enable_private_segment 0
		.amdhsa_system_sgpr_workgroup_id_x 1
		.amdhsa_system_sgpr_workgroup_id_y 0
		.amdhsa_system_sgpr_workgroup_id_z 0
		.amdhsa_system_sgpr_workgroup_info 0
		.amdhsa_system_vgpr_workitem_id 2
		.amdhsa_next_free_vgpr 254
		.amdhsa_next_free_sgpr 100
		.amdhsa_accum_offset 256
		.amdhsa_reserve_vcc 1
		.amdhsa_float_round_mode_32 0
		.amdhsa_float_round_mode_16_64 0
		.amdhsa_float_denorm_mode_32 3
		.amdhsa_float_denorm_mode_16_64 3
		.amdhsa_dx10_clamp 1
		.amdhsa_ieee_mode 1
		.amdhsa_fp16_overflow 0
		.amdhsa_tg_split 0
		.amdhsa_exception_fp_ieee_invalid_op 0
		.amdhsa_exception_fp_denorm_src 0
		.amdhsa_exception_fp_ieee_div_zero 0
		.amdhsa_exception_fp_ieee_overflow 0
		.amdhsa_exception_fp_ieee_underflow 0
		.amdhsa_exception_fp_ieee_inexact 0
		.amdhsa_exception_int_div_zero 0
	.end_amdhsa_kernel

; __global__ void __launch_bounds__(512, 2) mega(Args a) {
amdhsa.kernels:
  - .agpr_count:     0
    .args:
      - .offset:         0
        .size:           176
        .value_kind:     by_value
      - .offset:         176
        .size:           4
        .value_kind:     hidden_block_count_x
      - .offset:         180
        .size:           4
        .value_kind:     hidden_block_count_y
      - .offset:         184
        .size:           4
        .value_kind:     hidden_block_count_z
      - .offset:         188
        .size:           2
        .value_kind:     hidden_group_size_x
      - .offset:         190
        .size:           2
        .value_kind:     hidden_group_size_y
      - .offset:         192
        .size:           2
        .value_kind:     hidden_group_size_z
      - .offset:         194
        .size:           2
        .value_kind:     hidden_remainder_x
      - .offset:         196
        .size:           2
        .value_kind:     hidden_remainder_y
      - .offset:         198
        .size:           2
        .value_kind:     hidden_remainder_z
      - .offset:         216
        .size:           8
        .value_kind:     hidden_global_offset_x
      - .offset:         224
        .size:           8
        .value_kind:     hidden_global_offset_y
      - .offset:         232
        .size:           8
        .value_kind:     hidden_global_offset_z
      - .offset:         240
        .size:           2
        .value_kind:     hidden_grid_dims
      - .offset:         264
        .size:           8
        .value_kind:     hidden_multigrid_sync_arg
      - .offset:         296
        .size:           4
        .value_kind:     hidden_dynamic_lds_size
    .group_segment_fixed_size: 0
    .kernarg_segment_align: 8
    .kernarg_segment_size: 432
    .language:       OpenCL C
    .language_version:
      - 2
      - 0
    .max_flat_workgroup_size: 512
    .name:           _Z4mega4Args
    .private_segment_fixed_size: 0
    .sgpr_count:     106
    .sgpr_spill_count: 235
    .symbol:         _Z4mega4Args.kd
    .uniform_work_group_size: 1
    .uses_dynamic_stack: false
    .vgpr_count:     254
    .vgpr_spill_count: 0
    .wavefront_size: 64
